# stack9 + EpiFfn: 407 dead v_mov 0 (old value of full row-rotate DPP movs) deleted, hazard distances checked
# speedup vs baseline: 1.0061x; 1.0061x over previous
; DEVI unsigned pk2(float lo, float hi) { unsigned r; asm("v_cvt_pk_bf16_f32 %0, %1, %2" : "=v"(r) : "v"(lo), "v"(hi)); return r; }
; DEVI float siluf_(float x) { return x * sigmoidf_(x); }
;     DEVI void operator()(const f32x4 (&acc)[2][2][4][2], const pg8::Unit& u, int wr, int wc, int fr, int fq) const {
;     ...
;         for (int n = 0; n < 2; ++n) {
;             const int tc = u.pn * 256 + wc * 32 + 8 * fq + 4 * n;
;             const int j = u.pn * 128 + wc * 32 + 8 * fq + 4 * n;
;             const f32x4 sg = *(const f32x4*)(s + tc), cg_ = *(const f32x4*)(c + tc), su = *(const f32x4*)(s + tc + 128), cu = *(const f32x4*)(c + tc + 128);
;             const f32x4 w0 = *(const f32x4*)(cw + j), w1 = *(const f32x4*)(cw + DFF + j), w2 = *(const f32x4*)(cw + 2 * DFF + j), cbv = *(const f32x4*)(cb + j);
; #pragma unroll
;             for (int ai = 0; ai < 2; ++ai) {
;                 f32x4 gprev = (f32x4){0.f, 0.f, 0.f, 0.f};
; #pragma unroll
;                 for (int m = 0; m < 4; ++m) {
;                     const int row = u.pm * 256 + ai * 128 + wr * 64 + m * 16 + fr;
;                     const f32x4 g = (acc[ai][0][m][n] - mu[ai][m] * sg) * rs[ai][m] + cg_;
;                     const f32x4 uu = (acc[ai][1][m][n] - mu[ai][m] * su) * rs[ai][m] + cu;
;                     f32x4 p1, p2;
; #pragma unroll
;                     for (int e = 0; e < 4; ++e) {
;                         p1[e] = dppf<0x111>(dppf<0x121>(0.f, gprev[e]), g[e]);
;                         p2[e] = dppf<0x112>(dppf<0x122>(0.f, gprev[e]), g[e]);
;                     }
;                     const int blk = row >> 6;
;                     if (m == 0 && fr < 2) {
;                         const f32x4 pg = (fr == 0) ? (w2 * g + cbv) : (w1 * p1 + w2 * g + cbv);
;                         *(f32x4*)(headpg + ((size_t)blk * 2 + fr) * DFF + j) = pg;
;                         *(f32x4*)(headup + ((size_t)blk * 2 + fr) * DFF + j) = uu;
;                     } else {
;                         const f32x4 cv = w0 * p2 + w1 * p1 + w2 * g + cbv;
;                         u32x2 o; o.x = pk2(siluf_(cv[0]) * uu[0], siluf_(cv[1]) * uu[1]); o.y = pk2(siluf_(cv[2]) * uu[2], siluf_(cv[3]) * uu[3]);
;                         *(u32x2*)(H + (size_t)row * DFF + j) = o;
.LBB0_673:
	v_lshl_or_b32 v226, s68, 8, v244
	v_lshl_or_b32 v200, s68, 7, v244
	v_ashrrev_i32_e32 v227, 31, v226
	v_ashrrev_i32_e32 v201, 31, v200
	v_readlane_b32 s8, v249, 37
	v_lshlrev_b64 v[128:129], 2, v[226:227]
	v_lshlrev_b64 v[206:207], 2, v[200:201]
	v_readlane_b32 s16, v249, 45
	v_readlane_b32 s17, v249, 46
	v_lshl_add_u64 v[124:125], s[70:71], 0, v[128:129]
	v_lshl_add_u64 v[128:129], s[74:75], 0, v[128:129]
	v_readlane_b32 s18, v249, 47
	v_readlane_b32 s19, v249, 48
	v_lshl_add_u64 v[224:225], s[16:17], 0, v[206:207]
	v_lshl_add_u64 v[132:133], s[34:35], 0, v[206:207]
	v_lshl_add_u64 v[134:135], s[36:37], 0, v[206:207]
	flat_load_dwordx4 v[152:155], v[124:125]
	s_nop 0
	flat_load_dwordx4 v[124:127], v[124:125] offset:512
	v_lshl_add_u64 v[222:223], s[18:19], 0, v[206:207]
	flat_load_dwordx4 v[156:159], v[128:129]
	flat_load_dwordx4 v[128:131], v[128:129] offset:512
	s_nop 0
	global_load_dwordx4 v[144:147], v[224:225], off
	global_load_dwordx4 v[140:143], v[132:133], off
	global_load_dwordx4 v[136:139], v[134:135], off
	s_nop 0
	global_load_dwordx4 v[132:135], v[222:223], off
	v_mov_b32_dpp v239, v239 row_ror:1 row_mask:0xf bank_mask:0xf
	v_mov_b32_e32 v160, v239
	v_mov_b32_dpp v163, v163 row_ror:2 row_mask:0xf bank_mask:0xf
	v_mov_b32_e32 v240, v163
	v_mov_b32_e32 v161, v239
	v_mov_b32_e32 v241, v163
	v_mov_b32_e32 v238, v239
	v_mov_b32_e32 v162, v163
	v_readlane_b32 s9, v249, 38
	v_readlane_b32 s10, v249, 39
	v_readlane_b32 s11, v249, 40
	v_readlane_b32 s12, v249, 41
	v_readlane_b32 s13, v249, 42
	v_readlane_b32 s14, v249, 43
	v_readlane_b32 s15, v249, 44
	v_readlane_b32 s20, v249, 49
	v_readlane_b32 s21, v249, 50
	v_readlane_b32 s22, v249, 51
	v_readlane_b32 s23, v249, 52
	s_waitcnt vmcnt(0) lgkmcnt(0)
	v_pk_fma_f32 v[150:151], v[220:221], v[154:155], v[150:151] op_sel_hi:[0,1,1] neg_lo:[1,0,0] neg_hi:[1,0,0]
	v_pk_fma_f32 v[148:149], v[220:221], v[152:153], v[148:149] op_sel_hi:[0,1,1] neg_lo:[1,0,0] neg_hi:[1,0,0]
	v_pk_fma_f32 v[122:123], v[220:221], v[126:127], v[122:123] op_sel_hi:[0,1,1] neg_lo:[1,0,0] neg_hi:[1,0,0]
	v_pk_fma_f32 v[120:121], v[220:221], v[124:125], v[120:121] op_sel_hi:[0,1,1] neg_lo:[1,0,0] neg_hi:[1,0,0]
	v_pk_fma_f32 v[234:235], v[218:219], v[150:151], v[158:159] op_sel_hi:[0,1,1]
	v_pk_fma_f32 v[236:237], v[218:219], v[148:149], v[156:157] op_sel_hi:[0,1,1]
	v_pk_fma_f32 v[122:123], v[218:219], v[122:123], v[130:131] op_sel_hi:[0,1,1]
	v_mov_b32_dpp v238, v234 row_shr:1 row_mask:0xf bank_mask:0xf
	v_mov_b32_dpp v160, v236 row_shr:1 row_mask:0xf bank_mask:0xf
	v_mov_b32_dpp v240, v236 row_shr:2 row_mask:0xf bank_mask:0xf
	v_mov_b32_dpp v161, v237 row_shr:1 row_mask:0xf bank_mask:0xf
	v_mov_b32_dpp v241, v237 row_shr:2 row_mask:0xf bank_mask:0xf
	v_mov_b32_dpp v162, v234 row_shr:2 row_mask:0xf bank_mask:0xf
	v_mov_b32_dpp v239, v235 row_shr:1 row_mask:0xf bank_mask:0xf
	v_mov_b32_dpp v163, v235 row_shr:2 row_mask:0xf bank_mask:0xf
	v_pk_fma_f32 v[120:121], v[218:219], v[120:121], v[128:129] op_sel_hi:[0,1,1]
	s_and_saveexec_b64 s[0:1], s[2:3]
	s_xor_b64 s[0:1], exec, s[0:1]
	s_cbranch_execz .LBB0_675
	v_pk_mul_f32 v[150:151], v[144:145], v[240:241]
	v_pk_mul_f32 v[148:149], v[146:147], v[162:163]
	v_pk_fma_f32 v[150:151], v[140:141], v[160:161], v[150:151]
	v_pk_fma_f32 v[148:149], v[142:143], v[238:239], v[148:149]
	v_pk_fma_f32 v[150:151], v[236:237], v[136:137], v[150:151]
	v_pk_fma_f32 v[148:149], v[234:235], v[138:139], v[148:149]
	v_pk_add_f32 v[150:151], v[132:133], v[150:151]
	v_pk_add_f32 v[148:149], v[134:135], v[148:149]
	v_mul_f32_e32 v160, 0xbfb8aa3b, v150
	v_exp_f32_e32 v160, v160
	v_mul_f32_e32 v161, 0xbfb8aa3b, v151
	v_exp_f32_e32 v161, v161
	v_add_f32_e32 v160, 1.0, v160
	v_rcp_f32_e32 v160, v160
	v_add_f32_e32 v161, 1.0, v161
	v_rcp_f32_e32 v161, v161
	v_mul_f32_e32 v150, v150, v160
	v_mul_f32_e32 v120, v120, v150
	v_mul_f32_e32 v150, v151, v161
	v_mul_f32_e32 v151, 0xbfb8aa3b, v148
	v_exp_f32_e32 v151, v151
	v_mul_f32_e32 v160, 0xbfb8aa3b, v149
	v_exp_f32_e32 v160, v160
	v_mul_f32_e32 v121, v121, v150
	v_add_f32_e32 v150, 1.0, v151
	v_rcp_f32_e32 v150, v150
	v_add_f32_e32 v151, 1.0, v160
	v_rcp_f32_e32 v151, v151
	v_cvt_pk_bf16_f32 v120, v120, v121
	v_mul_f32_e32 v121, v148, v150
	v_mul_f32_e32 v121, v122, v121
	v_mul_f32_e32 v122, v149, v151
	v_mul_f32_e32 v122, v123, v122
	v_cvt_pk_bf16_f32 v121, v121, v122
	v_mov_b64_e32 v[122:123], s[66:67]
	v_mad_i64_i32 v[122:123], s[28:29], v216, s56, v[122:123]
	v_lshl_add_u64 v[122:123], v[200:201], 1, v[122:123]
	flat_store_dwordx2 v[122:123], v[120:121]

; DEVI unsigned pk2(float lo, float hi) { unsigned r; asm("v_cvt_pk_bf16_f32 %0, %1, %2" : "=v"(r) : "v"(lo), "v"(hi)); return r; }
; DEVI float siluf_(float x) { return x * sigmoidf_(x); }
; template <int CTRL> DEVI float dppf(float old, float src) { return __int_as_float(__builtin_amdgcn_update_dpp(__float_as_int(old), __float_as_int(src), CTRL, 0xf, 0xf, false)); }
;     DEVI void operator()(const f32x4 (&acc)[2][2][4][2], const pg8::Unit& u, int wr, int wc, int fr, int fq) const {
;     ...
;                     const int row = u.pm * 256 + ai * 128 + wr * 64 + m * 16 + fr;
;                     const f32x4 g = (acc[ai][0][m][n] - mu[ai][m] * sg) * rs[ai][m] + cg_;
;                     const f32x4 uu = (acc[ai][1][m][n] - mu[ai][m] * su) * rs[ai][m] + cu;
;                     f32x4 p1, p2;
; #pragma unroll
;                     for (int e = 0; e < 4; ++e) {
;                         p1[e] = dppf<0x111>(dppf<0x121>(0.f, gprev[e]), g[e]);
;                         p2[e] = dppf<0x112>(dppf<0x122>(0.f, gprev[e]), g[e]);
;                     }
;                     const int blk = row >> 6;
;                     if (m == 0 && fr < 2) {
;                         const f32x4 pg = (fr == 0) ? (w2 * g + cbv) : (w1 * p1 + w2 * g + cbv);
;                         *(f32x4*)(headpg + ((size_t)blk * 2 + fr) * DFF + j) = pg;
;                         *(f32x4*)(headup + ((size_t)blk * 2 + fr) * DFF + j) = uu;
;                     } else {
;                         const f32x4 cv = w0 * p2 + w1 * p1 + w2 * g + cbv;
;                         u32x2 o; o.x = pk2(siluf_(cv[0]) * uu[0], siluf_(cv[1]) * uu[1]); o.y = pk2(siluf_(cv[2]) * uu[2], siluf_(cv[3]) * uu[3]);
;                         *(u32x2*)(H + (size_t)row * DFF + j) = o;
.LBB0_677:
	s_or_b64 exec, exec, s[0:1]
	s_nop 0
	v_lshl_add_u64 v[122:123], s[48:49], 0, v[174:175]
	v_mad_u64_u32 v[120:121], s[0:1], v122, s57, 0
	v_pk_fma_f32 v[116:117], v[212:213], v[152:153], v[116:117] op_sel_hi:[0,1,1] neg_lo:[1,0,0] neg_hi:[1,0,0]
	v_mad_i32_i24 v121, v123, s57, v121
	v_pk_fma_f32 v[122:123], v[214:215], v[116:117], v[156:157] op_sel_hi:[0,1,1]
	v_mov_b32_dpp v160, v236 row_ror:2 row_mask:0xf bank_mask:0xf
	v_mov_b32_dpp v161, v237 row_ror:2 row_mask:0xf bank_mask:0xf
	v_mov_b32_dpp v116, v236 row_ror:1 row_mask:0xf bank_mask:0xf
	v_mov_b32_dpp v160, v122 row_shr:2 row_mask:0xf bank_mask:0xf
	v_mov_b32_dpp v117, v237 row_ror:1 row_mask:0xf bank_mask:0xf
	v_mov_b32_dpp v161, v123 row_shr:2 row_mask:0xf bank_mask:0xf
	v_mov_b32_dpp v116, v122 row_shr:1 row_mask:0xf bank_mask:0xf
	v_mov_b32_dpp v117, v123 row_shr:1 row_mask:0xf bank_mask:0xf
	v_pk_mul_f32 v[160:161], v[144:145], v[160:161]
	v_pk_fma_f32 v[118:119], v[212:213], v[154:155], v[118:119] op_sel_hi:[0,1,1] neg_lo:[1,0,0] neg_hi:[1,0,0]
	v_pk_fma_f32 v[116:117], v[140:141], v[116:117], v[160:161]
	v_pk_fma_f32 v[116:117], v[122:123], v[136:137], v[116:117]
	v_pk_add_f32 v[116:117], v[132:133], v[116:117]
	v_pk_fma_f32 v[118:119], v[214:215], v[118:119], v[158:159] op_sel_hi:[0,1,1]
	v_mul_f32_e32 v160, 0xbfb8aa3b, v116
	v_mov_b32_dpp v236, v234 row_ror:2 row_mask:0xf bank_mask:0xf
	v_mov_b32_dpp v237, v235 row_ror:2 row_mask:0xf bank_mask:0xf
	v_exp_f32_e32 v185, v160
	v_mul_f32_e32 v160, 0xbfb8aa3b, v117
	v_mov_b32_dpp v162, v234 row_ror:1 row_mask:0xf bank_mask:0xf
	v_mov_b32_dpp v236, v118 row_shr:2 row_mask:0xf bank_mask:0xf
	v_mov_b32_dpp v163, v235 row_ror:1 row_mask:0xf bank_mask:0xf
	v_mov_b32_dpp v237, v119 row_shr:2 row_mask:0xf bank_mask:0xf
	v_exp_f32_e32 v187, v160
	v_mov_b32_dpp v162, v118 row_shr:1 row_mask:0xf bank_mask:0xf
	v_mov_b32_dpp v163, v119 row_shr:1 row_mask:0xf bank_mask:0xf
	v_pk_mul_f32 v[234:235], v[146:147], v[236:237]
	v_pk_fma_f32 v[112:113], v[212:213], v[124:125], v[112:113] op_sel_hi:[0,1,1] neg_lo:[1,0,0] neg_hi:[1,0,0]
	v_pk_fma_f32 v[162:163], v[142:143], v[162:163], v[234:235]
	v_pk_fma_f32 v[112:113], v[214:215], v[112:113], v[128:129] op_sel_hi:[0,1,1]
	v_pk_fma_f32 v[160:161], v[118:119], v[138:139], v[162:163]
	v_add_f32_e32 v162, 1.0, v185
	v_rcp_f32_e32 v162, v162
	v_add_f32_e32 v163, 1.0, v187
	v_rcp_f32_e32 v163, v163
	v_pk_add_f32 v[160:161], v[134:135], v[160:161]
	v_mul_f32_e32 v116, v116, v162
	v_mul_f32_e32 v112, v112, v116
	v_mul_f32_e32 v116, v117, v163
	v_mul_f32_e32 v117, 0xbfb8aa3b, v160
	v_mul_f32_e32 v162, 0xbfb8aa3b, v161
	v_exp_f32_e32 v117, v117
	v_exp_f32_e32 v162, v162
	v_mul_f32_e32 v113, v113, v116
	v_pk_fma_f32 v[114:115], v[212:213], v[126:127], v[114:115] op_sel_hi:[0,1,1] neg_lo:[1,0,0] neg_hi:[1,0,0]
	v_add_f32_e32 v116, 1.0, v117
	v_add_f32_e32 v117, 1.0, v162
	v_rcp_f32_e32 v116, v116
	v_rcp_f32_e32 v117, v117
	v_pk_fma_f32 v[114:115], v[214:215], v[114:115], v[130:131] op_sel_hi:[0,1,1]
	v_cvt_pk_bf16_f32 v162, v112, v113
	v_mul_f32_e32 v112, v160, v116
	v_mul_f32_e32 v113, v161, v117
	v_mul_f32_e32 v112, v114, v112
	v_mul_f32_e32 v113, v115, v113
	v_mov_b64_e32 v[114:115], s[66:67]
	v_cvt_pk_bf16_f32 v163, v112, v113
	v_mad_i64_i32 v[112:113], s[0:1], v232, s56, v[114:115]
	v_lshlrev_b64 v[116:117], 1, v[200:201]
	v_lshl_add_u64 v[112:113], v[112:113], 0, v[116:117]
	flat_store_dwordx2 v[112:113], v[162:163]
	v_pk_fma_f32 v[108:109], v[208:209], v[152:153], v[108:109] op_sel_hi:[0,1,1] neg_lo:[1,0,0] neg_hi:[1,0,0]
	v_pk_fma_f32 v[160:161], v[210:211], v[108:109], v[156:157] op_sel_hi:[0,1,1]
	v_mov_b32_dpp v162, v122 row_ror:2 row_mask:0xf bank_mask:0xf
	v_mov_b32_dpp v163, v123 row_ror:2 row_mask:0xf bank_mask:0xf
	v_mov_b32_dpp v108, v122 row_ror:1 row_mask:0xf bank_mask:0xf
	v_mov_b32_dpp v162, v160 row_shr:2 row_mask:0xf bank_mask:0xf
	v_mov_b32_dpp v109, v123 row_ror:1 row_mask:0xf bank_mask:0xf
	v_mov_b32_dpp v163, v161 row_shr:2 row_mask:0xf bank_mask:0xf
	v_pk_fma_f32 v[110:111], v[208:209], v[154:155], v[110:111] op_sel_hi:[0,1,1] neg_lo:[1,0,0] neg_hi:[1,0,0]
	v_mov_b32_dpp v108, v160 row_shr:1 row_mask:0xf bank_mask:0xf
	v_mov_b32_dpp v109, v161 row_shr:1 row_mask:0xf bank_mask:0xf
	v_pk_mul_f32 v[162:163], v[144:145], v[162:163]
	v_pk_fma_f32 v[110:111], v[210:211], v[110:111], v[158:159] op_sel_hi:[0,1,1]
	v_mov_b32_dpp v232, v118 row_ror:2 row_mask:0xf bank_mask:0xf
	v_mov_b32_dpp v233, v119 row_ror:2 row_mask:0xf bank_mask:0xf
	v_pk_fma_f32 v[108:109], v[140:141], v[108:109], v[162:163]
	v_mov_b32_dpp v122, v118 row_ror:1 row_mask:0xf bank_mask:0xf
	v_mov_b32_dpp v232, v110 row_shr:2 row_mask:0xf bank_mask:0xf
	v_mov_b32_dpp v123, v119 row_ror:1 row_mask:0xf bank_mask:0xf
	v_mov_b32_dpp v233, v111 row_shr:2 row_mask:0xf bank_mask:0xf
	v_pk_fma_f32 v[108:109], v[160:161], v[136:137], v[108:109]
	v_mov_b32_dpp v122, v110 row_shr:1 row_mask:0xf bank_mask:0xf
	v_mov_b32_dpp v123, v111 row_shr:1 row_mask:0xf bank_mask:0xf
	v_pk_mul_f32 v[118:119], v[146:147], v[232:233]
	v_pk_add_f32 v[108:109], v[132:133], v[108:109]
	v_pk_fma_f32 v[118:119], v[142:143], v[122:123], v[118:119]
	v_mul_f32_e32 v122, 0xbfb8aa3b, v108
	v_exp_f32_e32 v122, v122
	v_mul_f32_e32 v123, 0xbfb8aa3b, v109
	v_exp_f32_e32 v123, v123
	v_pk_fma_f32 v[104:105], v[208:209], v[124:125], v[104:105] op_sel_hi:[0,1,1] neg_lo:[1,0,0] neg_hi:[1,0,0]
	v_add_f32_e32 v122, 1.0, v122
	v_rcp_f32_e32 v122, v122
	v_add_f32_e32 v123, 1.0, v123
	v_rcp_f32_e32 v123, v123
	v_pk_fma_f32 v[118:119], v[110:111], v[138:139], v[118:119]
	v_pk_fma_f32 v[104:105], v[210:211], v[104:105], v[128:129] op_sel_hi:[0,1,1]
; DEVI unsigned pk2(float lo, float hi) { unsigned r; asm("v_cvt_pk_bf16_f32 %0, %1, %2" : "=v"(r) : "v"(lo), "v"(hi)); return r; }
; DEVI float siluf_(float x) { return x * sigmoidf_(x); }
; template <int CTRL> DEVI float dppf(float old, float src) { return __int_as_float(__builtin_amdgcn_update_dpp(__float_as_int(old), __float_as_int(src), CTRL, 0xf, 0xf, false)); }
;     DEVI void operator()(const f32x4 (&acc)[2][2][4][2], const pg8::Unit& u, int wr, int wc, int fr, int fq) const {
;     ...
;                     const int row = u.pm * 256 + ai * 128 + wr * 64 + m * 16 + fr;
;                     const f32x4 g = (acc[ai][0][m][n] - mu[ai][m] * sg) * rs[ai][m] + cg_;
;                     const f32x4 uu = (acc[ai][1][m][n] - mu[ai][m] * su) * rs[ai][m] + cu;
;                     f32x4 p1, p2;
; #pragma unroll
;                     for (int e = 0; e < 4; ++e) {
;                         p1[e] = dppf<0x111>(dppf<0x121>(0.f, gprev[e]), g[e]);
;                         p2[e] = dppf<0x112>(dppf<0x122>(0.f, gprev[e]), g[e]);
;                     }
;                     const int blk = row >> 6;
;                     if (m == 0 && fr < 2) {
;                         const f32x4 pg = (fr == 0) ? (w2 * g + cbv) : (w1 * p1 + w2 * g + cbv);
;                         *(f32x4*)(headpg + ((size_t)blk * 2 + fr) * DFF + j) = pg;
;                         *(f32x4*)(headup + ((size_t)blk * 2 + fr) * DFF + j) = uu;
;                     } else {
;                         const f32x4 cv = w0 * p2 + w1 * p1 + w2 * g + cbv;
;                         u32x2 o; o.x = pk2(siluf_(cv[0]) * uu[0], siluf_(cv[1]) * uu[1]); o.y = pk2(siluf_(cv[2]) * uu[2], siluf_(cv[3]) * uu[3]);
;                         *(u32x2*)(H + (size_t)row * DFF + j) = o;
;                     }
;                     if (m == 3 && fr >= 14) *(f32x4*)(tailg + ((size_t)blk * 2 + (fr - 14)) * DFF + j) = g;
	v_pk_add_f32 v[118:119], v[134:135], v[118:119]
	v_mul_f32_e32 v108, v108, v122
	v_mul_f32_e32 v104, v104, v108
	v_mul_f32_e32 v108, v109, v123
	v_mul_f32_e32 v109, 0xbfb8aa3b, v118
	v_exp_f32_e32 v109, v109
	v_mul_f32_e32 v122, 0xbfb8aa3b, v119
	v_exp_f32_e32 v122, v122
	v_mul_f32_e32 v105, v105, v108
	v_add_f32_e32 v108, 1.0, v109
	v_rcp_f32_e32 v108, v108
	v_add_f32_e32 v109, 1.0, v122
	v_rcp_f32_e32 v109, v109
	v_pk_fma_f32 v[106:107], v[208:209], v[126:127], v[106:107] op_sel_hi:[0,1,1] neg_lo:[1,0,0] neg_hi:[1,0,0]
	v_pk_fma_f32 v[106:107], v[210:211], v[106:107], v[130:131] op_sel_hi:[0,1,1]
	v_cvt_pk_bf16_f32 v104, v104, v105
	v_mul_f32_e32 v105, v118, v108
	v_mul_f32_e32 v105, v106, v105
	v_mul_f32_e32 v106, v119, v109
	v_mul_f32_e32 v106, v107, v106
	v_cvt_pk_bf16_f32 v105, v105, v106
	v_mad_i64_i32 v[106:107], s[0:1], v230, s56, v[114:115]
	v_lshl_add_u64 v[108:109], v[106:107], 0, v[116:117]
	v_pk_fma_f32 v[100:101], v[202:203], v[152:153], v[100:101] op_sel_hi:[0,1,1] neg_lo:[1,0,0] neg_hi:[1,0,0]
	flat_store_dwordx2 v[108:109], v[104:105]
	v_pk_fma_f32 v[100:101], v[204:205], v[100:101], v[156:157] op_sel_hi:[0,1,1]
	v_mov_b32_dpp v106, v160 row_ror:2 row_mask:0xf bank_mask:0xf
	v_mov_b32_dpp v107, v161 row_ror:2 row_mask:0xf bank_mask:0xf
	v_mov_b32_dpp v104, v160 row_ror:1 row_mask:0xf bank_mask:0xf
	v_mov_b32_dpp v106, v100 row_shr:2 row_mask:0xf bank_mask:0xf
	v_mov_b32_dpp v105, v161 row_ror:1 row_mask:0xf bank_mask:0xf
	v_mov_b32_dpp v107, v101 row_shr:2 row_mask:0xf bank_mask:0xf
	v_mov_b32_dpp v104, v100 row_shr:1 row_mask:0xf bank_mask:0xf
	v_mov_b32_dpp v105, v101 row_shr:1 row_mask:0xf bank_mask:0xf
	v_pk_mul_f32 v[106:107], v[144:145], v[106:107]
	v_pk_fma_f32 v[102:103], v[202:203], v[154:155], v[102:103] op_sel_hi:[0,1,1] neg_lo:[1,0,0] neg_hi:[1,0,0]
	v_pk_fma_f32 v[104:105], v[140:141], v[104:105], v[106:107]
	v_pk_fma_f32 v[102:103], v[204:205], v[102:103], v[158:159] op_sel_hi:[0,1,1]
	v_mov_b32_dpp v122, v110 row_ror:2 row_mask:0xf bank_mask:0xf
	v_mov_b32_dpp v123, v111 row_ror:2 row_mask:0xf bank_mask:0xf
	v_pk_fma_f32 v[104:105], v[100:101], v[136:137], v[104:105]
	v_mov_b32_dpp v118, v110 row_ror:1 row_mask:0xf bank_mask:0xf
	v_mov_b32_dpp v122, v102 row_shr:2 row_mask:0xf bank_mask:0xf
	v_mov_b32_dpp v119, v111 row_ror:1 row_mask:0xf bank_mask:0xf
	v_mov_b32_dpp v123, v103 row_shr:2 row_mask:0xf bank_mask:0xf
	v_pk_add_f32 v[104:105], v[132:133], v[104:105]
	v_mov_b32_dpp v118, v102 row_shr:1 row_mask:0xf bank_mask:0xf
	v_mov_b32_dpp v119, v103 row_shr:1 row_mask:0xf bank_mask:0xf
	v_pk_mul_f32 v[110:111], v[146:147], v[122:123]
	v_mul_f32_e32 v106, 0xbfb8aa3b, v104
	v_pk_fma_f32 v[110:111], v[142:143], v[118:119], v[110:111]
	v_exp_f32_e32 v118, v106
	v_mul_f32_e32 v106, 0xbfb8aa3b, v105
	v_exp_f32_e32 v119, v106
	v_pk_fma_f32 v[106:107], v[102:103], v[138:139], v[110:111]
	v_add_f32_e32 v110, 1.0, v118
	v_rcp_f32_e32 v110, v110
	v_add_f32_e32 v111, 1.0, v119
	v_rcp_f32_e32 v111, v111
	v_pk_fma_f32 v[96:97], v[202:203], v[124:125], v[96:97] op_sel_hi:[0,1,1] neg_lo:[1,0,0] neg_hi:[1,0,0]
	v_pk_fma_f32 v[96:97], v[204:205], v[96:97], v[128:129] op_sel_hi:[0,1,1]
	v_pk_add_f32 v[106:107], v[134:135], v[106:107]
	v_mul_f32_e32 v104, v104, v110
	v_mul_f32_e32 v96, v96, v104
	v_mul_f32_e32 v104, v105, v111
	v_mul_f32_e32 v105, 0xbfb8aa3b, v106
	v_exp_f32_e32 v105, v105
	v_mul_f32_e32 v110, 0xbfb8aa3b, v107
	v_exp_f32_e32 v110, v110
	v_mul_f32_e32 v97, v97, v104
	v_add_f32_e32 v104, 1.0, v105
	v_rcp_f32_e32 v104, v104
	v_add_f32_e32 v105, 1.0, v110
	v_rcp_f32_e32 v105, v105
	v_pk_fma_f32 v[98:99], v[202:203], v[126:127], v[98:99] op_sel_hi:[0,1,1] neg_lo:[1,0,0] neg_hi:[1,0,0]
	v_pk_fma_f32 v[98:99], v[204:205], v[98:99], v[130:131] op_sel_hi:[0,1,1]
	v_cvt_pk_bf16_f32 v96, v96, v97
	v_mul_f32_e32 v97, v106, v104
	v_mul_f32_e32 v97, v98, v97
	v_mul_f32_e32 v98, v107, v105
	v_mul_f32_e32 v98, v99, v98
	v_cvt_pk_bf16_f32 v97, v97, v98
	v_mad_i64_i32 v[98:99], s[0:1], v228, s56, v[114:115]
	v_lshl_add_u64 v[106:107], v[98:99], 0, v[116:117]
	flat_store_dwordx2 v[106:107], v[96:97]
	v_lshl_add_u64 v[96:97], s[78:79], 0, v[120:121]
	v_lshl_add_u64 v[98:99], v[200:201], 2, v[96:97]
	s_and_saveexec_b64 s[0:1], s[6:7]
	s_cbranch_execz .LBB0_679
	flat_store_dwordx4 v[98:99], v[100:103]
; DEVI unsigned pk2(float lo, float hi) { unsigned r; asm("v_cvt_pk_bf16_f32 %0, %1, %2" : "=v"(r) : "v"(lo), "v"(hi)); return r; }
; DEVI float siluf_(float x) { return x * sigmoidf_(x); }
; template <int CTRL> DEVI float dppf(float old, float src) { return __int_as_float(__builtin_amdgcn_update_dpp(__float_as_int(old), __float_as_int(src), CTRL, 0xf, 0xf, false)); }
;     DEVI void operator()(const f32x4 (&acc)[2][2][4][2], const pg8::Unit& u, int wr, int wc, int fr, int fq) const {
;     ...
;                 for (int m = 0; m < 4; ++m) {
;                     const int row = u.pm * 256 + ai * 128 + wr * 64 + m * 16 + fr;
;                     const f32x4 g = (acc[ai][0][m][n] - mu[ai][m] * sg) * rs[ai][m] + cg_;
;                     const f32x4 uu = (acc[ai][1][m][n] - mu[ai][m] * su) * rs[ai][m] + cu;
;                     f32x4 p1, p2;
; #pragma unroll
;                     for (int e = 0; e < 4; ++e) {
;                         p1[e] = dppf<0x111>(dppf<0x121>(0.f, gprev[e]), g[e]);
;                         p2[e] = dppf<0x112>(dppf<0x122>(0.f, gprev[e]), g[e]);
;                     }
;                     const int blk = row >> 6;
;                     if (m == 0 && fr < 2) {
;                         const f32x4 pg = (fr == 0) ? (w2 * g + cbv) : (w1 * p1 + w2 * g + cbv);
;                         *(f32x4*)(headpg + ((size_t)blk * 2 + fr) * DFF + j) = pg;
;                         *(f32x4*)(headup + ((size_t)blk * 2 + fr) * DFF + j) = uu;
;                     } else {
;                         const f32x4 cv = w0 * p2 + w1 * p1 + w2 * g + cbv;
;                         u32x2 o; o.x = pk2(siluf_(cv[0]) * uu[0], siluf_(cv[1]) * uu[1]); o.y = pk2(siluf_(cv[2]) * uu[2], siluf_(cv[3]) * uu[3]);
;                         *(u32x2*)(H + (size_t)row * DFF + j) = o;
.LBB0_679:
	s_or_b64 exec, exec, s[0:1]
	s_nop 0
	v_pk_fma_f32 v[94:95], v[198:199], v[154:155], v[94:95] op_sel_hi:[0,1,1] neg_lo:[1,0,0] neg_hi:[1,0,0]
	v_pk_fma_f32 v[92:93], v[198:199], v[152:153], v[92:93] op_sel_hi:[0,1,1] neg_lo:[1,0,0] neg_hi:[1,0,0]
	v_mov_b32_dpp v103, v103 row_ror:1 row_mask:0xf bank_mask:0xf
	v_mov_b32_dpp v105, v105 row_ror:2 row_mask:0xf bank_mask:0xf
	s_addk_i32 s41, 0x80
	v_pk_fma_f32 v[96:97], v[196:197], v[94:95], v[158:159] op_sel_hi:[0,1,1]
	v_pk_fma_f32 v[100:101], v[196:197], v[92:93], v[156:157] op_sel_hi:[0,1,1]
	v_pk_fma_f32 v[90:91], v[198:199], v[126:127], v[90:91] op_sel_hi:[0,1,1] neg_lo:[1,0,0] neg_hi:[1,0,0]
	v_pk_fma_f32 v[88:89], v[198:199], v[124:125], v[88:89] op_sel_hi:[0,1,1] neg_lo:[1,0,0] neg_hi:[1,0,0]
	v_mov_b32_e32 v92, v103
	v_mov_b32_e32 v94, v105
	v_mov_b32_e32 v93, v103
	v_mov_b32_e32 v95, v105
	v_mov_b32_e32 v102, v103
	v_mov_b32_e32 v104, v105
	v_or_b32_e32 v160, s41, v172
	v_mov_b32_dpp v92, v100 row_shr:1 row_mask:0xf bank_mask:0xf
	v_mov_b32_dpp v94, v100 row_shr:2 row_mask:0xf bank_mask:0xf
	v_mov_b32_dpp v93, v101 row_shr:1 row_mask:0xf bank_mask:0xf
	v_mov_b32_dpp v95, v101 row_shr:2 row_mask:0xf bank_mask:0xf
	v_mov_b32_dpp v102, v96 row_shr:1 row_mask:0xf bank_mask:0xf
	v_mov_b32_dpp v104, v96 row_shr:2 row_mask:0xf bank_mask:0xf
	v_mov_b32_dpp v103, v97 row_shr:1 row_mask:0xf bank_mask:0xf
	v_mov_b32_dpp v105, v97 row_shr:2 row_mask:0xf bank_mask:0xf
	v_pk_fma_f32 v[90:91], v[196:197], v[90:91], v[130:131] op_sel_hi:[0,1,1]
	v_pk_fma_f32 v[88:89], v[196:197], v[88:89], v[128:129] op_sel_hi:[0,1,1]
	s_and_saveexec_b64 s[0:1], s[2:3]
	s_xor_b64 s[0:1], exec, s[0:1]
	s_cbranch_execz .LBB0_681
	v_pk_mul_f32 v[94:95], v[144:145], v[94:95]
	v_pk_mul_f32 v[104:105], v[146:147], v[104:105]
	v_pk_fma_f32 v[92:93], v[140:141], v[92:93], v[94:95]
	v_pk_fma_f32 v[102:103], v[142:143], v[102:103], v[104:105]
	v_pk_fma_f32 v[92:93], v[100:101], v[136:137], v[92:93]
	s_nop 0
	v_pk_add_f32 v[92:93], v[132:133], v[92:93]
	s_nop 0
	v_mul_f32_e32 v94, 0xbfb8aa3b, v92
	v_exp_f32_e32 v104, v94
	v_mul_f32_e32 v94, 0xbfb8aa3b, v93
	v_exp_f32_e32 v105, v94
	v_pk_fma_f32 v[94:95], v[96:97], v[138:139], v[102:103]
	v_add_f32_e32 v102, 1.0, v104
	v_rcp_f32_e32 v102, v102
	v_add_f32_e32 v103, 1.0, v105
	v_rcp_f32_e32 v103, v103
	v_pk_add_f32 v[94:95], v[134:135], v[94:95]
	v_mul_f32_e32 v92, v92, v102
	v_mul_f32_e32 v88, v88, v92
	v_mul_f32_e32 v92, v93, v103
	v_mul_f32_e32 v93, 0xbfb8aa3b, v94
	v_exp_f32_e32 v93, v93
	v_mul_f32_e32 v102, 0xbfb8aa3b, v95
	v_exp_f32_e32 v102, v102
	v_mul_f32_e32 v89, v89, v92
	v_add_f32_e32 v92, 1.0, v93
	v_rcp_f32_e32 v92, v92
	v_add_f32_e32 v93, 1.0, v102
	v_rcp_f32_e32 v93, v93
	v_cvt_pk_bf16_f32 v88, v88, v89
	v_mul_f32_e32 v89, v94, v92
	v_mul_f32_e32 v89, v90, v89
	v_mul_f32_e32 v90, v95, v93
	v_mul_f32_e32 v90, v91, v90
	v_cvt_pk_bf16_f32 v89, v89, v90
	v_mov_b64_e32 v[90:91], s[66:67]
	v_mad_i64_i32 v[90:91], s[28:29], v160, s56, v[90:91]
	v_lshl_add_u64 v[90:91], v[200:201], 1, v[90:91]
	flat_store_dwordx2 v[90:91], v[88:89]

; DEVI unsigned pk2(float lo, float hi) { unsigned r; asm("v_cvt_pk_bf16_f32 %0, %1, %2" : "=v"(r) : "v"(lo), "v"(hi)); return r; }
; DEVI float siluf_(float x) { return x * sigmoidf_(x); }
; template <int CTRL> DEVI float dppf(float old, float src) { return __int_as_float(__builtin_amdgcn_update_dpp(__float_as_int(old), __float_as_int(src), CTRL, 0xf, 0xf, false)); }
;     DEVI void operator()(const f32x4 (&acc)[2][2][4][2], const pg8::Unit& u, int wr, int wc, int fr, int fq) const {
;     ...
;                 for (int m = 0; m < 4; ++m) {
;                     const int row = u.pm * 256 + ai * 128 + wr * 64 + m * 16 + fr;
;                     const f32x4 g = (acc[ai][0][m][n] - mu[ai][m] * sg) * rs[ai][m] + cg_;
;                     const f32x4 uu = (acc[ai][1][m][n] - mu[ai][m] * su) * rs[ai][m] + cu;
;                     f32x4 p1, p2;
; #pragma unroll
;                     for (int e = 0; e < 4; ++e) {
;                         p1[e] = dppf<0x111>(dppf<0x121>(0.f, gprev[e]), g[e]);
;                         p2[e] = dppf<0x112>(dppf<0x122>(0.f, gprev[e]), g[e]);
;                     }
;                     const int blk = row >> 6;
;                     if (m == 0 && fr < 2) {
;                         const f32x4 pg = (fr == 0) ? (w2 * g + cbv) : (w1 * p1 + w2 * g + cbv);
;                         *(f32x4*)(headpg + ((size_t)blk * 2 + fr) * DFF + j) = pg;
;                         *(f32x4*)(headup + ((size_t)blk * 2 + fr) * DFF + j) = uu;
;                     } else {
;                         const f32x4 cv = w0 * p2 + w1 * p1 + w2 * g + cbv;
;                         u32x2 o; o.x = pk2(siluf_(cv[0]) * uu[0], siluf_(cv[1]) * uu[1]); o.y = pk2(siluf_(cv[2]) * uu[2], siluf_(cv[3]) * uu[3]);
;                         *(u32x2*)(H + (size_t)row * DFF + j) = o;
.LBB0_683:
	s_or_b64 exec, exec, s[0:1]
	s_nop 0
	v_lshl_add_u64 v[90:91], s[48:49], 0, v[174:175]
	v_mad_u64_u32 v[88:89], s[0:1], v90, s57, 0
	v_pk_fma_f32 v[84:85], v[192:193], v[152:153], v[84:85] op_sel_hi:[0,1,1] neg_lo:[1,0,0] neg_hi:[1,0,0]
	v_mad_i32_i24 v89, v91, s57, v89
	v_pk_fma_f32 v[84:85], v[194:195], v[84:85], v[156:157] op_sel_hi:[0,1,1]
	v_mov_b32_dpp v92, v100 row_ror:2 row_mask:0xf bank_mask:0xf
	v_mov_b32_dpp v93, v101 row_ror:2 row_mask:0xf bank_mask:0xf
	v_mov_b32_dpp v90, v100 row_ror:1 row_mask:0xf bank_mask:0xf
	v_mov_b32_dpp v92, v84 row_shr:2 row_mask:0xf bank_mask:0xf
	v_mov_b32_dpp v91, v101 row_ror:1 row_mask:0xf bank_mask:0xf
	v_mov_b32_dpp v93, v85 row_shr:2 row_mask:0xf bank_mask:0xf
	v_mov_b32_dpp v90, v84 row_shr:1 row_mask:0xf bank_mask:0xf
	v_mov_b32_dpp v91, v85 row_shr:1 row_mask:0xf bank_mask:0xf
	v_pk_mul_f32 v[92:93], v[144:145], v[92:93]
	v_pk_fma_f32 v[86:87], v[192:193], v[154:155], v[86:87] op_sel_hi:[0,1,1] neg_lo:[1,0,0] neg_hi:[1,0,0]
	v_pk_fma_f32 v[90:91], v[140:141], v[90:91], v[92:93]
	v_pk_fma_f32 v[86:87], v[194:195], v[86:87], v[158:159] op_sel_hi:[0,1,1]
	v_mov_b32_dpp v100, v96 row_ror:2 row_mask:0xf bank_mask:0xf
	v_mov_b32_dpp v101, v97 row_ror:2 row_mask:0xf bank_mask:0xf
	v_pk_fma_f32 v[90:91], v[84:85], v[136:137], v[90:91]
	v_mov_b32_dpp v94, v96 row_ror:1 row_mask:0xf bank_mask:0xf
	v_mov_b32_dpp v100, v86 row_shr:2 row_mask:0xf bank_mask:0xf
	v_mov_b32_dpp v95, v97 row_ror:1 row_mask:0xf bank_mask:0xf
	v_mov_b32_dpp v101, v87 row_shr:2 row_mask:0xf bank_mask:0xf
	v_pk_add_f32 v[90:91], v[132:133], v[90:91]
	v_mov_b32_dpp v94, v86 row_shr:1 row_mask:0xf bank_mask:0xf
	v_mov_b32_dpp v95, v87 row_shr:1 row_mask:0xf bank_mask:0xf
	v_pk_mul_f32 v[96:97], v[146:147], v[100:101]
	v_mul_f32_e32 v92, 0xbfb8aa3b, v90
	v_pk_fma_f32 v[94:95], v[142:143], v[94:95], v[96:97]
	v_exp_f32_e32 v96, v92
	v_mul_f32_e32 v92, 0xbfb8aa3b, v91
	v_exp_f32_e32 v97, v92
	v_pk_fma_f32 v[92:93], v[86:87], v[138:139], v[94:95]
	v_add_f32_e32 v94, 1.0, v96
	v_rcp_f32_e32 v94, v94
	v_add_f32_e32 v95, 1.0, v97
	v_rcp_f32_e32 v95, v95
	v_pk_fma_f32 v[80:81], v[192:193], v[124:125], v[80:81] op_sel_hi:[0,1,1] neg_lo:[1,0,0] neg_hi:[1,0,0]
	v_pk_fma_f32 v[80:81], v[194:195], v[80:81], v[128:129] op_sel_hi:[0,1,1]
	v_pk_add_f32 v[92:93], v[134:135], v[92:93]
	v_mul_f32_e32 v90, v90, v94
	v_mul_f32_e32 v80, v80, v90
	v_mul_f32_e32 v90, v91, v95
	v_mul_f32_e32 v91, 0xbfb8aa3b, v92
	v_exp_f32_e32 v91, v91
	v_mul_f32_e32 v94, 0xbfb8aa3b, v93
	v_exp_f32_e32 v94, v94
	v_mul_f32_e32 v81, v81, v90
	v_add_f32_e32 v90, 1.0, v91
	v_rcp_f32_e32 v90, v90
	v_add_f32_e32 v91, 1.0, v94
	v_rcp_f32_e32 v91, v91
	v_pk_fma_f32 v[82:83], v[192:193], v[126:127], v[82:83] op_sel_hi:[0,1,1] neg_lo:[1,0,0] neg_hi:[1,0,0]
	v_pk_fma_f32 v[82:83], v[194:195], v[82:83], v[130:131] op_sel_hi:[0,1,1]
	v_cvt_pk_bf16_f32 v80, v80, v81
	v_mul_f32_e32 v81, v92, v90
	v_mul_f32_e32 v81, v82, v81
	v_mul_f32_e32 v82, v93, v91
	v_mul_f32_e32 v82, v83, v82
	v_or_b32_e32 v102, 16, v160
	v_cvt_pk_bf16_f32 v81, v81, v82
	v_mov_b64_e32 v[82:83], s[66:67]
	v_mad_i64_i32 v[90:91], s[0:1], v102, s56, v[82:83]
	v_lshl_add_u64 v[100:101], v[90:91], 0, v[116:117]
	v_pk_fma_f32 v[76:77], v[188:189], v[152:153], v[76:77] op_sel_hi:[0,1,1] neg_lo:[1,0,0] neg_hi:[1,0,0]
	flat_store_dwordx2 v[100:101], v[80:81]
	v_pk_fma_f32 v[76:77], v[190:191], v[76:77], v[156:157] op_sel_hi:[0,1,1]
	v_mov_b32_dpp v90, v84 row_ror:2 row_mask:0xf bank_mask:0xf
	v_mov_b32_dpp v91, v85 row_ror:2 row_mask:0xf bank_mask:0xf
	v_mov_b32_dpp v80, v84 row_ror:1 row_mask:0xf bank_mask:0xf
	v_mov_b32_dpp v90, v76 row_shr:2 row_mask:0xf bank_mask:0xf
	v_mov_b32_dpp v81, v85 row_ror:1 row_mask:0xf bank_mask:0xf
	v_mov_b32_dpp v91, v77 row_shr:2 row_mask:0xf bank_mask:0xf
	v_pk_fma_f32 v[78:79], v[188:189], v[154:155], v[78:79] op_sel_hi:[0,1,1] neg_lo:[1,0,0] neg_hi:[1,0,0]
	v_mov_b32_dpp v80, v76 row_shr:1 row_mask:0xf bank_mask:0xf
	v_mov_b32_dpp v81, v77 row_shr:1 row_mask:0xf bank_mask:0xf
	v_pk_mul_f32 v[90:91], v[144:145], v[90:91]
	v_pk_fma_f32 v[78:79], v[190:191], v[78:79], v[158:159] op_sel_hi:[0,1,1]
	v_mov_b32_dpp v92, v86 row_ror:2 row_mask:0xf bank_mask:0xf
	v_mov_b32_dpp v93, v87 row_ror:2 row_mask:0xf bank_mask:0xf
	v_pk_fma_f32 v[80:81], v[140:141], v[80:81], v[90:91]
	v_mov_b32_dpp v84, v86 row_ror:1 row_mask:0xf bank_mask:0xf
	v_mov_b32_dpp v92, v78 row_shr:2 row_mask:0xf bank_mask:0xf
	v_mov_b32_dpp v85, v87 row_ror:1 row_mask:0xf bank_mask:0xf
	v_mov_b32_dpp v93, v79 row_shr:2 row_mask:0xf bank_mask:0xf
	v_pk_fma_f32 v[80:81], v[76:77], v[136:137], v[80:81]
	v_mov_b32_dpp v84, v78 row_shr:1 row_mask:0xf bank_mask:0xf
	v_mov_b32_dpp v85, v79 row_shr:1 row_mask:0xf bank_mask:0xf
	v_pk_mul_f32 v[86:87], v[146:147], v[92:93]
	v_pk_add_f32 v[80:81], v[132:133], v[80:81]
	v_pk_fma_f32 v[84:85], v[142:143], v[84:85], v[86:87]
	v_mul_f32_e32 v86, 0xbfb8aa3b, v80
	v_exp_f32_e32 v86, v86
	v_mul_f32_e32 v87, 0xbfb8aa3b, v81
	v_exp_f32_e32 v87, v87
	v_pk_fma_f32 v[72:73], v[188:189], v[124:125], v[72:73] op_sel_hi:[0,1,1] neg_lo:[1,0,0] neg_hi:[1,0,0]
	v_add_f32_e32 v86, 1.0, v86
	v_rcp_f32_e32 v86, v86
	v_add_f32_e32 v87, 1.0, v87
	v_rcp_f32_e32 v87, v87
	v_pk_fma_f32 v[84:85], v[78:79], v[138:139], v[84:85]
	v_pk_fma_f32 v[72:73], v[190:191], v[72:73], v[128:129] op_sel_hi:[0,1,1]
	v_pk_add_f32 v[84:85], v[134:135], v[84:85]
	v_mul_f32_e32 v80, v80, v86
	v_mul_f32_e32 v72, v72, v80
	v_mul_f32_e32 v80, v81, v87
	v_mul_f32_e32 v81, 0xbfb8aa3b, v84
	v_exp_f32_e32 v81, v81
	v_mul_f32_e32 v86, 0xbfb8aa3b, v85
	v_exp_f32_e32 v86, v86
	v_mul_f32_e32 v73, v73, v80
	v_add_f32_e32 v80, 1.0, v81
; DEVI unsigned pk2(float lo, float hi) { unsigned r; asm("v_cvt_pk_bf16_f32 %0, %1, %2" : "=v"(r) : "v"(lo), "v"(hi)); return r; }
; DEVI float siluf_(float x) { return x * sigmoidf_(x); }
; template <int CTRL> DEVI float dppf(float old, float src) { return __int_as_float(__builtin_amdgcn_update_dpp(__float_as_int(old), __float_as_int(src), CTRL, 0xf, 0xf, false)); }
;     DEVI void operator()(const f32x4 (&acc)[2][2][4][2], const pg8::Unit& u, int wr, int wc, int fr, int fq) const {
;     ...
;                     const int row = u.pm * 256 + ai * 128 + wr * 64 + m * 16 + fr;
;                     const f32x4 g = (acc[ai][0][m][n] - mu[ai][m] * sg) * rs[ai][m] + cg_;
;                     const f32x4 uu = (acc[ai][1][m][n] - mu[ai][m] * su) * rs[ai][m] + cu;
;                     f32x4 p1, p2;
; #pragma unroll
;                     for (int e = 0; e < 4; ++e) {
;                         p1[e] = dppf<0x111>(dppf<0x121>(0.f, gprev[e]), g[e]);
;                         p2[e] = dppf<0x112>(dppf<0x122>(0.f, gprev[e]), g[e]);
;                     }
;                     const int blk = row >> 6;
;                     if (m == 0 && fr < 2) {
;                         const f32x4 pg = (fr == 0) ? (w2 * g + cbv) : (w1 * p1 + w2 * g + cbv);
;                         *(f32x4*)(headpg + ((size_t)blk * 2 + fr) * DFF + j) = pg;
;                         *(f32x4*)(headup + ((size_t)blk * 2 + fr) * DFF + j) = uu;
;                     } else {
;                         const f32x4 cv = w0 * p2 + w1 * p1 + w2 * g + cbv;
;                         u32x2 o; o.x = pk2(siluf_(cv[0]) * uu[0], siluf_(cv[1]) * uu[1]); o.y = pk2(siluf_(cv[2]) * uu[2], siluf_(cv[3]) * uu[3]);
;                         *(u32x2*)(H + (size_t)row * DFF + j) = o;
;                     }
;                     if (m == 3 && fr >= 14) *(f32x4*)(tailg + ((size_t)blk * 2 + (fr - 14)) * DFF + j) = g;
	v_rcp_f32_e32 v80, v80
	v_add_f32_e32 v81, 1.0, v86
	v_rcp_f32_e32 v81, v81
	v_pk_fma_f32 v[74:75], v[188:189], v[126:127], v[74:75] op_sel_hi:[0,1,1] neg_lo:[1,0,0] neg_hi:[1,0,0]
	v_pk_fma_f32 v[74:75], v[190:191], v[74:75], v[130:131] op_sel_hi:[0,1,1]
	v_cvt_pk_bf16_f32 v72, v72, v73
	v_mul_f32_e32 v73, v84, v80
	v_mul_f32_e32 v73, v74, v73
	v_mul_f32_e32 v74, v85, v81
	v_or_b32_e32 v94, 32, v160
	v_mul_f32_e32 v74, v75, v74
	v_cvt_pk_bf16_f32 v73, v73, v74
	v_mad_i64_i32 v[74:75], s[0:1], v94, s56, v[82:83]
	v_lshl_add_u64 v[102:103], v[74:75], 0, v[116:117]
	v_pk_fma_f32 v[68:69], v[184:185], v[152:153], v[68:69] op_sel_hi:[0,1,1] neg_lo:[1,0,0] neg_hi:[1,0,0]
	flat_store_dwordx2 v[102:103], v[72:73]
	v_pk_fma_f32 v[68:69], v[186:187], v[68:69], v[156:157] op_sel_hi:[0,1,1]
	v_mov_b32_dpp v74, v76 row_ror:2 row_mask:0xf bank_mask:0xf
	v_mov_b32_dpp v75, v77 row_ror:2 row_mask:0xf bank_mask:0xf
	v_mov_b32_dpp v72, v76 row_ror:1 row_mask:0xf bank_mask:0xf
	v_mov_b32_dpp v74, v68 row_shr:2 row_mask:0xf bank_mask:0xf
	v_mov_b32_dpp v73, v77 row_ror:1 row_mask:0xf bank_mask:0xf
	v_mov_b32_dpp v75, v69 row_shr:2 row_mask:0xf bank_mask:0xf
	v_mov_b32_dpp v72, v68 row_shr:1 row_mask:0xf bank_mask:0xf
	v_mov_b32_dpp v73, v69 row_shr:1 row_mask:0xf bank_mask:0xf
	v_pk_mul_f32 v[74:75], v[144:145], v[74:75]
	v_pk_fma_f32 v[70:71], v[184:185], v[154:155], v[70:71] op_sel_hi:[0,1,1] neg_lo:[1,0,0] neg_hi:[1,0,0]
	v_pk_fma_f32 v[72:73], v[140:141], v[72:73], v[74:75]
	v_pk_fma_f32 v[70:71], v[186:187], v[70:71], v[158:159] op_sel_hi:[0,1,1]
	v_mov_b32_dpp v80, v78 row_ror:2 row_mask:0xf bank_mask:0xf
	v_mov_b32_dpp v81, v79 row_ror:2 row_mask:0xf bank_mask:0xf
	v_pk_fma_f32 v[72:73], v[68:69], v[136:137], v[72:73]
	v_mov_b32_dpp v76, v78 row_ror:1 row_mask:0xf bank_mask:0xf
	v_mov_b32_dpp v80, v70 row_shr:2 row_mask:0xf bank_mask:0xf
	v_mov_b32_dpp v77, v79 row_ror:1 row_mask:0xf bank_mask:0xf
	v_mov_b32_dpp v81, v71 row_shr:2 row_mask:0xf bank_mask:0xf
	v_pk_add_f32 v[72:73], v[132:133], v[72:73]
	v_mov_b32_dpp v76, v70 row_shr:1 row_mask:0xf bank_mask:0xf
	v_mov_b32_dpp v77, v71 row_shr:1 row_mask:0xf bank_mask:0xf
	v_pk_mul_f32 v[78:79], v[146:147], v[80:81]
	v_mul_f32_e32 v74, 0xbfb8aa3b, v72
	v_pk_fma_f32 v[76:77], v[142:143], v[76:77], v[78:79]
	v_exp_f32_e32 v78, v74
	v_mul_f32_e32 v74, 0xbfb8aa3b, v73
	v_exp_f32_e32 v79, v74
	v_pk_fma_f32 v[74:75], v[70:71], v[138:139], v[76:77]
	v_add_f32_e32 v76, 1.0, v78
	v_rcp_f32_e32 v76, v76
	v_add_f32_e32 v77, 1.0, v79
	v_rcp_f32_e32 v77, v77
	v_pk_fma_f32 v[64:65], v[184:185], v[124:125], v[64:65] op_sel_hi:[0,1,1] neg_lo:[1,0,0] neg_hi:[1,0,0]
	v_pk_fma_f32 v[64:65], v[186:187], v[64:65], v[128:129] op_sel_hi:[0,1,1]
	v_pk_add_f32 v[74:75], v[134:135], v[74:75]
	v_mul_f32_e32 v72, v72, v76
	v_mul_f32_e32 v64, v64, v72
	v_mul_f32_e32 v72, v73, v77
	v_mul_f32_e32 v73, 0xbfb8aa3b, v74
	v_exp_f32_e32 v73, v73
	v_mul_f32_e32 v76, 0xbfb8aa3b, v75
	v_exp_f32_e32 v76, v76
	v_mul_f32_e32 v65, v65, v72
	v_add_f32_e32 v72, 1.0, v73
	v_rcp_f32_e32 v72, v72
	v_add_f32_e32 v73, 1.0, v76
	v_rcp_f32_e32 v73, v73
	v_pk_fma_f32 v[66:67], v[184:185], v[126:127], v[66:67] op_sel_hi:[0,1,1] neg_lo:[1,0,0] neg_hi:[1,0,0]
	v_pk_fma_f32 v[66:67], v[186:187], v[66:67], v[130:131] op_sel_hi:[0,1,1]
	v_cvt_pk_bf16_f32 v64, v64, v65
	v_mul_f32_e32 v65, v74, v72
	v_mul_f32_e32 v65, v66, v65
	v_mul_f32_e32 v66, v75, v73
	v_or_b32_e32 v84, 48, v160
	v_mul_f32_e32 v66, v67, v66
	v_cvt_pk_bf16_f32 v65, v65, v66
	v_mad_i64_i32 v[66:67], s[0:1], v84, s56, v[82:83]
	v_lshl_add_u64 v[104:105], v[66:67], 0, v[116:117]
	flat_store_dwordx2 v[104:105], v[64:65]
	v_lshl_add_u64 v[64:65], s[78:79], 0, v[88:89]
	v_lshl_add_u64 v[96:97], v[200:201], 2, v[64:65]
	s_and_saveexec_b64 s[0:1], s[6:7]
	s_cbranch_execz .LBB0_685
	flat_store_dwordx4 v[96:97], v[68:71]
; DEVI unsigned pk2(float lo, float hi) { unsigned r; asm("v_cvt_pk_bf16_f32 %0, %1, %2" : "=v"(r) : "v"(lo), "v"(hi)); return r; }
; DEVI float siluf_(float x) { return x * sigmoidf_(x); }
; template <int CTRL> DEVI float dppf(float old, float src) { return __int_as_float(__builtin_amdgcn_update_dpp(__float_as_int(old), __float_as_int(src), CTRL, 0xf, 0xf, false)); }
;     DEVI void operator()(const f32x4 (&acc)[2][2][4][2], const pg8::Unit& u, int wr, int wc, int fr, int fq) const {
;     ...
;             const int tc = u.pn * 256 + wc * 32 + 8 * fq + 4 * n;
;             const int j = u.pn * 128 + wc * 32 + 8 * fq + 4 * n;
;             const f32x4 sg = *(const f32x4*)(s + tc), cg_ = *(const f32x4*)(c + tc), su = *(const f32x4*)(s + tc + 128), cu = *(const f32x4*)(c + tc + 128);
;             const f32x4 w0 = *(const f32x4*)(cw + j), w1 = *(const f32x4*)(cw + DFF + j), w2 = *(const f32x4*)(cw + 2 * DFF + j), cbv = *(const f32x4*)(cb + j);
; #pragma unroll
;             for (int ai = 0; ai < 2; ++ai) {
;                 f32x4 gprev = (f32x4){0.f, 0.f, 0.f, 0.f};
; #pragma unroll
;                 for (int m = 0; m < 4; ++m) {
;                     const int row = u.pm * 256 + ai * 128 + wr * 64 + m * 16 + fr;
;                     const f32x4 g = (acc[ai][0][m][n] - mu[ai][m] * sg) * rs[ai][m] + cg_;
;                     const f32x4 uu = (acc[ai][1][m][n] - mu[ai][m] * su) * rs[ai][m] + cu;
;                     f32x4 p1, p2;
; #pragma unroll
;                     for (int e = 0; e < 4; ++e) {
;                         p1[e] = dppf<0x111>(dppf<0x121>(0.f, gprev[e]), g[e]);
;                         p2[e] = dppf<0x112>(dppf<0x122>(0.f, gprev[e]), g[e]);
;                     }
;                     const int blk = row >> 6;
;                     if (m == 0 && fr < 2) {
;                         const f32x4 pg = (fr == 0) ? (w2 * g + cbv) : (w1 * p1 + w2 * g + cbv);
;                         *(f32x4*)(headpg + ((size_t)blk * 2 + fr) * DFF + j) = pg;
;                         *(f32x4*)(headup + ((size_t)blk * 2 + fr) * DFF + j) = uu;
;                     } else {
;                         const f32x4 cv = w0 * p2 + w1 * p1 + w2 * g + cbv;
;                         u32x2 o; o.x = pk2(siluf_(cv[0]) * uu[0], siluf_(cv[1]) * uu[1]); o.y = pk2(siluf_(cv[2]) * uu[2], siluf_(cv[3]) * uu[3]);
;                         *(u32x2*)(H + (size_t)row * DFF + j) = o;
.LBB0_685:
	s_or_b64 exec, exec, s[0:1]
	v_or_b32_e32 v64, 4, v226
	v_ashrrev_i32_e32 v65, 31, v64
	v_lshlrev_b64 v[64:65], 2, v[64:65]
	v_lshl_add_u64 v[68:69], s[70:71], 0, v[64:65]
	v_or_b32_e32 v66, 4, v200
	flat_load_dwordx4 v[92:95], v[68:69]
	v_lshl_add_u64 v[64:65], s[74:75], 0, v[64:65]
	flat_load_dwordx4 v[88:91], v[64:65]
	s_nop 0
	flat_load_dwordx4 v[68:71], v[68:69] offset:512
	s_nop 0
	flat_load_dwordx4 v[72:75], v[64:65] offset:512
	v_ashrrev_i32_e32 v67, 31, v66
	v_lshlrev_b64 v[64:65], 2, v[66:67]
	v_lshl_add_u64 v[66:67], s[34:35], 0, v[64:65]
	v_lshl_add_u64 v[64:65], s[36:37], 0, v[64:65]
	global_load_dwordx4 v[80:83], v[224:225], off offset:16
	global_load_dwordx4 v[76:79], v[66:67], off
	s_nop 0
	global_load_dwordx4 v[64:67], v[64:65], off
	s_nop 0
	global_load_dwordx4 v[84:87], v[222:223], off offset:16
	v_xor_b32_e32 v118, 0x80000000, v220
	v_mov_b32_e32 v119, v118
	v_mov_b32_e32 v221, v220
	v_mov_b32_e32 v219, v218
	v_mov_b32_e32 v124, v218
	v_mov_b32_e32 v125, v218
	v_mov_b32_dpp v121, v121 row_ror:2 row_mask:0xf bank_mask:0xf
	v_mov_b32_e32 v122, v121
	v_mov_b32_e32 v123, v121
	v_mov_b32_e32 v120, v121
	s_waitcnt vmcnt(0) lgkmcnt(0)
	v_pk_fma_f32 v[62:63], v[118:119], v[94:95], v[62:63]
	v_pk_fma_f32 v[58:59], v[118:119], v[70:71], v[58:59]
	v_pk_fma_f32 v[60:61], v[220:221], v[92:93], v[60:61] neg_lo:[1,0,0] neg_hi:[1,0,0]
	v_pk_fma_f32 v[62:63], v[124:125], v[62:63], v[90:91]
	v_mov_b32_dpp v119, v119 row_ror:1 row_mask:0xf bank_mask:0xf
	v_pk_fma_f32 v[116:117], v[218:219], v[60:61], v[88:89]
	v_pk_fma_f32 v[126:127], v[220:221], v[68:69], v[56:57] neg_lo:[1,0,0] neg_hi:[1,0,0]
	v_mov_b32_e32 v56, v119
	v_mov_b32_e32 v57, v119
	v_mov_b32_e32 v118, v119
	v_mov_b32_dpp v56, v116 row_shr:1 row_mask:0xf bank_mask:0xf
	v_mov_b32_dpp v122, v116 row_shr:2 row_mask:0xf bank_mask:0xf
	v_mov_b32_dpp v57, v117 row_shr:1 row_mask:0xf bank_mask:0xf
	v_mov_b32_dpp v123, v117 row_shr:2 row_mask:0xf bank_mask:0xf
	v_mov_b32_dpp v118, v62 row_shr:1 row_mask:0xf bank_mask:0xf
	v_mov_b32_dpp v120, v62 row_shr:2 row_mask:0xf bank_mask:0xf
	v_mov_b32_dpp v119, v63 row_shr:1 row_mask:0xf bank_mask:0xf
	v_mov_b32_dpp v121, v63 row_shr:2 row_mask:0xf bank_mask:0xf
	v_pk_fma_f32 v[60:61], v[124:125], v[58:59], v[74:75]
	v_pk_fma_f32 v[58:59], v[218:219], v[126:127], v[72:73]
	s_and_saveexec_b64 s[0:1], s[2:3]
	s_xor_b64 s[0:1], exec, s[0:1]
	s_cbranch_execz .LBB0_687
	v_pk_mul_f32 v[122:123], v[80:81], v[122:123]
	v_pk_mul_f32 v[120:121], v[82:83], v[120:121]
	v_pk_fma_f32 v[56:57], v[76:77], v[56:57], v[122:123]
	v_pk_fma_f32 v[118:119], v[78:79], v[118:119], v[120:121]
	v_pk_fma_f32 v[56:57], v[116:117], v[64:65], v[56:57]
	v_pk_fma_f32 v[118:119], v[62:63], v[66:67], v[118:119]
	v_pk_add_f32 v[56:57], v[84:85], v[56:57]
	v_pk_add_f32 v[118:119], v[86:87], v[118:119]
	v_mul_f32_e32 v120, 0xbfb8aa3b, v56
	v_exp_f32_e32 v120, v120
	v_mul_f32_e32 v121, 0xbfb8aa3b, v57
	v_exp_f32_e32 v121, v121
	v_add_f32_e32 v120, 1.0, v120
	v_rcp_f32_e32 v120, v120
	v_add_f32_e32 v121, 1.0, v121
	v_rcp_f32_e32 v121, v121
	v_mul_f32_e32 v56, v56, v120
	v_mul_f32_e32 v56, v58, v56
	v_mul_f32_e32 v58, 0xbfb8aa3b, v118
	v_mul_f32_e32 v120, 0xbfb8aa3b, v119
	v_exp_f32_e32 v58, v58
	v_exp_f32_e32 v120, v120
	v_mul_f32_e32 v57, v57, v121
	v_mul_f32_e32 v57, v59, v57
	v_add_f32_e32 v58, 1.0, v58
	v_add_f32_e32 v59, 1.0, v120
	v_rcp_f32_e32 v58, v58
	v_rcp_f32_e32 v59, v59
	v_cvt_pk_bf16_f32 v56, v56, v57
	v_mul_f32_e32 v57, v118, v58
	v_mul_f32_e32 v58, v119, v59
	v_mul_f32_e32 v57, v60, v57
	v_mul_f32_e32 v58, v61, v58
	v_cvt_pk_bf16_f32 v57, v57, v58
	v_mov_b64_e32 v[58:59], s[66:67]
	v_mad_i64_i32 v[58:59], s[28:29], v216, s56, v[58:59]
	v_lshl_add_u64 v[58:59], v[200:201], 1, v[58:59]
	flat_store_dwordx2 v[58:59], v[56:57] offset:8

; DEVI unsigned pk2(float lo, float hi) { unsigned r; asm("v_cvt_pk_bf16_f32 %0, %1, %2" : "=v"(r) : "v"(lo), "v"(hi)); return r; }
; DEVI float siluf_(float x) { return x * sigmoidf_(x); }
; template <int CTRL> DEVI float dppf(float old, float src) { return __int_as_float(__builtin_amdgcn_update_dpp(__float_as_int(old), __float_as_int(src), CTRL, 0xf, 0xf, false)); }
;     DEVI void operator()(const f32x4 (&acc)[2][2][4][2], const pg8::Unit& u, int wr, int wc, int fr, int fq) const {
;     ...
;                     const int row = u.pm * 256 + ai * 128 + wr * 64 + m * 16 + fr;
;                     const f32x4 g = (acc[ai][0][m][n] - mu[ai][m] * sg) * rs[ai][m] + cg_;
;                     const f32x4 uu = (acc[ai][1][m][n] - mu[ai][m] * su) * rs[ai][m] + cu;
;                     f32x4 p1, p2;
; #pragma unroll
;                     for (int e = 0; e < 4; ++e) {
;                         p1[e] = dppf<0x111>(dppf<0x121>(0.f, gprev[e]), g[e]);
;                         p2[e] = dppf<0x112>(dppf<0x122>(0.f, gprev[e]), g[e]);
;                     }
;                     const int blk = row >> 6;
;                     if (m == 0 && fr < 2) {
;                         const f32x4 pg = (fr == 0) ? (w2 * g + cbv) : (w1 * p1 + w2 * g + cbv);
;                         *(f32x4*)(headpg + ((size_t)blk * 2 + fr) * DFF + j) = pg;
;                         *(f32x4*)(headup + ((size_t)blk * 2 + fr) * DFF + j) = uu;
;                     } else {
;                         const f32x4 cv = w0 * p2 + w1 * p1 + w2 * g + cbv;
;                         u32x2 o; o.x = pk2(siluf_(cv[0]) * uu[0], siluf_(cv[1]) * uu[1]); o.y = pk2(siluf_(cv[2]) * uu[2], siluf_(cv[3]) * uu[3]);
;                         *(u32x2*)(H + (size_t)row * DFF + j) = o;
.LBB0_689:
	s_or_b64 exec, exec, s[0:1]
	v_mov_b32_e32 v213, v212
	v_mov_b32_e32 v215, v214
	v_pk_fma_f32 v[52:53], v[212:213], v[92:93], v[52:53] neg_lo:[1,0,0] neg_hi:[1,0,0]
	v_xor_b32_e32 v56, 0x80000000, v212
	v_pk_fma_f32 v[52:53], v[214:215], v[52:53], v[88:89]
	v_mov_b32_dpp v118, v116 row_ror:2 row_mask:0xf bank_mask:0xf
	v_mov_b32_dpp v119, v117 row_ror:2 row_mask:0xf bank_mask:0xf
	v_mov_b32_e32 v57, v56
	v_mov_b32_dpp v60, v116 row_ror:1 row_mask:0xf bank_mask:0xf
	v_mov_b32_dpp v118, v52 row_shr:2 row_mask:0xf bank_mask:0xf
	v_mov_b32_dpp v61, v117 row_ror:1 row_mask:0xf bank_mask:0xf
	v_mov_b32_dpp v119, v53 row_shr:2 row_mask:0xf bank_mask:0xf
	v_pk_fma_f32 v[54:55], v[56:57], v[94:95], v[54:55]
	v_mov_b32_dpp v60, v52 row_shr:1 row_mask:0xf bank_mask:0xf
	v_mov_b32_dpp v61, v53 row_shr:1 row_mask:0xf bank_mask:0xf
	v_pk_fma_f32 v[50:51], v[56:57], v[70:71], v[50:51]
	v_pk_mul_f32 v[56:57], v[80:81], v[118:119]
	v_mov_b32_e32 v58, v214
	v_pk_fma_f32 v[56:57], v[76:77], v[60:61], v[56:57]
	v_mov_b32_e32 v59, v214
	v_pk_fma_f32 v[56:57], v[52:53], v[64:65], v[56:57]
	v_pk_add_f32 v[56:57], v[84:85], v[56:57]
	v_mul_f32_e32 v60, 0xbfb8aa3b, v56
	v_exp_f32_e32 v60, v60
	v_mul_f32_e32 v61, 0xbfb8aa3b, v57
	v_exp_f32_e32 v61, v61
	v_pk_fma_f32 v[54:55], v[58:59], v[54:55], v[90:91]
	v_mov_b32_dpp v120, v62 row_ror:2 row_mask:0xf bank_mask:0xf
	v_mov_b32_dpp v121, v63 row_ror:2 row_mask:0xf bank_mask:0xf
	v_add_f32_e32 v60, 1.0, v60
	v_mov_b32_dpp v116, v62 row_ror:1 row_mask:0xf bank_mask:0xf
	v_mov_b32_dpp v120, v54 row_shr:2 row_mask:0xf bank_mask:0xf
	v_mov_b32_dpp v117, v63 row_ror:1 row_mask:0xf bank_mask:0xf
	v_mov_b32_dpp v121, v55 row_shr:2 row_mask:0xf bank_mask:0xf
	v_rcp_f32_e32 v60, v60
	v_add_f32_e32 v61, 1.0, v61
	v_mov_b32_dpp v116, v54 row_shr:1 row_mask:0xf bank_mask:0xf
	v_mov_b32_dpp v117, v55 row_shr:1 row_mask:0xf bank_mask:0xf
	v_pk_fma_f32 v[50:51], v[58:59], v[50:51], v[74:75]
	v_pk_mul_f32 v[58:59], v[82:83], v[120:121]
	v_rcp_f32_e32 v61, v61
	v_pk_fma_f32 v[58:59], v[78:79], v[116:117], v[58:59]
	v_pk_fma_f32 v[48:49], v[212:213], v[68:69], v[48:49] neg_lo:[1,0,0] neg_hi:[1,0,0]
	v_pk_fma_f32 v[58:59], v[54:55], v[66:67], v[58:59]
	v_pk_fma_f32 v[48:49], v[214:215], v[48:49], v[72:73]
	v_pk_add_f32 v[58:59], v[86:87], v[58:59]
	v_mul_f32_e32 v56, v56, v60
	v_mul_f32_e32 v48, v48, v56
	v_mul_f32_e32 v56, v57, v61
	v_mul_f32_e32 v57, 0xbfb8aa3b, v58
	v_exp_f32_e32 v57, v57
	v_mul_f32_e32 v60, 0xbfb8aa3b, v59
	v_exp_f32_e32 v60, v60
	v_mul_f32_e32 v49, v49, v56
	v_add_f32_e32 v56, 1.0, v57
	v_rcp_f32_e32 v56, v56
	v_add_f32_e32 v57, 1.0, v60
	v_rcp_f32_e32 v57, v57
	v_mov_b32_e32 v209, v208
	v_cvt_pk_bf16_f32 v48, v48, v49
	v_mul_f32_e32 v49, v58, v56
	v_mov_b32_e32 v211, v210
	v_mul_f32_e32 v49, v50, v49
	v_mul_f32_e32 v50, v59, v57
	v_pk_fma_f32 v[44:45], v[208:209], v[92:93], v[44:45] neg_lo:[1,0,0] neg_hi:[1,0,0]
	v_mul_f32_e32 v50, v51, v50
	v_cvt_pk_bf16_f32 v49, v49, v50
	flat_store_dwordx2 v[112:113], v[48:49] offset:8
	v_xor_b32_e32 v48, 0x80000000, v208
	v_pk_fma_f32 v[44:45], v[210:211], v[44:45], v[88:89]
	v_mov_b32_dpp v58, v52 row_ror:2 row_mask:0xf bank_mask:0xf
	v_mov_b32_dpp v59, v53 row_ror:2 row_mask:0xf bank_mask:0xf
	v_mov_b32_e32 v49, v48
	v_mov_b32_dpp v56, v52 row_ror:1 row_mask:0xf bank_mask:0xf
	v_mov_b32_dpp v58, v44 row_shr:2 row_mask:0xf bank_mask:0xf
	v_mov_b32_dpp v57, v53 row_ror:1 row_mask:0xf bank_mask:0xf
	v_mov_b32_dpp v59, v45 row_shr:2 row_mask:0xf bank_mask:0xf
	v_pk_fma_f32 v[46:47], v[48:49], v[94:95], v[46:47]
	v_mov_b32_e32 v50, v210
	v_mov_b32_e32 v51, v210
	v_mov_b32_dpp v56, v44 row_shr:1 row_mask:0xf bank_mask:0xf
	v_mov_b32_dpp v57, v45 row_shr:1 row_mask:0xf bank_mask:0xf
	v_pk_fma_f32 v[42:43], v[48:49], v[70:71], v[42:43]
	v_pk_mul_f32 v[48:49], v[80:81], v[58:59]
	v_pk_fma_f32 v[46:47], v[50:51], v[46:47], v[90:91]
	v_mov_b32_dpp v60, v54 row_ror:2 row_mask:0xf bank_mask:0xf
	v_mov_b32_dpp v61, v55 row_ror:2 row_mask:0xf bank_mask:0xf
	v_pk_fma_f32 v[48:49], v[76:77], v[56:57], v[48:49]
	v_mov_b32_dpp v52, v54 row_ror:1 row_mask:0xf bank_mask:0xf
	v_mov_b32_dpp v60, v46 row_shr:2 row_mask:0xf bank_mask:0xf
	v_mov_b32_dpp v53, v55 row_ror:1 row_mask:0xf bank_mask:0xf
	v_mov_b32_dpp v61, v47 row_shr:2 row_mask:0xf bank_mask:0xf
	v_pk_fma_f32 v[48:49], v[44:45], v[64:65], v[48:49]
	v_mov_b32_dpp v52, v46 row_shr:1 row_mask:0xf bank_mask:0xf
	v_mov_b32_dpp v53, v47 row_shr:1 row_mask:0xf bank_mask:0xf
	v_pk_fma_f32 v[42:43], v[50:51], v[42:43], v[74:75]
	v_pk_mul_f32 v[50:51], v[82:83], v[60:61]
	v_pk_add_f32 v[48:49], v[84:85], v[48:49]
	v_pk_fma_f32 v[50:51], v[78:79], v[52:53], v[50:51]
	v_mul_f32_e32 v52, 0xbfb8aa3b, v48
	v_exp_f32_e32 v52, v52
	v_mul_f32_e32 v53, 0xbfb8aa3b, v49
	v_exp_f32_e32 v53, v53
	v_pk_fma_f32 v[40:41], v[208:209], v[68:69], v[40:41] neg_lo:[1,0,0] neg_hi:[1,0,0]
	v_add_f32_e32 v52, 1.0, v52
	v_rcp_f32_e32 v52, v52
	v_add_f32_e32 v53, 1.0, v53
	v_rcp_f32_e32 v53, v53
	v_pk_fma_f32 v[50:51], v[46:47], v[66:67], v[50:51]
	v_pk_fma_f32 v[40:41], v[210:211], v[40:41], v[72:73]
	v_pk_add_f32 v[50:51], v[86:87], v[50:51]
	v_mul_f32_e32 v48, v48, v52
	v_mul_f32_e32 v40, v40, v48
	v_mul_f32_e32 v48, v49, v53
	v_mul_f32_e32 v49, 0xbfb8aa3b, v50
	v_exp_f32_e32 v49, v49
	v_mul_f32_e32 v52, 0xbfb8aa3b, v51
	v_exp_f32_e32 v52, v52
	v_mul_f32_e32 v41, v41, v48
	v_add_f32_e32 v48, 1.0, v49
	v_rcp_f32_e32 v48, v48
	v_add_f32_e32 v49, 1.0, v52
	v_rcp_f32_e32 v49, v49
	v_mov_b32_e32 v203, v202
	v_cvt_pk_bf16_f32 v40, v40, v41
	v_mul_f32_e32 v41, v50, v48
	v_mov_b32_e32 v205, v204
	v_mul_f32_e32 v41, v42, v41
	v_mul_f32_e32 v42, v51, v49
; DEVI unsigned pk2(float lo, float hi) { unsigned r; asm("v_cvt_pk_bf16_f32 %0, %1, %2" : "=v"(r) : "v"(lo), "v"(hi)); return r; }
; DEVI float siluf_(float x) { return x * sigmoidf_(x); }
; template <int CTRL> DEVI float dppf(float old, float src) { return __int_as_float(__builtin_amdgcn_update_dpp(__float_as_int(old), __float_as_int(src), CTRL, 0xf, 0xf, false)); }
;     DEVI void operator()(const f32x4 (&acc)[2][2][4][2], const pg8::Unit& u, int wr, int wc, int fr, int fq) const {
;     ...
;                     const int row = u.pm * 256 + ai * 128 + wr * 64 + m * 16 + fr;
;                     const f32x4 g = (acc[ai][0][m][n] - mu[ai][m] * sg) * rs[ai][m] + cg_;
;                     const f32x4 uu = (acc[ai][1][m][n] - mu[ai][m] * su) * rs[ai][m] + cu;
;                     f32x4 p1, p2;
; #pragma unroll
;                     for (int e = 0; e < 4; ++e) {
;                         p1[e] = dppf<0x111>(dppf<0x121>(0.f, gprev[e]), g[e]);
;                         p2[e] = dppf<0x112>(dppf<0x122>(0.f, gprev[e]), g[e]);
;                     }
;                     const int blk = row >> 6;
;                     if (m == 0 && fr < 2) {
;                         const f32x4 pg = (fr == 0) ? (w2 * g + cbv) : (w1 * p1 + w2 * g + cbv);
;                         *(f32x4*)(headpg + ((size_t)blk * 2 + fr) * DFF + j) = pg;
;                         *(f32x4*)(headup + ((size_t)blk * 2 + fr) * DFF + j) = uu;
;                     } else {
;                         const f32x4 cv = w0 * p2 + w1 * p1 + w2 * g + cbv;
;                         u32x2 o; o.x = pk2(siluf_(cv[0]) * uu[0], siluf_(cv[1]) * uu[1]); o.y = pk2(siluf_(cv[2]) * uu[2], siluf_(cv[3]) * uu[3]);
;                         *(u32x2*)(H + (size_t)row * DFF + j) = o;
;                     }
;                     if (m == 3 && fr >= 14) *(f32x4*)(tailg + ((size_t)blk * 2 + (fr - 14)) * DFF + j) = g;
	v_pk_fma_f32 v[36:37], v[202:203], v[92:93], v[36:37] neg_lo:[1,0,0] neg_hi:[1,0,0]
	v_mul_f32_e32 v42, v43, v42
	v_cvt_pk_bf16_f32 v41, v41, v42
	flat_store_dwordx2 v[108:109], v[40:41] offset:8
	v_xor_b32_e32 v40, 0x80000000, v202
	v_pk_fma_f32 v[36:37], v[204:205], v[36:37], v[88:89]
	v_mov_b32_dpp v50, v44 row_ror:2 row_mask:0xf bank_mask:0xf
	v_mov_b32_dpp v51, v45 row_ror:2 row_mask:0xf bank_mask:0xf
	v_mov_b32_e32 v41, v40
	v_mov_b32_dpp v48, v44 row_ror:1 row_mask:0xf bank_mask:0xf
	v_mov_b32_dpp v50, v36 row_shr:2 row_mask:0xf bank_mask:0xf
	v_mov_b32_dpp v49, v45 row_ror:1 row_mask:0xf bank_mask:0xf
	v_mov_b32_dpp v51, v37 row_shr:2 row_mask:0xf bank_mask:0xf
	v_pk_fma_f32 v[38:39], v[40:41], v[94:95], v[38:39]
	v_mov_b32_e32 v42, v204
	v_mov_b32_e32 v43, v204
	v_mov_b32_dpp v48, v36 row_shr:1 row_mask:0xf bank_mask:0xf
	v_mov_b32_dpp v49, v37 row_shr:1 row_mask:0xf bank_mask:0xf
	v_pk_fma_f32 v[34:35], v[40:41], v[70:71], v[34:35]
	v_pk_mul_f32 v[40:41], v[80:81], v[50:51]
	v_pk_fma_f32 v[38:39], v[42:43], v[38:39], v[90:91]
	v_mov_b32_dpp v52, v46 row_ror:2 row_mask:0xf bank_mask:0xf
	v_mov_b32_dpp v53, v47 row_ror:2 row_mask:0xf bank_mask:0xf
	v_pk_fma_f32 v[40:41], v[76:77], v[48:49], v[40:41]
	v_mov_b32_dpp v44, v46 row_ror:1 row_mask:0xf bank_mask:0xf
	v_mov_b32_dpp v52, v38 row_shr:2 row_mask:0xf bank_mask:0xf
	v_mov_b32_dpp v45, v47 row_ror:1 row_mask:0xf bank_mask:0xf
	v_mov_b32_dpp v53, v39 row_shr:2 row_mask:0xf bank_mask:0xf
	v_pk_fma_f32 v[40:41], v[36:37], v[64:65], v[40:41]
	v_mov_b32_dpp v44, v38 row_shr:1 row_mask:0xf bank_mask:0xf
	v_mov_b32_dpp v45, v39 row_shr:1 row_mask:0xf bank_mask:0xf
	v_pk_fma_f32 v[34:35], v[42:43], v[34:35], v[74:75]
	v_pk_mul_f32 v[42:43], v[82:83], v[52:53]
	v_pk_add_f32 v[40:41], v[84:85], v[40:41]
	v_pk_fma_f32 v[42:43], v[78:79], v[44:45], v[42:43]
	v_mul_f32_e32 v44, 0xbfb8aa3b, v40
	v_exp_f32_e32 v44, v44
	v_mul_f32_e32 v45, 0xbfb8aa3b, v41
	v_exp_f32_e32 v45, v45
	v_pk_fma_f32 v[32:33], v[202:203], v[68:69], v[32:33] neg_lo:[1,0,0] neg_hi:[1,0,0]
	v_add_f32_e32 v44, 1.0, v44
	v_rcp_f32_e32 v44, v44
	v_add_f32_e32 v45, 1.0, v45
	v_rcp_f32_e32 v45, v45
	v_pk_fma_f32 v[42:43], v[38:39], v[66:67], v[42:43]
	v_pk_fma_f32 v[32:33], v[204:205], v[32:33], v[72:73]
	v_pk_add_f32 v[42:43], v[86:87], v[42:43]
	v_mul_f32_e32 v40, v40, v44
	v_mul_f32_e32 v32, v32, v40
	v_mul_f32_e32 v40, v41, v45
	v_mul_f32_e32 v41, 0xbfb8aa3b, v42
	v_exp_f32_e32 v41, v41
	v_mul_f32_e32 v44, 0xbfb8aa3b, v43
	v_exp_f32_e32 v44, v44
	v_mul_f32_e32 v33, v33, v40
	v_add_f32_e32 v40, 1.0, v41
	v_rcp_f32_e32 v40, v40
	v_add_f32_e32 v41, 1.0, v44
	v_rcp_f32_e32 v41, v41
	v_cvt_pk_bf16_f32 v32, v32, v33
	v_mul_f32_e32 v33, v42, v40
	v_mul_f32_e32 v33, v34, v33
	v_mul_f32_e32 v34, v43, v41
	v_mul_f32_e32 v34, v35, v34
	v_cvt_pk_bf16_f32 v33, v33, v34
	flat_store_dwordx2 v[106:107], v[32:33] offset:8
	s_and_saveexec_b64 s[0:1], s[6:7]
	s_cbranch_execz .LBB0_691
	flat_store_dwordx4 v[98:99], v[36:39] offset:16
.LBB0_691:
	s_or_b64 exec, exec, s[0:1]
	s_nop 0
	v_xor_b32_e32 v36, 0x80000000, v198
	v_mov_b32_e32 v37, v36
	v_mov_b32_e32 v199, v198
	v_pk_fma_f32 v[30:31], v[36:37], v[94:95], v[30:31]
	v_pk_fma_f32 v[26:27], v[36:37], v[70:71], v[26:27]
	v_mov_b32_e32 v197, v196
	v_pk_fma_f32 v[28:29], v[198:199], v[92:93], v[28:29] neg_lo:[1,0,0] neg_hi:[1,0,0]
	v_mov_b32_e32 v40, v196
	v_mov_b32_e32 v41, v196
	v_mov_b32_dpp v37, v37 row_ror:1 row_mask:0xf bank_mask:0xf
	v_mov_b32_dpp v39, v39 row_ror:2 row_mask:0xf bank_mask:0xf
	v_pk_fma_f32 v[34:35], v[196:197], v[28:29], v[88:89]
	v_pk_fma_f32 v[32:33], v[40:41], v[30:31], v[90:91]
	v_pk_fma_f32 v[24:25], v[198:199], v[68:69], v[24:25] neg_lo:[1,0,0] neg_hi:[1,0,0]
	v_mov_b32_e32 v28, v37
	v_mov_b32_e32 v30, v39
	v_mov_b32_e32 v29, v37
	v_mov_b32_e32 v31, v39
	v_mov_b32_e32 v36, v37
	v_mov_b32_e32 v38, v39
	v_mov_b32_dpp v28, v34 row_shr:1 row_mask:0xf bank_mask:0xf
	v_mov_b32_dpp v30, v34 row_shr:2 row_mask:0xf bank_mask:0xf
	v_mov_b32_dpp v29, v35 row_shr:1 row_mask:0xf bank_mask:0xf
	v_mov_b32_dpp v31, v35 row_shr:2 row_mask:0xf bank_mask:0xf
	v_mov_b32_dpp v36, v32 row_shr:1 row_mask:0xf bank_mask:0xf
	v_mov_b32_dpp v38, v32 row_shr:2 row_mask:0xf bank_mask:0xf
	v_mov_b32_dpp v37, v33 row_shr:1 row_mask:0xf bank_mask:0xf
	v_mov_b32_dpp v39, v33 row_shr:2 row_mask:0xf bank_mask:0xf
	v_pk_fma_f32 v[24:25], v[196:197], v[24:25], v[72:73]
	v_pk_fma_f32 v[26:27], v[40:41], v[26:27], v[74:75]
	s_and_saveexec_b64 s[0:1], s[2:3]
	s_xor_b64 s[0:1], exec, s[0:1]
	s_cbranch_execz .LBB0_693
	v_pk_mul_f32 v[30:31], v[80:81], v[30:31]
	v_pk_mul_f32 v[38:39], v[82:83], v[38:39]
	v_pk_fma_f32 v[28:29], v[76:77], v[28:29], v[30:31]
	v_pk_fma_f32 v[36:37], v[78:79], v[36:37], v[38:39]
	v_pk_fma_f32 v[28:29], v[34:35], v[64:65], v[28:29]
	s_nop 0
	v_pk_add_f32 v[28:29], v[84:85], v[28:29]
	s_nop 0
	v_mul_f32_e32 v30, 0xbfb8aa3b, v28
	v_exp_f32_e32 v38, v30
	v_mul_f32_e32 v30, 0xbfb8aa3b, v29
	v_exp_f32_e32 v39, v30
	v_pk_fma_f32 v[30:31], v[32:33], v[66:67], v[36:37]
	v_add_f32_e32 v36, 1.0, v38
	v_rcp_f32_e32 v36, v36
	v_add_f32_e32 v37, 1.0, v39
	v_rcp_f32_e32 v37, v37
	v_pk_add_f32 v[30:31], v[86:87], v[30:31]
	v_mul_f32_e32 v28, v28, v36
	v_mul_f32_e32 v24, v24, v28
	v_mul_f32_e32 v28, v29, v37
	v_mul_f32_e32 v29, 0xbfb8aa3b, v30
	v_exp_f32_e32 v29, v29
	v_mul_f32_e32 v36, 0xbfb8aa3b, v31
	v_exp_f32_e32 v36, v36
	v_mul_f32_e32 v25, v25, v28
	v_add_f32_e32 v28, 1.0, v29
	v_rcp_f32_e32 v28, v28
	v_add_f32_e32 v29, 1.0, v36
	v_rcp_f32_e32 v29, v29
	v_cvt_pk_bf16_f32 v24, v24, v25
	v_mul_f32_e32 v25, v30, v28
	v_mul_f32_e32 v25, v26, v25
	v_mul_f32_e32 v26, v31, v29
	v_mul_f32_e32 v26, v27, v26
	v_cvt_pk_bf16_f32 v25, v25, v26
	v_mov_b64_e32 v[26:27], s[66:67]
	v_mad_i64_i32 v[26:27], s[28:29], v160, s56, v[26:27]
	v_lshl_add_u64 v[26:27], v[200:201], 1, v[26:27]
	flat_store_dwordx2 v[26:27], v[24:25] offset:8

; DEVI unsigned pk2(float lo, float hi) { unsigned r; asm("v_cvt_pk_bf16_f32 %0, %1, %2" : "=v"(r) : "v"(lo), "v"(hi)); return r; }
; DEVI float siluf_(float x) { return x * sigmoidf_(x); }
; template <int CTRL> DEVI float dppf(float old, float src) { return __int_as_float(__builtin_amdgcn_update_dpp(__float_as_int(old), __float_as_int(src), CTRL, 0xf, 0xf, false)); }
;     DEVI void operator()(const f32x4 (&acc)[2][2][4][2], const pg8::Unit& u, int wr, int wc, int fr, int fq) const {
;     ...
;                     const int row = u.pm * 256 + ai * 128 + wr * 64 + m * 16 + fr;
;                     const f32x4 g = (acc[ai][0][m][n] - mu[ai][m] * sg) * rs[ai][m] + cg_;
;                     const f32x4 uu = (acc[ai][1][m][n] - mu[ai][m] * su) * rs[ai][m] + cu;
;                     f32x4 p1, p2;
; #pragma unroll
;                     for (int e = 0; e < 4; ++e) {
;                         p1[e] = dppf<0x111>(dppf<0x121>(0.f, gprev[e]), g[e]);
;                         p2[e] = dppf<0x112>(dppf<0x122>(0.f, gprev[e]), g[e]);
;                     }
;                     const int blk = row >> 6;
;                     if (m == 0 && fr < 2) {
;                         const f32x4 pg = (fr == 0) ? (w2 * g + cbv) : (w1 * p1 + w2 * g + cbv);
;                         *(f32x4*)(headpg + ((size_t)blk * 2 + fr) * DFF + j) = pg;
;                         *(f32x4*)(headup + ((size_t)blk * 2 + fr) * DFF + j) = uu;
;                     } else {
;                         const f32x4 cv = w0 * p2 + w1 * p1 + w2 * g + cbv;
;                         u32x2 o; o.x = pk2(siluf_(cv[0]) * uu[0], siluf_(cv[1]) * uu[1]); o.y = pk2(siluf_(cv[2]) * uu[2], siluf_(cv[3]) * uu[3]);
;                         *(u32x2*)(H + (size_t)row * DFF + j) = o;
.LBB0_695:
	s_or_b64 exec, exec, s[0:1]
	v_mov_b32_e32 v193, v192
	v_mov_b32_e32 v195, v194
	v_pk_fma_f32 v[20:21], v[192:193], v[92:93], v[20:21] neg_lo:[1,0,0] neg_hi:[1,0,0]
	v_xor_b32_e32 v24, 0x80000000, v192
	v_pk_fma_f32 v[20:21], v[194:195], v[20:21], v[88:89]
	v_mov_b32_dpp v30, v34 row_ror:2 row_mask:0xf bank_mask:0xf
	v_mov_b32_dpp v31, v35 row_ror:2 row_mask:0xf bank_mask:0xf
	v_mov_b32_e32 v25, v24
	v_mov_b32_dpp v28, v34 row_ror:1 row_mask:0xf bank_mask:0xf
	v_mov_b32_dpp v30, v20 row_shr:2 row_mask:0xf bank_mask:0xf
	v_mov_b32_dpp v29, v35 row_ror:1 row_mask:0xf bank_mask:0xf
	v_mov_b32_dpp v31, v21 row_shr:2 row_mask:0xf bank_mask:0xf
	v_pk_fma_f32 v[22:23], v[24:25], v[94:95], v[22:23]
	v_mov_b32_dpp v28, v20 row_shr:1 row_mask:0xf bank_mask:0xf
	v_mov_b32_dpp v29, v21 row_shr:1 row_mask:0xf bank_mask:0xf
	v_pk_fma_f32 v[18:19], v[24:25], v[70:71], v[18:19]
	v_pk_mul_f32 v[24:25], v[80:81], v[30:31]
	v_mov_b32_e32 v26, v194
	v_pk_fma_f32 v[24:25], v[76:77], v[28:29], v[24:25]
	v_mov_b32_e32 v27, v194
	v_pk_fma_f32 v[24:25], v[20:21], v[64:65], v[24:25]
	v_pk_add_f32 v[24:25], v[84:85], v[24:25]
	v_mul_f32_e32 v28, 0xbfb8aa3b, v24
	v_exp_f32_e32 v28, v28
	v_mul_f32_e32 v29, 0xbfb8aa3b, v25
	v_exp_f32_e32 v29, v29
	v_pk_fma_f32 v[22:23], v[26:27], v[22:23], v[90:91]
	v_mov_b32_dpp v36, v32 row_ror:2 row_mask:0xf bank_mask:0xf
	v_mov_b32_dpp v37, v33 row_ror:2 row_mask:0xf bank_mask:0xf
	v_add_f32_e32 v28, 1.0, v28
	v_mov_b32_dpp v34, v32 row_ror:1 row_mask:0xf bank_mask:0xf
	v_mov_b32_dpp v36, v22 row_shr:2 row_mask:0xf bank_mask:0xf
	v_mov_b32_dpp v35, v33 row_ror:1 row_mask:0xf bank_mask:0xf
	v_mov_b32_dpp v37, v23 row_shr:2 row_mask:0xf bank_mask:0xf
	v_rcp_f32_e32 v28, v28
	v_add_f32_e32 v29, 1.0, v29
	v_mov_b32_dpp v34, v22 row_shr:1 row_mask:0xf bank_mask:0xf
	v_mov_b32_dpp v35, v23 row_shr:1 row_mask:0xf bank_mask:0xf
	v_pk_fma_f32 v[18:19], v[26:27], v[18:19], v[74:75]
	v_pk_mul_f32 v[26:27], v[82:83], v[36:37]
	v_rcp_f32_e32 v29, v29
	v_pk_fma_f32 v[26:27], v[78:79], v[34:35], v[26:27]
	v_pk_fma_f32 v[16:17], v[192:193], v[68:69], v[16:17] neg_lo:[1,0,0] neg_hi:[1,0,0]
	v_pk_fma_f32 v[26:27], v[22:23], v[66:67], v[26:27]
	v_pk_fma_f32 v[16:17], v[194:195], v[16:17], v[72:73]
	v_pk_add_f32 v[26:27], v[86:87], v[26:27]
	v_mul_f32_e32 v24, v24, v28
	v_mul_f32_e32 v16, v16, v24
	v_mul_f32_e32 v24, v25, v29
	v_mul_f32_e32 v25, 0xbfb8aa3b, v26
	v_exp_f32_e32 v25, v25
	v_mul_f32_e32 v28, 0xbfb8aa3b, v27
	v_exp_f32_e32 v28, v28
	v_mul_f32_e32 v17, v17, v24
	v_add_f32_e32 v24, 1.0, v25
	v_rcp_f32_e32 v24, v24
	v_add_f32_e32 v25, 1.0, v28
	v_rcp_f32_e32 v25, v25
	v_mov_b32_e32 v189, v188
	v_cvt_pk_bf16_f32 v16, v16, v17
	v_mul_f32_e32 v17, v26, v24
	v_mov_b32_e32 v191, v190
	v_mul_f32_e32 v17, v18, v17
	v_mul_f32_e32 v18, v27, v25
	v_pk_fma_f32 v[12:13], v[188:189], v[92:93], v[12:13] neg_lo:[1,0,0] neg_hi:[1,0,0]
	v_mul_f32_e32 v18, v19, v18
	v_cvt_pk_bf16_f32 v17, v17, v18
	flat_store_dwordx2 v[100:101], v[16:17] offset:8
	v_xor_b32_e32 v16, 0x80000000, v188
	v_pk_fma_f32 v[12:13], v[190:191], v[12:13], v[88:89]
	v_mov_b32_dpp v26, v20 row_ror:2 row_mask:0xf bank_mask:0xf
	v_mov_b32_dpp v27, v21 row_ror:2 row_mask:0xf bank_mask:0xf
	v_mov_b32_e32 v17, v16
	v_mov_b32_dpp v24, v20 row_ror:1 row_mask:0xf bank_mask:0xf
	v_mov_b32_dpp v26, v12 row_shr:2 row_mask:0xf bank_mask:0xf
	v_mov_b32_dpp v25, v21 row_ror:1 row_mask:0xf bank_mask:0xf
	v_mov_b32_dpp v27, v13 row_shr:2 row_mask:0xf bank_mask:0xf
	v_pk_fma_f32 v[14:15], v[16:17], v[94:95], v[14:15]
	v_mov_b32_e32 v18, v190
	v_mov_b32_e32 v19, v190
	v_mov_b32_dpp v24, v12 row_shr:1 row_mask:0xf bank_mask:0xf
	v_mov_b32_dpp v25, v13 row_shr:1 row_mask:0xf bank_mask:0xf
	v_pk_fma_f32 v[10:11], v[16:17], v[70:71], v[10:11]
	v_pk_mul_f32 v[16:17], v[80:81], v[26:27]
	v_pk_fma_f32 v[14:15], v[18:19], v[14:15], v[90:91]
	v_mov_b32_dpp v28, v22 row_ror:2 row_mask:0xf bank_mask:0xf
	v_mov_b32_dpp v29, v23 row_ror:2 row_mask:0xf bank_mask:0xf
	v_pk_fma_f32 v[16:17], v[76:77], v[24:25], v[16:17]
	v_mov_b32_dpp v20, v22 row_ror:1 row_mask:0xf bank_mask:0xf
	v_mov_b32_dpp v28, v14 row_shr:2 row_mask:0xf bank_mask:0xf
	v_mov_b32_dpp v21, v23 row_ror:1 row_mask:0xf bank_mask:0xf
; DEVI unsigned pk2(float lo, float hi) { unsigned r; asm("v_cvt_pk_bf16_f32 %0, %1, %2" : "=v"(r) : "v"(lo), "v"(hi)); return r; }
; DEVI float siluf_(float x) { return x * sigmoidf_(x); }
; template <int CTRL> DEVI float dppf(float old, float src) { return __int_as_float(__builtin_amdgcn_update_dpp(__float_as_int(old), __float_as_int(src), CTRL, 0xf, 0xf, false)); }
;     DEVI void operator()(const f32x4 (&acc)[2][2][4][2], const pg8::Unit& u, int wr, int wc, int fr, int fq) const {
;     ...
;                     const int row = u.pm * 256 + ai * 128 + wr * 64 + m * 16 + fr;
;                     const f32x4 g = (acc[ai][0][m][n] - mu[ai][m] * sg) * rs[ai][m] + cg_;
;                     const f32x4 uu = (acc[ai][1][m][n] - mu[ai][m] * su) * rs[ai][m] + cu;
;                     f32x4 p1, p2;
; #pragma unroll
;                     for (int e = 0; e < 4; ++e) {
;                         p1[e] = dppf<0x111>(dppf<0x121>(0.f, gprev[e]), g[e]);
;                         p2[e] = dppf<0x112>(dppf<0x122>(0.f, gprev[e]), g[e]);
;                     }
;                     const int blk = row >> 6;
;                     if (m == 0 && fr < 2) {
;                         const f32x4 pg = (fr == 0) ? (w2 * g + cbv) : (w1 * p1 + w2 * g + cbv);
;                         *(f32x4*)(headpg + ((size_t)blk * 2 + fr) * DFF + j) = pg;
;                         *(f32x4*)(headup + ((size_t)blk * 2 + fr) * DFF + j) = uu;
;                     } else {
;                         const f32x4 cv = w0 * p2 + w1 * p1 + w2 * g + cbv;
;                         u32x2 o; o.x = pk2(siluf_(cv[0]) * uu[0], siluf_(cv[1]) * uu[1]); o.y = pk2(siluf_(cv[2]) * uu[2], siluf_(cv[3]) * uu[3]);
;                         *(u32x2*)(H + (size_t)row * DFF + j) = o;
;                     }
;                     if (m == 3 && fr >= 14) *(f32x4*)(tailg + ((size_t)blk * 2 + (fr - 14)) * DFF + j) = g;
	v_mov_b32_dpp v29, v15 row_shr:2 row_mask:0xf bank_mask:0xf
	v_pk_fma_f32 v[16:17], v[12:13], v[64:65], v[16:17]
	v_mov_b32_dpp v20, v14 row_shr:1 row_mask:0xf bank_mask:0xf
	v_mov_b32_dpp v21, v15 row_shr:1 row_mask:0xf bank_mask:0xf
	v_pk_fma_f32 v[10:11], v[18:19], v[10:11], v[74:75]
	v_pk_mul_f32 v[18:19], v[82:83], v[28:29]
	v_pk_add_f32 v[16:17], v[84:85], v[16:17]
	v_pk_fma_f32 v[18:19], v[78:79], v[20:21], v[18:19]
	v_mul_f32_e32 v20, 0xbfb8aa3b, v16
	v_exp_f32_e32 v20, v20
	v_mul_f32_e32 v21, 0xbfb8aa3b, v17
	v_exp_f32_e32 v21, v21
	v_pk_fma_f32 v[8:9], v[188:189], v[68:69], v[8:9] neg_lo:[1,0,0] neg_hi:[1,0,0]
	v_add_f32_e32 v20, 1.0, v20
	v_rcp_f32_e32 v20, v20
	v_add_f32_e32 v21, 1.0, v21
	v_rcp_f32_e32 v21, v21
	v_pk_fma_f32 v[18:19], v[14:15], v[66:67], v[18:19]
	v_pk_fma_f32 v[8:9], v[190:191], v[8:9], v[72:73]
	v_pk_add_f32 v[18:19], v[86:87], v[18:19]
	v_mul_f32_e32 v16, v16, v20
	v_mul_f32_e32 v8, v8, v16
	v_mul_f32_e32 v16, v17, v21
	v_mul_f32_e32 v17, 0xbfb8aa3b, v18
	v_exp_f32_e32 v17, v17
	v_mul_f32_e32 v20, 0xbfb8aa3b, v19
	v_exp_f32_e32 v20, v20
	v_mul_f32_e32 v9, v9, v16
	v_add_f32_e32 v16, 1.0, v17
	v_rcp_f32_e32 v16, v16
	v_add_f32_e32 v17, 1.0, v20
	v_rcp_f32_e32 v17, v17
	v_mov_b32_e32 v185, v184
	v_cvt_pk_bf16_f32 v8, v8, v9
	v_mul_f32_e32 v9, v18, v16
	v_mov_b32_e32 v187, v186
	v_mul_f32_e32 v9, v10, v9
	v_mul_f32_e32 v10, v19, v17
	v_pk_fma_f32 v[4:5], v[184:185], v[92:93], v[4:5] neg_lo:[1,0,0] neg_hi:[1,0,0]
	v_mul_f32_e32 v10, v11, v10
	v_cvt_pk_bf16_f32 v9, v9, v10
	flat_store_dwordx2 v[102:103], v[8:9] offset:8
	v_xor_b32_e32 v8, 0x80000000, v184
	v_pk_fma_f32 v[4:5], v[186:187], v[4:5], v[88:89]
	v_mov_b32_dpp v18, v12 row_ror:2 row_mask:0xf bank_mask:0xf
	v_mov_b32_dpp v19, v13 row_ror:2 row_mask:0xf bank_mask:0xf
	v_mov_b32_e32 v9, v8
	v_mov_b32_dpp v16, v12 row_ror:1 row_mask:0xf bank_mask:0xf
	v_mov_b32_dpp v18, v4 row_shr:2 row_mask:0xf bank_mask:0xf
	v_mov_b32_dpp v17, v13 row_ror:1 row_mask:0xf bank_mask:0xf
	v_mov_b32_dpp v19, v5 row_shr:2 row_mask:0xf bank_mask:0xf
	v_pk_fma_f32 v[6:7], v[8:9], v[94:95], v[6:7]
	v_mov_b32_e32 v10, v186
	v_mov_b32_e32 v11, v186
	v_mov_b32_dpp v16, v4 row_shr:1 row_mask:0xf bank_mask:0xf
	v_mov_b32_dpp v17, v5 row_shr:1 row_mask:0xf bank_mask:0xf
	v_pk_fma_f32 v[2:3], v[8:9], v[70:71], v[2:3]
	v_pk_mul_f32 v[8:9], v[80:81], v[18:19]
	v_pk_fma_f32 v[6:7], v[10:11], v[6:7], v[90:91]
	v_mov_b32_dpp v20, v14 row_ror:2 row_mask:0xf bank_mask:0xf
	v_mov_b32_dpp v21, v15 row_ror:2 row_mask:0xf bank_mask:0xf
	v_pk_fma_f32 v[8:9], v[76:77], v[16:17], v[8:9]
	v_mov_b32_dpp v12, v14 row_ror:1 row_mask:0xf bank_mask:0xf
	v_mov_b32_dpp v20, v6 row_shr:2 row_mask:0xf bank_mask:0xf
	v_mov_b32_dpp v13, v15 row_ror:1 row_mask:0xf bank_mask:0xf
	v_mov_b32_dpp v21, v7 row_shr:2 row_mask:0xf bank_mask:0xf
	v_pk_fma_f32 v[8:9], v[4:5], v[64:65], v[8:9]
	v_mov_b32_dpp v12, v6 row_shr:1 row_mask:0xf bank_mask:0xf
	v_mov_b32_dpp v13, v7 row_shr:1 row_mask:0xf bank_mask:0xf
	v_pk_fma_f32 v[2:3], v[10:11], v[2:3], v[74:75]
	v_pk_mul_f32 v[10:11], v[82:83], v[20:21]
	v_pk_add_f32 v[8:9], v[84:85], v[8:9]
	v_pk_fma_f32 v[10:11], v[78:79], v[12:13], v[10:11]
	v_mul_f32_e32 v12, 0xbfb8aa3b, v8
	v_exp_f32_e32 v12, v12
	v_mul_f32_e32 v13, 0xbfb8aa3b, v9
	v_exp_f32_e32 v13, v13
	v_pk_fma_f32 v[0:1], v[184:185], v[68:69], v[0:1] neg_lo:[1,0,0] neg_hi:[1,0,0]
	v_add_f32_e32 v12, 1.0, v12
	v_rcp_f32_e32 v12, v12
	v_add_f32_e32 v13, 1.0, v13
	v_rcp_f32_e32 v13, v13
	v_pk_fma_f32 v[10:11], v[6:7], v[66:67], v[10:11]
	v_pk_fma_f32 v[0:1], v[186:187], v[0:1], v[72:73]
	v_pk_add_f32 v[10:11], v[86:87], v[10:11]
	v_mul_f32_e32 v8, v8, v12
	v_mul_f32_e32 v0, v0, v8
	v_mul_f32_e32 v8, v9, v13
	v_mul_f32_e32 v9, 0xbfb8aa3b, v10
	v_exp_f32_e32 v9, v9
	v_mul_f32_e32 v12, 0xbfb8aa3b, v11
	v_exp_f32_e32 v12, v12
	v_mul_f32_e32 v1, v1, v8
	v_add_f32_e32 v8, 1.0, v9
	v_rcp_f32_e32 v8, v8
	v_add_f32_e32 v9, 1.0, v12
	v_rcp_f32_e32 v9, v9
	v_cvt_pk_bf16_f32 v0, v0, v1
	v_mul_f32_e32 v1, v10, v8
	v_mul_f32_e32 v1, v2, v1
	v_mul_f32_e32 v2, v11, v9
	v_mul_f32_e32 v2, v3, v2
	v_cvt_pk_bf16_f32 v1, v1, v2
	flat_store_dwordx2 v[104:105], v[0:1] offset:8
	s_and_saveexec_b64 s[0:1], s[6:7]
	s_cbranch_execz .LBB0_697
	flat_store_dwordx4 v[96:97], v[4:7] offset:16

; template <int CTRL> DEVI float dppf(float old, float src) { return __int_as_float(__builtin_amdgcn_update_dpp(__float_as_int(old), __float_as_int(src), CTRL, 0xf, 0xf, false)); }
; DEVI void row_stats(const float* stats, int row, float& mu, float& rs) {
;     if (stats) { const float2 st = *(const float2*)(stats + 2 * (size_t)row); mu = st.x * (1.0f / 1024.0f); const float var = st.y * (1.0f / 1024.0f) - mu * mu; rs = rsqrtf(fmaxf(var, 0.f) + LN_EPS); }
;     DEVI void operator()(const f32x4 (&acc)[2][2][4][2], const pg8::Unit& u, int wr, int wc, int fr, int fq) const {
;         float mu[2][4], rs[2][4];
; #pragma unroll
;         for (int ai = 0; ai < 2; ++ai)
; #pragma unroll
;             for (int m = 0; m < 4; ++m) row_stats(stats, u.pm * 256 + ai * 128 + wr * 64 + m * 16 + fr, mu[ai][m], rs[ai][m]);
; #pragma unroll
;         for (int n = 0; n < 2; ++n) {
;             const int tc = u.pn * 256 + wc * 32 + 8 * fq + 4 * n;
;             const int j = u.pn * 128 + wc * 32 + 8 * fq + 4 * n;
;             const f32x4 sg = *(const f32x4*)(s + tc), cg_ = *(const f32x4*)(c + tc), su = *(const f32x4*)(s + tc + 128), cu = *(const f32x4*)(c + tc + 128);
;             const f32x4 w0 = *(const f32x4*)(cw + j), w1 = *(const f32x4*)(cw + DFF + j), w2 = *(const f32x4*)(cw + 2 * DFF + j), cbv = *(const f32x4*)(cb + j);
; #pragma unroll
;             for (int ai = 0; ai < 2; ++ai) {
;                 f32x4 gprev = (f32x4){0.f, 0.f, 0.f, 0.f};
; #pragma unroll
;                 for (int m = 0; m < 4; ++m) {
;                     const int row = u.pm * 256 + ai * 128 + wr * 64 + m * 16 + fr;
;                     const f32x4 g = (acc[ai][0][m][n] - mu[ai][m] * sg) * rs[ai][m] + cg_;
;                     const f32x4 uu = (acc[ai][1][m][n] - mu[ai][m] * su) * rs[ai][m] + cu;
;                     f32x4 p1, p2;
; #pragma unroll
;                     for (int e = 0; e < 4; ++e) {
;                         p1[e] = dppf<0x111>(dppf<0x121>(0.f, gprev[e]), g[e]);
;                         p2[e] = dppf<0x112>(dppf<0x122>(0.f, gprev[e]), g[e]);
;                     }
;                     const int blk = row >> 6;
;                     if (m == 0 && fr < 2) {
;                         const f32x4 pg = (fr == 0) ? (w2 * g + cbv) : (w1 * p1 + w2 * g + cbv);
.LBB0_1415:
	s_lshl_b32 s41, s72, 8
	s_add_i32 s41, s41, s39
	v_or_b32_e32 v188, s41, v172
	v_ashrrev_i32_e32 v189, 31, v188
	v_or_b32_e32 v208, 16, v188
	v_or_b32_e32 v212, 32, v188
	v_or_b32_e32 v200, 48, v188
	v_lshl_add_u64 v[96:97], v[188:189], 3, s[12:13]
	v_ashrrev_i32_e32 v209, 31, v208
	v_ashrrev_i32_e32 v213, 31, v212
	v_ashrrev_i32_e32 v201, 31, v200
	v_lshl_add_u64 v[98:99], v[208:209], 3, s[12:13]
	v_lshl_add_u64 v[100:101], v[212:213], 3, s[12:13]
	v_lshl_add_u64 v[102:103], v[200:201], 3, s[12:13]
	s_waitcnt vmcnt(0)
	flat_load_dwordx2 v[190:191], v[96:97]
	flat_load_dwordx2 v[220:221], v[98:99]
	flat_load_dwordx2 v[216:217], v[100:101]
	flat_load_dwordx2 v[214:215], v[102:103]
	v_add_u32_e32 v96, 0x80, v188
	v_ashrrev_i32_e32 v97, 31, v96
	v_lshl_add_u64 v[160:161], v[96:97], 3, s[12:13]
	v_add_u32_e32 v96, 0x90, v188
	v_ashrrev_i32_e32 v97, 31, v96
	v_lshl_add_u64 v[162:163], v[96:97], 3, s[12:13]
	v_add_u32_e32 v96, 0xa0, v188
	v_lshl_or_b32 v198, s68, 8, v226
	v_ashrrev_i32_e32 v97, 31, v96
	v_ashrrev_i32_e32 v199, 31, v198
	v_lshl_add_u64 v[192:193], v[96:97], 3, s[12:13]
	v_add_u32_e32 v96, 0xb0, v188
	v_lshl_or_b32 v184, s68, 7, v226
	v_lshlrev_b64 v[98:99], 2, v[198:199]
	v_ashrrev_i32_e32 v97, 31, v96
	v_ashrrev_i32_e32 v185, 31, v184
	v_lshl_add_u64 v[100:101], s[16:17], 0, v[98:99]
	v_lshl_add_u64 v[194:195], v[96:97], 3, s[12:13]
	v_lshl_add_u64 v[96:97], s[18:19], 0, v[98:99]
	v_lshlrev_b64 v[186:187], 2, v[184:185]
	flat_load_dwordx4 v[120:123], v[100:101]
	flat_load_dwordx4 v[108:111], v[100:101] offset:512
	flat_load_dwordx4 v[124:127], v[96:97]
	flat_load_dwordx4 v[112:115], v[96:97] offset:512
	v_lshl_add_u64 v[96:97], s[0:1], 0, v[186:187]
	v_lshl_add_u64 v[98:99], s[34:35], 0, v[186:187]
	global_load_dwordx4 v[116:119], v[96:97], off
	global_load_dwordx4 v[100:103], v[98:99], off
	v_lshl_add_u64 v[96:97], s[36:37], 0, v[186:187]
	global_load_dwordx4 v[104:107], v[96:97], off
	v_lshl_add_u64 v[96:97], s[20:21], 0, v[186:187]
	global_load_dwordx4 v[96:99], v[96:97], off
	s_nop 0
	flat_load_dwordx2 v[202:203], v[160:161]
	flat_load_dwordx2 v[210:211], v[162:163]
	flat_load_dwordx2 v[206:207], v[192:193]
	flat_load_dwordx2 v[204:205], v[194:195]
	s_waitcnt vmcnt(0) lgkmcnt(0)
	v_pk_mul_f32 v[196:197], v[190:191], s[38:39] op_sel_hi:[1,0]
	s_nop 0
	v_fma_f32 v189, -v196, v196, v197
	v_max_f32_e32 v189, 0, v189
	v_add_f32_e32 v189, 0x3727c5ac, v189
	v_mul_f32_e32 v190, 0x4b800000, v189
	v_cmp_gt_f32_e32 vcc, s62, v189
	v_mov_b32_dpp v225, v225 row_ror:1 row_mask:0xf bank_mask:0xf
	v_mov_b32_dpp v163, v163 row_ror:2 row_mask:0xf bank_mask:0xf
	v_cndmask_b32_e32 v189, v189, v190, vcc
	v_rsq_f32_e32 v189, v189
	v_mov_b32_e32 v160, v225
	v_mov_b32_e32 v192, v163
	v_mov_b32_e32 v161, v225
	v_mul_f32_e32 v190, 0x45800000, v189
	v_cndmask_b32_e32 v190, v189, v190, vcc
	v_mov_b32_e32 v193, v163
	v_mov_b32_e32 v224, v225
	v_mov_b32_e32 v162, v163
	v_pk_fma_f32 v[154:155], v[196:197], v[110:111], v[154:155] op_sel_hi:[0,1,1] neg_lo:[1,0,0] neg_hi:[1,0,0]
	v_pk_fma_f32 v[158:159], v[196:197], v[122:123], v[158:159] op_sel_hi:[0,1,1] neg_lo:[1,0,0] neg_hi:[1,0,0]
	v_pk_fma_f32 v[156:157], v[196:197], v[120:121], v[156:157] op_sel_hi:[0,1,1] neg_lo:[1,0,0] neg_hi:[1,0,0]
	v_pk_fma_f32 v[152:153], v[196:197], v[108:109], v[152:153] op_sel_hi:[0,1,1] neg_lo:[1,0,0] neg_hi:[1,0,0]
	v_pk_fma_f32 v[218:219], v[190:191], v[158:159], v[126:127] op_sel_hi:[0,1,1]
	v_pk_fma_f32 v[222:223], v[190:191], v[156:157], v[124:125] op_sel_hi:[0,1,1]
	v_pk_fma_f32 v[154:155], v[190:191], v[154:155], v[114:115] op_sel_hi:[0,1,1]
	v_mov_b32_dpp v224, v218 row_shr:1 row_mask:0xf bank_mask:0xf
	v_mov_b32_dpp v160, v222 row_shr:1 row_mask:0xf bank_mask:0xf
	v_mov_b32_dpp v192, v222 row_shr:2 row_mask:0xf bank_mask:0xf
	v_mov_b32_dpp v161, v223 row_shr:1 row_mask:0xf bank_mask:0xf
	v_mov_b32_dpp v193, v223 row_shr:2 row_mask:0xf bank_mask:0xf
	v_mov_b32_dpp v162, v218 row_shr:2 row_mask:0xf bank_mask:0xf
	v_mov_b32_dpp v225, v219 row_shr:1 row_mask:0xf bank_mask:0xf
	v_mov_b32_dpp v163, v219 row_shr:2 row_mask:0xf bank_mask:0xf
	v_pk_fma_f32 v[152:153], v[190:191], v[152:153], v[112:113] op_sel_hi:[0,1,1]
	s_and_saveexec_b64 s[30:31], s[2:3]
	s_xor_b64 s[48:49], exec, s[30:31]
	s_cbranch_execz .LBB0_1417
	v_pk_mul_f32 v[158:159], v[116:117], v[192:193]
	v_pk_mul_f32 v[156:157], v[118:119], v[162:163]
	v_pk_fma_f32 v[158:159], v[100:101], v[160:161], v[158:159]
	v_pk_fma_f32 v[156:157], v[102:103], v[224:225], v[156:157]
	v_pk_fma_f32 v[158:159], v[222:223], v[104:105], v[158:159]
	v_pk_fma_f32 v[156:157], v[218:219], v[106:107], v[156:157]
	v_pk_add_f32 v[158:159], v[96:97], v[158:159]
	v_pk_add_f32 v[156:157], v[98:99], v[156:157]
	v_mul_f32_e32 v160, 0xbfb8aa3b, v158
	v_exp_f32_e32 v160, v160
	v_mul_f32_e32 v161, 0xbfb8aa3b, v159
	v_exp_f32_e32 v161, v161
	v_add_f32_e32 v160, 1.0, v160
	v_rcp_f32_e32 v160, v160
	v_add_f32_e32 v161, 1.0, v161
	v_rcp_f32_e32 v161, v161
	v_mul_f32_e32 v158, v158, v160
	v_mul_f32_e32 v152, v152, v158
	v_mul_f32_e32 v158, v159, v161
	v_mul_f32_e32 v159, 0xbfb8aa3b, v156
	v_exp_f32_e32 v159, v159
	v_mul_f32_e32 v160, 0xbfb8aa3b, v157
	v_exp_f32_e32 v160, v160
	v_mul_f32_e32 v153, v153, v158
	v_add_f32_e32 v158, 1.0, v159
	v_rcp_f32_e32 v158, v158
	v_add_f32_e32 v159, 1.0, v160
	v_rcp_f32_e32 v159, v159
	v_cvt_pk_bf16_f32 v152, v152, v153
	v_mul_f32_e32 v153, v156, v158
	v_mul_f32_e32 v153, v154, v153
	v_mul_f32_e32 v154, v157, v159
	v_mul_f32_e32 v154, v155, v154
	v_cvt_pk_bf16_f32 v153, v153, v154
	v_mov_b64_e32 v[154:155], s[14:15]
	v_mad_i64_i32 v[154:155], s[30:31], v188, s57, v[154:155]
	v_lshl_add_u64 v[154:155], v[184:185], 1, v[154:155]
	flat_store_dwordx2 v[154:155], v[152:153]

; DEVI unsigned pk2(float lo, float hi) { unsigned r; asm("v_cvt_pk_bf16_f32 %0, %1, %2" : "=v"(r) : "v"(lo), "v"(hi)); return r; }
; DEVI float siluf_(float x) { return x * sigmoidf_(x); }
;     DEVI void operator()(const f32x4 (&acc)[2][2][4][2], const pg8::Unit& u, int wr, int wc, int fr, int fq) const {
;     ...
;             for (int m = 0; m < 4; ++m) row_stats(stats, u.pm * 256 + ai * 128 + wr * 64 + m * 16 + fr, mu[ai][m], rs[ai][m]);
; #pragma unroll
;         for (int n = 0; n < 2; ++n) {
;             const int tc = u.pn * 256 + wc * 32 + 8 * fq + 4 * n;
;             const int j = u.pn * 128 + wc * 32 + 8 * fq + 4 * n;
;             const f32x4 sg = *(const f32x4*)(s + tc), cg_ = *(const f32x4*)(c + tc), su = *(const f32x4*)(s + tc + 128), cu = *(const f32x4*)(c + tc + 128);
;             const f32x4 w0 = *(const f32x4*)(cw + j), w1 = *(const f32x4*)(cw + DFF + j), w2 = *(const f32x4*)(cw + 2 * DFF + j), cbv = *(const f32x4*)(cb + j);
; #pragma unroll
;             for (int ai = 0; ai < 2; ++ai) {
;                 f32x4 gprev = (f32x4){0.f, 0.f, 0.f, 0.f};
; #pragma unroll
;                 for (int m = 0; m < 4; ++m) {
;                     const int row = u.pm * 256 + ai * 128 + wr * 64 + m * 16 + fr;
;                     const f32x4 g = (acc[ai][0][m][n] - mu[ai][m] * sg) * rs[ai][m] + cg_;
;                     const f32x4 uu = (acc[ai][1][m][n] - mu[ai][m] * su) * rs[ai][m] + cu;
;                     f32x4 p1, p2;
; #pragma unroll
;                     for (int e = 0; e < 4; ++e) {
;                         p1[e] = dppf<0x111>(dppf<0x121>(0.f, gprev[e]), g[e]);
;                         p2[e] = dppf<0x112>(dppf<0x122>(0.f, gprev[e]), g[e]);
;                     }
;                     const int blk = row >> 6;
;                     if (m == 0 && fr < 2) {
;                         const f32x4 pg = (fr == 0) ? (w2 * g + cbv) : (w1 * p1 + w2 * g + cbv);
;                         *(f32x4*)(headpg + ((size_t)blk * 2 + fr) * DFF + j) = pg;
;                         *(f32x4*)(headup + ((size_t)blk * 2 + fr) * DFF + j) = uu;
;                     } else {
;                         const f32x4 cv = w0 * p2 + w1 * p1 + w2 * g + cbv;
;                         u32x2 o; o.x = pk2(siluf_(cv[0]) * uu[0], siluf_(cv[1]) * uu[1]); o.y = pk2(siluf_(cv[2]) * uu[2], siluf_(cv[3]) * uu[3]);
;                         *(u32x2*)(H + (size_t)row * DFF + j) = o;
.LBB0_1419:
	s_or_b64 exec, exec, s[50:51]
	v_pk_mul_f32 v[160:161], v[220:221], s[38:39] op_sel_hi:[1,0]
	v_pk_mul_f32 v[156:157], v[216:217], s[38:39] op_sel_hi:[1,0]
	v_fma_f32 v152, -v160, v160, v161
	v_max_f32_e32 v152, 0, v152
	v_add_f32_e32 v152, 0x3727c5ac, v152
	v_cmp_gt_f32_e32 vcc, s62, v152
	v_mul_f32_e32 v153, 0x4b800000, v152
	v_lshl_add_u64 v[216:217], s[48:49], 0, v[174:175]
	v_cndmask_b32_e32 v152, v152, v153, vcc
	v_rsq_f32_e32 v152, v152
	v_pk_fma_f32 v[148:149], v[160:161], v[120:121], v[148:149] op_sel_hi:[0,1,1] neg_lo:[1,0,0] neg_hi:[1,0,0]
	v_mul_f32_e32 v153, 0x45800000, v152
	v_cndmask_b32_e32 v162, v152, v153, vcc
	v_fma_f32 v152, -v156, v156, v157
	v_max_f32_e32 v152, 0, v152
	v_add_f32_e32 v152, 0x3727c5ac, v152
	v_cmp_gt_f32_e32 vcc, s62, v152
	v_mul_f32_e32 v153, 0x4b800000, v152
	v_pk_fma_f32 v[148:149], v[162:163], v[148:149], v[124:125] op_sel_hi:[0,1,1]
	v_cndmask_b32_e32 v152, v152, v153, vcc
	v_rsq_f32_e32 v152, v152
	v_mov_b32_dpp v220, v222 row_ror:2 row_mask:0xf bank_mask:0xf
	v_mov_b32_dpp v221, v223 row_ror:2 row_mask:0xf bank_mask:0xf
	v_mul_f32_e32 v153, 0x45800000, v152
	v_cndmask_b32_e32 v158, v152, v153, vcc
	v_pk_mul_f32 v[152:153], v[214:215], s[38:39] op_sel_hi:[1,0]
	v_mad_u64_u32 v[214:215], s[30:31], v216, s58, 0
	v_fma_f32 v154, -v152, v152, v153
	v_max_f32_e32 v154, 0, v154
	v_add_f32_e32 v154, 0x3727c5ac, v154
	v_cmp_gt_f32_e32 vcc, s62, v154
	v_mul_f32_e32 v155, 0x4b800000, v154
	v_mad_i32_i24 v215, v217, s58, v215
	v_cndmask_b32_e32 v154, v154, v155, vcc
	v_rsq_f32_e32 v154, v154
	v_mov_b32_dpp v216, v222 row_ror:1 row_mask:0xf bank_mask:0xf
	v_mov_b32_dpp v220, v148 row_shr:2 row_mask:0xf bank_mask:0xf
	v_mov_b32_dpp v217, v223 row_ror:1 row_mask:0xf bank_mask:0xf
	v_mov_b32_dpp v221, v149 row_shr:2 row_mask:0xf bank_mask:0xf
	v_mov_b32_dpp v216, v148 row_shr:1 row_mask:0xf bank_mask:0xf
	v_mov_b32_dpp v217, v149 row_shr:1 row_mask:0xf bank_mask:0xf
	v_mov_b32_dpp v222, v218 row_ror:1 row_mask:0xf bank_mask:0xf
	v_mov_b32_dpp v224, v218 row_ror:2 row_mask:0xf bank_mask:0xf
	v_mov_b32_dpp v223, v219 row_ror:1 row_mask:0xf bank_mask:0xf
	v_mov_b32_dpp v225, v219 row_ror:2 row_mask:0xf bank_mask:0xf
	v_pk_mul_f32 v[218:219], v[116:117], v[220:221]
	v_mul_f32_e32 v155, 0x45800000, v154
	v_pk_fma_f32 v[216:217], v[100:101], v[216:217], v[218:219]
	v_cndmask_b32_e32 v154, v154, v155, vcc
	v_pk_fma_f32 v[216:217], v[148:149], v[104:105], v[216:217]
	v_pk_fma_f32 v[144:145], v[160:161], v[108:109], v[144:145] op_sel_hi:[0,1,1] neg_lo:[1,0,0] neg_hi:[1,0,0]
	v_pk_add_f32 v[216:217], v[96:97], v[216:217]
	v_pk_fma_f32 v[144:145], v[162:163], v[144:145], v[112:113] op_sel_hi:[0,1,1]
	v_mul_f32_e32 v155, 0xbfb8aa3b, v216
	v_exp_f32_e32 v155, v155
	v_pk_fma_f32 v[150:151], v[160:161], v[122:123], v[150:151] op_sel_hi:[0,1,1] neg_lo:[1,0,0] neg_hi:[1,0,0]
	v_pk_fma_f32 v[150:151], v[162:163], v[150:151], v[126:127] op_sel_hi:[0,1,1]
	v_pk_fma_f32 v[146:147], v[160:161], v[110:111], v[146:147] op_sel_hi:[0,1,1] neg_lo:[1,0,0] neg_hi:[1,0,0]
	v_add_f32_e32 v155, 1.0, v155
	v_rcp_f32_e32 v155, v155
	v_mov_b32_dpp v224, v150 row_shr:2 row_mask:0xf bank_mask:0xf
	v_mov_b32_dpp v225, v151 row_shr:2 row_mask:0xf bank_mask:0xf
	v_mov_b32_dpp v222, v150 row_shr:1 row_mask:0xf bank_mask:0xf
	v_mul_f32_e32 v155, v216, v155
	v_mul_f32_e32 v144, v144, v155
	v_mul_f32_e32 v155, 0xbfb8aa3b, v217
	v_exp_f32_e32 v155, v155
	v_mov_b32_dpp v223, v151 row_shr:1 row_mask:0xf bank_mask:0xf
	v_pk_mul_f32 v[220:221], v[118:119], v[224:225]
	v_pk_fma_f32 v[146:147], v[162:163], v[146:147], v[114:115] op_sel_hi:[0,1,1]
	v_add_f32_e32 v155, 1.0, v155
	v_rcp_f32_e32 v155, v155
	v_pk_fma_f32 v[220:221], v[102:103], v[222:223], v[220:221]
	v_pk_fma_f32 v[140:141], v[156:157], v[120:121], v[140:141] op_sel_hi:[0,1,1] neg_lo:[1,0,0] neg_hi:[1,0,0]
	v_pk_fma_f32 v[218:219], v[150:151], v[106:107], v[220:221]
	v_mul_f32_e32 v155, v217, v155
	v_pk_add_f32 v[218:219], v[98:99], v[218:219]
	v_mul_f32_e32 v145, v145, v155
	v_cvt_pk_bf16_f32 v216, v144, v145
	v_mul_f32_e32 v144, 0xbfb8aa3b, v218
	v_mul_f32_e32 v145, 0xbfb8aa3b, v219
	v_exp_f32_e32 v144, v144
	v_exp_f32_e32 v145, v145
	v_pk_fma_f32 v[140:141], v[158:159], v[140:141], v[124:125] op_sel_hi:[0,1,1]
	v_add_f32_e32 v144, 1.0, v144
	v_add_f32_e32 v145, 1.0, v145
	v_rcp_f32_e32 v144, v144
	v_rcp_f32_e32 v145, v145
	v_mov_b32_dpp v220, v150 row_ror:2 row_mask:0xf bank_mask:0xf
	v_mul_f32_e32 v144, v218, v144
	v_mul_f32_e32 v145, v219, v145
	v_mul_f32_e32 v144, v146, v144
	v_mul_f32_e32 v145, v147, v145
	v_mov_b64_e32 v[146:147], s[14:15]
	v_cvt_pk_bf16_f32 v217, v144, v145
	v_mad_i64_i32 v[144:145], s[30:31], v208, s57, v[146:147]
	v_lshlrev_b64 v[208:209], 1, v[184:185]
	v_lshl_add_u64 v[144:145], v[144:145], 0, v[208:209]
	flat_store_dwordx2 v[144:145], v[216:217]
	v_mov_b32_dpp v218, v148 row_ror:2 row_mask:0xf bank_mask:0xf
	v_mov_b32_dpp v219, v149 row_ror:2 row_mask:0xf bank_mask:0xf
	v_mov_b32_dpp v216, v148 row_ror:1 row_mask:0xf bank_mask:0xf
	v_mov_b32_dpp v218, v140 row_shr:2 row_mask:0xf bank_mask:0xf
	v_mov_b32_dpp v217, v149 row_ror:1 row_mask:0xf bank_mask:0xf
	v_mov_b32_dpp v219, v141 row_shr:2 row_mask:0xf bank_mask:0xf
	v_mov_b32_dpp v216, v140 row_shr:1 row_mask:0xf bank_mask:0xf
	v_mov_b32_dpp v217, v141 row_shr:1 row_mask:0xf bank_mask:0xf
	v_mov_b32_dpp v148, v150 row_ror:1 row_mask:0xf bank_mask:0xf
	v_mov_b32_dpp v149, v151 row_ror:1 row_mask:0xf bank_mask:0xf
	v_mov_b32_dpp v221, v151 row_ror:2 row_mask:0xf bank_mask:0xf
	v_pk_mul_f32 v[150:151], v[116:117], v[218:219]
	v_pk_fma_f32 v[136:137], v[156:157], v[108:109], v[136:137] op_sel_hi:[0,1,1] neg_lo:[1,0,0] neg_hi:[1,0,0]
; DEVI unsigned pk2(float lo, float hi) { unsigned r; asm("v_cvt_pk_bf16_f32 %0, %1, %2" : "=v"(r) : "v"(lo), "v"(hi)); return r; }
; DEVI float siluf_(float x) { return x * sigmoidf_(x); }
; template <int CTRL> DEVI float dppf(float old, float src) { return __int_as_float(__builtin_amdgcn_update_dpp(__float_as_int(old), __float_as_int(src), CTRL, 0xf, 0xf, false)); }
;     DEVI void operator()(const f32x4 (&acc)[2][2][4][2], const pg8::Unit& u, int wr, int wc, int fr, int fq) const {
;     ...
;                     const int row = u.pm * 256 + ai * 128 + wr * 64 + m * 16 + fr;
;                     const f32x4 g = (acc[ai][0][m][n] - mu[ai][m] * sg) * rs[ai][m] + cg_;
;                     const f32x4 uu = (acc[ai][1][m][n] - mu[ai][m] * su) * rs[ai][m] + cu;
;                     f32x4 p1, p2;
; #pragma unroll
;                     for (int e = 0; e < 4; ++e) {
;                         p1[e] = dppf<0x111>(dppf<0x121>(0.f, gprev[e]), g[e]);
;                         p2[e] = dppf<0x112>(dppf<0x122>(0.f, gprev[e]), g[e]);
;                     }
;                     const int blk = row >> 6;
;                     if (m == 0 && fr < 2) {
;                         const f32x4 pg = (fr == 0) ? (w2 * g + cbv) : (w1 * p1 + w2 * g + cbv);
;                         *(f32x4*)(headpg + ((size_t)blk * 2 + fr) * DFF + j) = pg;
;                         *(f32x4*)(headup + ((size_t)blk * 2 + fr) * DFF + j) = uu;
;                     } else {
;                         const f32x4 cv = w0 * p2 + w1 * p1 + w2 * g + cbv;
;                         u32x2 o; o.x = pk2(siluf_(cv[0]) * uu[0], siluf_(cv[1]) * uu[1]); o.y = pk2(siluf_(cv[2]) * uu[2], siluf_(cv[3]) * uu[3]);
;                         *(u32x2*)(H + (size_t)row * DFF + j) = o;
;                     }
;                     if (m == 3 && fr >= 14) *(f32x4*)(tailg + ((size_t)blk * 2 + (fr - 14)) * DFF + j) = g;
	v_pk_fma_f32 v[150:151], v[100:101], v[216:217], v[150:151]
	v_pk_fma_f32 v[136:137], v[158:159], v[136:137], v[112:113] op_sel_hi:[0,1,1]
	v_pk_fma_f32 v[150:151], v[140:141], v[104:105], v[150:151]
	v_pk_fma_f32 v[142:143], v[156:157], v[122:123], v[142:143] op_sel_hi:[0,1,1] neg_lo:[1,0,0] neg_hi:[1,0,0]
	v_pk_add_f32 v[150:151], v[96:97], v[150:151]
	v_pk_fma_f32 v[142:143], v[158:159], v[142:143], v[126:127] op_sel_hi:[0,1,1]
	v_mul_f32_e32 v155, 0xbfb8aa3b, v150
	v_exp_f32_e32 v155, v155
	v_mov_b32_dpp v220, v142 row_shr:2 row_mask:0xf bank_mask:0xf
	v_mov_b32_dpp v221, v143 row_shr:2 row_mask:0xf bank_mask:0xf
	v_mov_b32_dpp v148, v142 row_shr:1 row_mask:0xf bank_mask:0xf
	v_add_f32_e32 v155, 1.0, v155
	v_rcp_f32_e32 v155, v155
	v_mov_b32_dpp v149, v143 row_shr:1 row_mask:0xf bank_mask:0xf
	v_pk_mul_f32 v[218:219], v[118:119], v[220:221]
	v_pk_fma_f32 v[138:139], v[156:157], v[110:111], v[138:139] op_sel_hi:[0,1,1] neg_lo:[1,0,0] neg_hi:[1,0,0]
	v_mul_f32_e32 v150, v150, v155
	v_mul_f32_e32 v136, v136, v150
	v_mul_f32_e32 v150, 0xbfb8aa3b, v151
	v_exp_f32_e32 v150, v150
	v_pk_fma_f32 v[148:149], v[102:103], v[148:149], v[218:219]
	v_pk_fma_f32 v[138:139], v[158:159], v[138:139], v[114:115] op_sel_hi:[0,1,1]
	v_pk_fma_f32 v[148:149], v[142:143], v[106:107], v[148:149]
	v_add_f32_e32 v150, 1.0, v150
	v_rcp_f32_e32 v150, v150
	v_pk_add_f32 v[148:149], v[98:99], v[148:149]
	v_pk_fma_f32 v[132:133], v[152:153], v[120:121], v[132:133] op_sel_hi:[0,1,1] neg_lo:[1,0,0] neg_hi:[1,0,0]
	v_pk_fma_f32 v[132:133], v[154:155], v[132:133], v[124:125] op_sel_hi:[0,1,1]
	v_mul_f32_e32 v150, v151, v150
	v_mul_f32_e32 v137, v137, v150
	v_cvt_pk_bf16_f32 v150, v136, v137
	v_mul_f32_e32 v136, 0xbfb8aa3b, v148
	v_mul_f32_e32 v137, 0xbfb8aa3b, v149
	v_exp_f32_e32 v136, v136
	v_exp_f32_e32 v137, v137
	v_pk_fma_f32 v[128:129], v[152:153], v[108:109], v[128:129] op_sel_hi:[0,1,1] neg_lo:[1,0,0] neg_hi:[1,0,0]
	v_pk_fma_f32 v[128:129], v[154:155], v[128:129], v[112:113] op_sel_hi:[0,1,1]
	v_add_f32_e32 v136, 1.0, v136
	v_add_f32_e32 v137, 1.0, v137
	v_rcp_f32_e32 v136, v136
	v_rcp_f32_e32 v137, v137
	v_pk_fma_f32 v[134:135], v[152:153], v[122:123], v[134:135] op_sel_hi:[0,1,1] neg_lo:[1,0,0] neg_hi:[1,0,0]
	v_pk_fma_f32 v[134:135], v[154:155], v[134:135], v[126:127] op_sel_hi:[0,1,1]
	v_mul_f32_e32 v136, v148, v136
	v_mul_f32_e32 v137, v149, v137
	v_mul_f32_e32 v136, v138, v136
	v_mul_f32_e32 v137, v139, v137
	v_cvt_pk_bf16_f32 v151, v136, v137
	v_mad_i64_i32 v[136:137], s[30:31], v212, s57, v[146:147]
	v_lshl_add_u64 v[136:137], v[136:137], 0, v[208:209]
	v_mov_b32_dpp v148, v140 row_ror:2 row_mask:0xf bank_mask:0xf
	v_mov_b32_dpp v149, v141 row_ror:2 row_mask:0xf bank_mask:0xf
	flat_store_dwordx2 v[136:137], v[150:151]
	v_mov_b32_dpp v138, v140 row_ror:1 row_mask:0xf bank_mask:0xf
	v_mov_b32_dpp v148, v132 row_shr:2 row_mask:0xf bank_mask:0xf
	v_mov_b32_dpp v139, v141 row_ror:1 row_mask:0xf bank_mask:0xf
	v_mov_b32_dpp v149, v133 row_shr:2 row_mask:0xf bank_mask:0xf
	v_mov_b32_dpp v138, v132 row_shr:1 row_mask:0xf bank_mask:0xf
	v_mov_b32_dpp v139, v133 row_shr:1 row_mask:0xf bank_mask:0xf
	v_mov_b32_dpp v140, v142 row_ror:1 row_mask:0xf bank_mask:0xf
	v_mov_b32_dpp v150, v142 row_ror:2 row_mask:0xf bank_mask:0xf
	v_mov_b32_dpp v141, v143 row_ror:1 row_mask:0xf bank_mask:0xf
	v_mov_b32_dpp v151, v143 row_ror:2 row_mask:0xf bank_mask:0xf
	v_pk_mul_f32 v[142:143], v[116:117], v[148:149]
	v_mov_b32_dpp v150, v134 row_shr:2 row_mask:0xf bank_mask:0xf
	v_pk_fma_f32 v[138:139], v[100:101], v[138:139], v[142:143]
	v_mov_b32_dpp v151, v135 row_shr:2 row_mask:0xf bank_mask:0xf
	v_pk_fma_f32 v[138:139], v[132:133], v[104:105], v[138:139]
	v_mov_b32_dpp v140, v134 row_shr:1 row_mask:0xf bank_mask:0xf
	v_pk_add_f32 v[138:139], v[96:97], v[138:139]
	v_mov_b32_dpp v141, v135 row_shr:1 row_mask:0xf bank_mask:0xf
	v_mul_f32_e32 v142, 0xbfb8aa3b, v138
	v_exp_f32_e32 v142, v142
	v_pk_mul_f32 v[148:149], v[118:119], v[150:151]
	v_pk_fma_f32 v[130:131], v[152:153], v[110:111], v[130:131] op_sel_hi:[0,1,1] neg_lo:[1,0,0] neg_hi:[1,0,0]
	v_pk_fma_f32 v[140:141], v[102:103], v[140:141], v[148:149]
	v_add_f32_e32 v142, 1.0, v142
	v_rcp_f32_e32 v142, v142
	v_pk_fma_f32 v[140:141], v[134:135], v[106:107], v[140:141]
	v_pk_fma_f32 v[130:131], v[154:155], v[130:131], v[114:115] op_sel_hi:[0,1,1]
	v_pk_add_f32 v[140:141], v[98:99], v[140:141]
	v_mul_f32_e32 v138, v138, v142
	v_mul_f32_e32 v128, v128, v138
	v_mul_f32_e32 v138, 0xbfb8aa3b, v139
	v_exp_f32_e32 v138, v138
	s_nop 0
	v_add_f32_e32 v138, 1.0, v138
	v_rcp_f32_e32 v138, v138
	s_nop 0
	v_mul_f32_e32 v138, v139, v138
	v_mul_f32_e32 v129, v129, v138
	v_cvt_pk_bf16_f32 v128, v128, v129
	v_mul_f32_e32 v129, 0xbfb8aa3b, v140
	v_exp_f32_e32 v129, v129
	s_nop 0
	v_add_f32_e32 v129, 1.0, v129
	v_rcp_f32_e32 v129, v129
	s_nop 0
	v_mul_f32_e32 v129, v140, v129
	v_mul_f32_e32 v129, v130, v129
	v_mul_f32_e32 v130, 0xbfb8aa3b, v141
	v_exp_f32_e32 v130, v130
	s_nop 0
	v_add_f32_e32 v130, 1.0, v130
	v_rcp_f32_e32 v130, v130
	s_nop 0
	v_mul_f32_e32 v130, v141, v130
	v_mul_f32_e32 v130, v131, v130
	v_cvt_pk_bf16_f32 v129, v129, v130
	v_mad_i64_i32 v[130:131], s[30:31], v200, s57, v[146:147]
	v_lshl_add_u64 v[148:149], v[130:131], 0, v[208:209]
	flat_store_dwordx2 v[148:149], v[128:129]
	v_lshl_add_u64 v[128:129], s[22:23], 0, v[214:215]
	v_lshl_add_u64 v[146:147], v[184:185], 2, v[128:129]
	s_and_saveexec_b64 s[48:49], s[6:7]
	s_cbranch_execz .LBB0_1421
	flat_store_dwordx4 v[146:147], v[132:135]
; DEVI unsigned pk2(float lo, float hi) { unsigned r; asm("v_cvt_pk_bf16_f32 %0, %1, %2" : "=v"(r) : "v"(lo), "v"(hi)); return r; }
; DEVI float siluf_(float x) { return x * sigmoidf_(x); }
; template <int CTRL> DEVI float dppf(float old, float src) { return __int_as_float(__builtin_amdgcn_update_dpp(__float_as_int(old), __float_as_int(src), CTRL, 0xf, 0xf, false)); }
; DEVI void row_stats(const float* stats, int row, float& mu, float& rs) {
;     if (stats) { const float2 st = *(const float2*)(stats + 2 * (size_t)row); mu = st.x * (1.0f / 1024.0f); const float var = st.y * (1.0f / 1024.0f) - mu * mu; rs = rsqrtf(fmaxf(var, 0.f) + LN_EPS); }
;     DEVI void operator()(const f32x4 (&acc)[2][2][4][2], const pg8::Unit& u, int wr, int wc, int fr, int fq) const {
;     ...
;                 for (int m = 0; m < 4; ++m) {
;                     const int row = u.pm * 256 + ai * 128 + wr * 64 + m * 16 + fr;
;                     const f32x4 g = (acc[ai][0][m][n] - mu[ai][m] * sg) * rs[ai][m] + cg_;
;                     const f32x4 uu = (acc[ai][1][m][n] - mu[ai][m] * su) * rs[ai][m] + cu;
;                     f32x4 p1, p2;
; #pragma unroll
;                     for (int e = 0; e < 4; ++e) {
;                         p1[e] = dppf<0x111>(dppf<0x121>(0.f, gprev[e]), g[e]);
;                         p2[e] = dppf<0x112>(dppf<0x122>(0.f, gprev[e]), g[e]);
;                     }
;                     const int blk = row >> 6;
;                     if (m == 0 && fr < 2) {
;                         const f32x4 pg = (fr == 0) ? (w2 * g + cbv) : (w1 * p1 + w2 * g + cbv);
;                         *(f32x4*)(headpg + ((size_t)blk * 2 + fr) * DFF + j) = pg;
;                         *(f32x4*)(headup + ((size_t)blk * 2 + fr) * DFF + j) = uu;
;                     } else {
;                         const f32x4 cv = w0 * p2 + w1 * p1 + w2 * g + cbv;
;                         u32x2 o; o.x = pk2(siluf_(cv[0]) * uu[0], siluf_(cv[1]) * uu[1]); o.y = pk2(siluf_(cv[2]) * uu[2], siluf_(cv[3]) * uu[3]);
;                         *(u32x2*)(H + (size_t)row * DFF + j) = o;
.LBB0_1421:
	s_or_b64 exec, exec, s[48:49]
	v_pk_mul_f32 v[140:141], v[202:203], s[38:39] op_sel_hi:[1,0]
	v_fma_f32 v128, -v140, v140, v141
	v_max_f32_e32 v128, 0, v128
	v_add_f32_e32 v128, 0x3727c5ac, v128
	v_cmp_gt_f32_e32 vcc, s62, v128
	v_mul_f32_e32 v129, 0x4b800000, v128
	v_pk_fma_f32 v[94:95], v[140:141], v[122:123], v[94:95] op_sel_hi:[0,1,1] neg_lo:[1,0,0] neg_hi:[1,0,0]
	v_cndmask_b32_e32 v128, v128, v129, vcc
	v_rsq_f32_e32 v128, v128
	v_pk_fma_f32 v[92:93], v[140:141], v[120:121], v[92:93] op_sel_hi:[0,1,1] neg_lo:[1,0,0] neg_hi:[1,0,0]
	v_mov_b32_dpp v131, v131 row_ror:2 row_mask:0xf bank_mask:0xf
	s_addk_i32 s41, 0x80
	v_mul_f32_e32 v129, 0x45800000, v128
	v_cndmask_b32_e32 v138, v128, v129, vcc
	v_pk_fma_f32 v[212:213], v[94:95], v[138:139], v[126:127] op_sel_hi:[1,0,1]
	v_pk_fma_f32 v[214:215], v[92:93], v[138:139], v[124:125] op_sel_hi:[1,0,1]
	v_mov_b32_dpp v129, v129 row_ror:1 row_mask:0xf bank_mask:0xf
	v_pk_fma_f32 v[90:91], v[140:141], v[110:111], v[90:91] op_sel_hi:[0,1,1] neg_lo:[1,0,0] neg_hi:[1,0,0]
	v_pk_fma_f32 v[88:89], v[140:141], v[108:109], v[88:89] op_sel_hi:[0,1,1] neg_lo:[1,0,0] neg_hi:[1,0,0]
	v_mov_b32_e32 v92, v129
	v_mov_b32_e32 v94, v131
	v_mov_b32_e32 v93, v129
	v_mov_b32_e32 v95, v131
	v_mov_b32_e32 v128, v129
	v_mov_b32_e32 v130, v131
	v_or_b32_e32 v135, s41, v172
	v_mov_b32_dpp v92, v214 row_shr:1 row_mask:0xf bank_mask:0xf
	v_mov_b32_dpp v94, v214 row_shr:2 row_mask:0xf bank_mask:0xf
	v_mov_b32_dpp v93, v215 row_shr:1 row_mask:0xf bank_mask:0xf
	v_mov_b32_dpp v95, v215 row_shr:2 row_mask:0xf bank_mask:0xf
	v_mov_b32_dpp v128, v212 row_shr:1 row_mask:0xf bank_mask:0xf
	v_mov_b32_dpp v130, v212 row_shr:2 row_mask:0xf bank_mask:0xf
	v_mov_b32_dpp v129, v213 row_shr:1 row_mask:0xf bank_mask:0xf
	v_mov_b32_dpp v131, v213 row_shr:2 row_mask:0xf bank_mask:0xf
	v_pk_fma_f32 v[90:91], v[138:139], v[90:91], v[114:115] op_sel_hi:[0,1,1]
	v_pk_fma_f32 v[88:89], v[138:139], v[88:89], v[112:113] op_sel_hi:[0,1,1]
	s_and_saveexec_b64 s[30:31], s[2:3]
	s_xor_b64 s[48:49], exec, s[30:31]
	s_cbranch_execz .LBB0_1423
	v_pk_mul_f32 v[94:95], v[116:117], v[94:95]
	v_pk_mul_f32 v[130:131], v[118:119], v[130:131]
	v_pk_fma_f32 v[92:93], v[100:101], v[92:93], v[94:95]
	v_pk_fma_f32 v[128:129], v[102:103], v[128:129], v[130:131]
	v_pk_fma_f32 v[92:93], v[104:105], v[214:215], v[92:93]
	s_nop 0
	v_pk_add_f32 v[92:93], v[96:97], v[92:93]
	s_nop 0
	v_mul_f32_e32 v94, 0xbfb8aa3b, v92
	v_exp_f32_e32 v130, v94
	v_mul_f32_e32 v94, 0xbfb8aa3b, v93
	v_exp_f32_e32 v131, v94
	v_pk_fma_f32 v[94:95], v[106:107], v[212:213], v[128:129]
	v_add_f32_e32 v128, 1.0, v130
	v_rcp_f32_e32 v128, v128
	v_add_f32_e32 v129, 1.0, v131
	v_rcp_f32_e32 v129, v129
	v_pk_add_f32 v[94:95], v[98:99], v[94:95]
	v_mul_f32_e32 v92, v92, v128
	v_mul_f32_e32 v88, v88, v92
	v_mul_f32_e32 v92, v93, v129
	v_mul_f32_e32 v93, 0xbfb8aa3b, v94
	v_exp_f32_e32 v93, v93
	v_mul_f32_e32 v128, 0xbfb8aa3b, v95
	v_exp_f32_e32 v128, v128
	v_mul_f32_e32 v89, v89, v92
	v_add_f32_e32 v92, 1.0, v93
	v_rcp_f32_e32 v92, v92
	v_add_f32_e32 v93, 1.0, v128
	v_rcp_f32_e32 v93, v93
	v_cvt_pk_bf16_f32 v88, v88, v89
	v_mul_f32_e32 v89, v94, v92
	v_mul_f32_e32 v89, v90, v89
	v_mul_f32_e32 v90, v95, v93
	v_mul_f32_e32 v90, v91, v90
	v_cvt_pk_bf16_f32 v89, v89, v90
	v_mov_b64_e32 v[90:91], s[14:15]
	v_mad_i64_i32 v[90:91], s[30:31], v135, s57, v[90:91]
	v_lshl_add_u64 v[90:91], v[184:185], 1, v[90:91]
	flat_store_dwordx2 v[90:91], v[88:89]

; DEVI unsigned pk2(float lo, float hi) { unsigned r; asm("v_cvt_pk_bf16_f32 %0, %1, %2" : "=v"(r) : "v"(lo), "v"(hi)); return r; }
; DEVI float siluf_(float x) { return x * sigmoidf_(x); }
; template <int CTRL> DEVI float dppf(float old, float src) { return __int_as_float(__builtin_amdgcn_update_dpp(__float_as_int(old), __float_as_int(src), CTRL, 0xf, 0xf, false)); }
; DEVI void row_stats(const float* stats, int row, float& mu, float& rs) {
;     if (stats) { const float2 st = *(const float2*)(stats + 2 * (size_t)row); mu = st.x * (1.0f / 1024.0f); const float var = st.y * (1.0f / 1024.0f) - mu * mu; rs = rsqrtf(fmaxf(var, 0.f) + LN_EPS); }
;     DEVI void operator()(const f32x4 (&acc)[2][2][4][2], const pg8::Unit& u, int wr, int wc, int fr, int fq) const {
;     ...
;                     const int row = u.pm * 256 + ai * 128 + wr * 64 + m * 16 + fr;
;                     const f32x4 g = (acc[ai][0][m][n] - mu[ai][m] * sg) * rs[ai][m] + cg_;
;                     const f32x4 uu = (acc[ai][1][m][n] - mu[ai][m] * su) * rs[ai][m] + cu;
;                     f32x4 p1, p2;
; #pragma unroll
;                     for (int e = 0; e < 4; ++e) {
;                         p1[e] = dppf<0x111>(dppf<0x121>(0.f, gprev[e]), g[e]);
;                         p2[e] = dppf<0x112>(dppf<0x122>(0.f, gprev[e]), g[e]);
;                     }
;                     const int blk = row >> 6;
;                     if (m == 0 && fr < 2) {
;                         const f32x4 pg = (fr == 0) ? (w2 * g + cbv) : (w1 * p1 + w2 * g + cbv);
;                         *(f32x4*)(headpg + ((size_t)blk * 2 + fr) * DFF + j) = pg;
;                         *(f32x4*)(headup + ((size_t)blk * 2 + fr) * DFF + j) = uu;
;                     } else {
;                         const f32x4 cv = w0 * p2 + w1 * p1 + w2 * g + cbv;
;                         u32x2 o; o.x = pk2(siluf_(cv[0]) * uu[0], siluf_(cv[1]) * uu[1]); o.y = pk2(siluf_(cv[2]) * uu[2], siluf_(cv[3]) * uu[3]);
;                         *(u32x2*)(H + (size_t)row * DFF + j) = o;
.LBB0_1425:
	s_or_b64 exec, exec, s[48:49]
	s_nop 0
	v_lshl_add_u64 v[90:91], s[50:51], 0, v[174:175]
	v_pk_mul_f32 v[142:143], v[210:211], s[38:39] op_sel_hi:[1,0]
	v_mad_u64_u32 v[88:89], s[30:31], v90, s58, 0
	v_fma_f32 v90, -v142, v142, v143
	v_max_f32_e32 v90, 0, v90
	v_add_f32_e32 v90, 0x3727c5ac, v90
	v_mad_i32_i24 v89, v91, s58, v89
	v_cmp_gt_f32_e32 vcc, s62, v90
	v_mul_f32_e32 v91, 0x4b800000, v90
	v_pk_mul_f32 v[132:133], v[206:207], s[38:39] op_sel_hi:[1,0]
	v_cndmask_b32_e32 v90, v90, v91, vcc
	v_rsq_f32_e32 v90, v90
	v_pk_mul_f32 v[128:129], v[204:205], s[38:39] op_sel_hi:[1,0]
	v_pk_fma_f32 v[84:85], v[142:143], v[120:121], v[84:85] op_sel_hi:[0,1,1] neg_lo:[1,0,0] neg_hi:[1,0,0]
	v_mul_f32_e32 v91, 0x45800000, v90
	v_cndmask_b32_e32 v150, v90, v91, vcc
	v_fma_f32 v90, -v132, v132, v133
	v_max_f32_e32 v90, 0, v90
	v_add_f32_e32 v90, 0x3727c5ac, v90
	v_cmp_gt_f32_e32 vcc, s62, v90
	v_mul_f32_e32 v91, 0x4b800000, v90
	v_mov_b32_e32 v93, 0
	v_cndmask_b32_e32 v90, v90, v91, vcc
	v_rsq_f32_e32 v90, v90
	v_pk_fma_f32 v[84:85], v[84:85], v[150:151], v[124:125] op_sel_hi:[1,0,1]
	v_mov_b32_dpp v92, v214 row_ror:2 row_mask:0xf bank_mask:0xf
	v_mov_b32_dpp v93, v215 row_ror:2 row_mask:0xf bank_mask:0xf
	v_mul_f32_e32 v91, 0x45800000, v90
	v_cndmask_b32_e32 v134, v90, v91, vcc
	v_fma_f32 v90, -v128, v128, v129
	v_max_f32_e32 v90, 0, v90
	v_add_f32_e32 v90, 0x3727c5ac, v90
	v_cmp_gt_f32_e32 vcc, s62, v90
	v_mul_f32_e32 v91, 0x4b800000, v90
	v_pk_fma_f32 v[86:87], v[142:143], v[122:123], v[86:87] op_sel_hi:[0,1,1] neg_lo:[1,0,0] neg_hi:[1,0,0]
	v_cndmask_b32_e32 v90, v90, v91, vcc
	v_rsq_f32_e32 v90, v90
	v_mov_b32_dpp v92, v84 row_shr:2 row_mask:0xf bank_mask:0xf
	v_mov_b32_dpp v93, v85 row_shr:2 row_mask:0xf bank_mask:0xf
	v_mul_f32_e32 v91, 0x45800000, v90
	v_cndmask_b32_e32 v130, v90, v91, vcc
	v_mov_b32_dpp v90, v214 row_ror:1 row_mask:0xf bank_mask:0xf
	v_mov_b32_dpp v91, v215 row_ror:1 row_mask:0xf bank_mask:0xf
	v_pk_fma_f32 v[86:87], v[86:87], v[150:151], v[126:127] op_sel_hi:[1,0,1]
	v_mov_b32_dpp v90, v84 row_shr:1 row_mask:0xf bank_mask:0xf
	v_mov_b32_dpp v91, v85 row_shr:1 row_mask:0xf bank_mask:0xf
	v_mov_b32_dpp v204, v212 row_ror:2 row_mask:0xf bank_mask:0xf
	v_mov_b32_dpp v205, v213 row_ror:2 row_mask:0xf bank_mask:0xf
	v_pk_mul_f32 v[92:93], v[116:117], v[92:93]
	v_mov_b32_dpp v94, v212 row_ror:1 row_mask:0xf bank_mask:0xf
	v_mov_b32_dpp v204, v86 row_shr:2 row_mask:0xf bank_mask:0xf
	v_mov_b32_dpp v95, v213 row_ror:1 row_mask:0xf bank_mask:0xf
	v_mov_b32_dpp v205, v87 row_shr:2 row_mask:0xf bank_mask:0xf
	v_pk_fma_f32 v[90:91], v[100:101], v[90:91], v[92:93]
	v_mov_b32_dpp v94, v86 row_shr:1 row_mask:0xf bank_mask:0xf
	v_mov_b32_dpp v95, v87 row_shr:1 row_mask:0xf bank_mask:0xf
	v_pk_mul_f32 v[204:205], v[118:119], v[204:205]
	v_pk_fma_f32 v[90:91], v[104:105], v[84:85], v[90:91]
	v_pk_fma_f32 v[94:95], v[102:103], v[94:95], v[204:205]
	v_pk_add_f32 v[90:91], v[96:97], v[90:91]
	v_pk_fma_f32 v[92:93], v[106:107], v[86:87], v[94:95]
	v_mul_f32_e32 v94, 0xbfb8aa3b, v90
	v_exp_f32_e32 v94, v94
	v_pk_fma_f32 v[80:81], v[142:143], v[108:109], v[80:81] op_sel_hi:[0,1,1] neg_lo:[1,0,0] neg_hi:[1,0,0]
	v_pk_fma_f32 v[80:81], v[80:81], v[150:151], v[112:113] op_sel_hi:[1,0,1]
	v_pk_add_f32 v[92:93], v[98:99], v[92:93]
	v_add_f32_e32 v94, 1.0, v94
	v_rcp_f32_e32 v94, v94
	v_pk_fma_f32 v[82:83], v[142:143], v[110:111], v[82:83] op_sel_hi:[0,1,1] neg_lo:[1,0,0] neg_hi:[1,0,0]
	v_pk_fma_f32 v[82:83], v[82:83], v[150:151], v[114:115] op_sel_hi:[1,0,1]
	v_or_b32_e32 v131, 16, v135
	v_mul_f32_e32 v90, v90, v94
	v_mul_f32_e32 v80, v80, v90
	v_mul_f32_e32 v90, 0xbfb8aa3b, v91
	v_exp_f32_e32 v90, v90
	v_pk_fma_f32 v[76:77], v[132:133], v[120:121], v[76:77] op_sel_hi:[0,1,1] neg_lo:[1,0,0] neg_hi:[1,0,0]
	v_pk_fma_f32 v[76:77], v[76:77], v[134:135], v[124:125] op_sel_hi:[1,0,1]
	v_pk_fma_f32 v[72:73], v[132:133], v[108:109], v[72:73] op_sel_hi:[0,1,1] neg_lo:[1,0,0] neg_hi:[1,0,0]
	v_add_f32_e32 v90, 1.0, v90
	v_rcp_f32_e32 v90, v90
	v_pk_fma_f32 v[72:73], v[72:73], v[134:135], v[112:113] op_sel_hi:[1,0,1]
	v_pk_fma_f32 v[78:79], v[132:133], v[122:123], v[78:79] op_sel_hi:[0,1,1] neg_lo:[1,0,0] neg_hi:[1,0,0]
	v_pk_fma_f32 v[78:79], v[78:79], v[134:135], v[126:127] op_sel_hi:[1,0,1]
	v_mul_f32_e32 v90, v91, v90
	v_mul_f32_e32 v81, v81, v90
	v_cvt_pk_bf16_f32 v90, v80, v81
	v_mul_f32_e32 v80, 0xbfb8aa3b, v92
	v_mul_f32_e32 v81, 0xbfb8aa3b, v93
	v_exp_f32_e32 v80, v80
	v_exp_f32_e32 v81, v81
	v_pk_fma_f32 v[74:75], v[132:133], v[110:111], v[74:75] op_sel_hi:[0,1,1] neg_lo:[1,0,0] neg_hi:[1,0,0]
	v_pk_fma_f32 v[74:75], v[74:75], v[134:135], v[114:115] op_sel_hi:[1,0,1]
	v_add_f32_e32 v80, 1.0, v80
	v_add_f32_e32 v81, 1.0, v81
	v_rcp_f32_e32 v80, v80
	v_rcp_f32_e32 v81, v81
	v_or_b32_e32 v94, 32, v135
	v_pk_fma_f32 v[68:69], v[120:121], v[128:129], v[68:69] op_sel_hi:[1,0,1] neg_lo:[1,0,0] neg_hi:[1,0,0]
	v_mul_f32_e32 v80, v92, v80
	v_mul_f32_e32 v81, v93, v81
	v_mul_f32_e32 v80, v82, v80
	v_mul_f32_e32 v81, v83, v81
	v_cvt_pk_bf16_f32 v91, v80, v81
	v_mov_b64_e32 v[80:81], s[14:15]
	v_mad_i64_i32 v[82:83], s[30:31], v131, s57, v[80:81]
	v_lshl_add_u64 v[204:205], v[82:83], 0, v[208:209]
	flat_store_dwordx2 v[204:205], v[90:91]
	v_mov_b32_dpp v90, v84 row_ror:2 row_mask:0xf bank_mask:0xf
	v_mov_b32_dpp v91, v85 row_ror:2 row_mask:0xf bank_mask:0xf
	v_mov_b32_dpp v82, v84 row_ror:1 row_mask:0xf bank_mask:0xf
	v_mov_b32_dpp v90, v76 row_shr:2 row_mask:0xf bank_mask:0xf
	v_mov_b32_dpp v83, v85 row_ror:1 row_mask:0xf bank_mask:0xf
	v_mov_b32_dpp v91, v77 row_shr:2 row_mask:0xf bank_mask:0xf
	v_mov_b32_dpp v82, v76 row_shr:1 row_mask:0xf bank_mask:0xf
; DEVI unsigned pk2(float lo, float hi) { unsigned r; asm("v_cvt_pk_bf16_f32 %0, %1, %2" : "=v"(r) : "v"(lo), "v"(hi)); return r; }
; DEVI float siluf_(float x) { return x * sigmoidf_(x); }
; template <int CTRL> DEVI float dppf(float old, float src) { return __int_as_float(__builtin_amdgcn_update_dpp(__float_as_int(old), __float_as_int(src), CTRL, 0xf, 0xf, false)); }
;     DEVI void operator()(const f32x4 (&acc)[2][2][4][2], const pg8::Unit& u, int wr, int wc, int fr, int fq) const {
;     ...
;                     const int row = u.pm * 256 + ai * 128 + wr * 64 + m * 16 + fr;
;                     const f32x4 g = (acc[ai][0][m][n] - mu[ai][m] * sg) * rs[ai][m] + cg_;
;                     const f32x4 uu = (acc[ai][1][m][n] - mu[ai][m] * su) * rs[ai][m] + cu;
;                     f32x4 p1, p2;
; #pragma unroll
;                     for (int e = 0; e < 4; ++e) {
;                         p1[e] = dppf<0x111>(dppf<0x121>(0.f, gprev[e]), g[e]);
;                         p2[e] = dppf<0x112>(dppf<0x122>(0.f, gprev[e]), g[e]);
;                     }
;                     const int blk = row >> 6;
;                     if (m == 0 && fr < 2) {
;                         const f32x4 pg = (fr == 0) ? (w2 * g + cbv) : (w1 * p1 + w2 * g + cbv);
;                         *(f32x4*)(headpg + ((size_t)blk * 2 + fr) * DFF + j) = pg;
;                         *(f32x4*)(headup + ((size_t)blk * 2 + fr) * DFF + j) = uu;
;                     } else {
;                         const f32x4 cv = w0 * p2 + w1 * p1 + w2 * g + cbv;
;                         u32x2 o; o.x = pk2(siluf_(cv[0]) * uu[0], siluf_(cv[1]) * uu[1]); o.y = pk2(siluf_(cv[2]) * uu[2], siluf_(cv[3]) * uu[3]);
;                         *(u32x2*)(H + (size_t)row * DFF + j) = o;
;                     }
;                     if (m == 3 && fr >= 14) *(f32x4*)(tailg + ((size_t)blk * 2 + (fr - 14)) * DFF + j) = g;
	v_mov_b32_dpp v83, v77 row_shr:1 row_mask:0xf bank_mask:0xf
	v_mov_b32_dpp v84, v86 row_ror:1 row_mask:0xf bank_mask:0xf
	v_mov_b32_dpp v92, v86 row_ror:2 row_mask:0xf bank_mask:0xf
	v_mov_b32_dpp v85, v87 row_ror:1 row_mask:0xf bank_mask:0xf
	v_mov_b32_dpp v93, v87 row_ror:2 row_mask:0xf bank_mask:0xf
	v_pk_mul_f32 v[86:87], v[116:117], v[90:91]
	v_mov_b32_dpp v92, v78 row_shr:2 row_mask:0xf bank_mask:0xf
	v_pk_fma_f32 v[82:83], v[100:101], v[82:83], v[86:87]
	v_mov_b32_dpp v93, v79 row_shr:2 row_mask:0xf bank_mask:0xf
	v_pk_fma_f32 v[82:83], v[104:105], v[76:77], v[82:83]
	v_mov_b32_dpp v84, v78 row_shr:1 row_mask:0xf bank_mask:0xf
	v_pk_add_f32 v[82:83], v[96:97], v[82:83]
	v_mov_b32_dpp v85, v79 row_shr:1 row_mask:0xf bank_mask:0xf
	v_mul_f32_e32 v86, 0xbfb8aa3b, v82
	v_exp_f32_e32 v86, v86
	v_pk_mul_f32 v[90:91], v[118:119], v[92:93]
	v_pk_fma_f32 v[68:69], v[68:69], v[130:131], v[124:125] op_sel_hi:[1,0,1]
	v_pk_fma_f32 v[84:85], v[102:103], v[84:85], v[90:91]
	v_add_f32_e32 v86, 1.0, v86
	v_rcp_f32_e32 v86, v86
	v_pk_fma_f32 v[84:85], v[106:107], v[78:79], v[84:85]
	v_pk_fma_f32 v[64:65], v[128:129], v[108:109], v[64:65] op_sel_hi:[0,1,1] neg_lo:[1,0,0] neg_hi:[1,0,0]
	v_pk_add_f32 v[84:85], v[98:99], v[84:85]
	v_mul_f32_e32 v82, v82, v86
	v_mul_f32_e32 v72, v72, v82
	v_mul_f32_e32 v82, 0xbfb8aa3b, v83
	v_exp_f32_e32 v82, v82
	v_pk_fma_f32 v[64:65], v[64:65], v[130:131], v[112:113] op_sel_hi:[1,0,1]
	v_pk_fma_f32 v[66:67], v[128:129], v[110:111], v[66:67] op_sel_hi:[0,1,1] neg_lo:[1,0,0] neg_hi:[1,0,0]
	v_pk_fma_f32 v[66:67], v[66:67], v[130:131], v[114:115] op_sel_hi:[1,0,1]
	v_add_f32_e32 v82, 1.0, v82
	v_rcp_f32_e32 v82, v82
	s_nop 0
	v_mul_f32_e32 v82, v83, v82
	v_mul_f32_e32 v73, v73, v82
	v_cvt_pk_bf16_f32 v72, v72, v73
	v_mul_f32_e32 v73, 0xbfb8aa3b, v84
	v_exp_f32_e32 v73, v73
	v_mov_b32_e32 v83, 0
	v_add_f32_e32 v73, 1.0, v73
	v_rcp_f32_e32 v73, v73
	v_mov_b32_dpp v82, v78 row_ror:2 row_mask:0xf bank_mask:0xf
	v_mov_b32_dpp v83, v79 row_ror:2 row_mask:0xf bank_mask:0xf
	v_mul_f32_e32 v73, v84, v73
	v_mul_f32_e32 v73, v74, v73
	v_mul_f32_e32 v74, 0xbfb8aa3b, v85
	v_exp_f32_e32 v74, v74
	v_or_b32_e32 v84, 48, v135
	v_add_f32_e32 v74, 1.0, v74
	v_rcp_f32_e32 v74, v74
	s_nop 0
	v_mul_f32_e32 v74, v85, v74
	v_mul_f32_e32 v74, v75, v74
	v_cvt_pk_bf16_f32 v73, v73, v74
	v_mad_i64_i32 v[74:75], s[30:31], v94, s57, v[80:81]
	v_lshl_add_u64 v[206:207], v[74:75], 0, v[208:209]
	flat_store_dwordx2 v[206:207], v[72:73]
	v_xor_b32_e32 v73, 0x80000000, v123
	v_xor_b32_e32 v72, 0x80000000, v122
	v_pk_fma_f32 v[70:71], v[72:73], v[128:129], v[70:71] op_sel_hi:[1,0,1]
	v_mov_b32_dpp v74, v76 row_ror:2 row_mask:0xf bank_mask:0xf
	v_mov_b32_dpp v75, v77 row_ror:2 row_mask:0xf bank_mask:0xf
	v_mov_b32_dpp v72, v76 row_ror:1 row_mask:0xf bank_mask:0xf
	v_mov_b32_dpp v74, v68 row_shr:2 row_mask:0xf bank_mask:0xf
	v_mov_b32_dpp v73, v77 row_ror:1 row_mask:0xf bank_mask:0xf
	v_mov_b32_dpp v75, v69 row_shr:2 row_mask:0xf bank_mask:0xf
	v_pk_fma_f32 v[70:71], v[70:71], v[130:131], v[126:127] op_sel_hi:[1,0,1]
	v_mov_b32_dpp v72, v68 row_shr:1 row_mask:0xf bank_mask:0xf
	v_mov_b32_dpp v73, v69 row_shr:1 row_mask:0xf bank_mask:0xf
	v_pk_mul_f32 v[74:75], v[116:117], v[74:75]
	v_mov_b32_dpp v76, v78 row_ror:1 row_mask:0xf bank_mask:0xf
	v_mov_b32_dpp v82, v70 row_shr:2 row_mask:0xf bank_mask:0xf
	v_mov_b32_dpp v77, v79 row_ror:1 row_mask:0xf bank_mask:0xf
	v_mov_b32_dpp v83, v71 row_shr:2 row_mask:0xf bank_mask:0xf
	v_pk_fma_f32 v[72:73], v[100:101], v[72:73], v[74:75]
	v_mov_b32_dpp v76, v70 row_shr:1 row_mask:0xf bank_mask:0xf
	v_mov_b32_dpp v77, v71 row_shr:1 row_mask:0xf bank_mask:0xf
	v_pk_mul_f32 v[78:79], v[118:119], v[82:83]
	v_pk_fma_f32 v[72:73], v[104:105], v[68:69], v[72:73]
	v_pk_fma_f32 v[76:77], v[102:103], v[76:77], v[78:79]
	v_pk_add_f32 v[72:73], v[96:97], v[72:73]
	v_pk_fma_f32 v[74:75], v[106:107], v[70:71], v[76:77]
	v_mul_f32_e32 v76, 0xbfb8aa3b, v72
	v_exp_f32_e32 v76, v76
	v_pk_add_f32 v[74:75], v[98:99], v[74:75]
	v_add_f32_e32 v76, 1.0, v76
	v_rcp_f32_e32 v76, v76
	s_nop 0
	v_mul_f32_e32 v72, v72, v76
	v_mul_f32_e32 v64, v64, v72
	v_mul_f32_e32 v72, 0xbfb8aa3b, v73
	v_exp_f32_e32 v72, v72
	s_nop 0
	v_add_f32_e32 v72, 1.0, v72
	v_rcp_f32_e32 v72, v72
	s_nop 0
	v_mul_f32_e32 v72, v73, v72
	v_mul_f32_e32 v65, v65, v72
	v_cvt_pk_bf16_f32 v64, v64, v65
	v_mul_f32_e32 v65, 0xbfb8aa3b, v74
	v_exp_f32_e32 v65, v65
	s_nop 0
	v_add_f32_e32 v65, 1.0, v65
	v_rcp_f32_e32 v65, v65
	s_nop 0
	v_mul_f32_e32 v65, v74, v65
	v_mul_f32_e32 v65, v66, v65
	v_mul_f32_e32 v66, 0xbfb8aa3b, v75
	v_exp_f32_e32 v66, v66
	s_nop 0
	v_add_f32_e32 v66, 1.0, v66
	v_rcp_f32_e32 v66, v66
	s_nop 0
	v_mul_f32_e32 v66, v75, v66
	v_mul_f32_e32 v66, v67, v66
	v_cvt_pk_bf16_f32 v65, v65, v66
	v_mad_i64_i32 v[66:67], s[30:31], v84, s57, v[80:81]
	v_lshl_add_u64 v[98:99], v[66:67], 0, v[208:209]
	flat_store_dwordx2 v[98:99], v[64:65]
	v_lshl_add_u64 v[64:65], s[22:23], 0, v[88:89]
	v_lshl_add_u64 v[96:97], v[184:185], 2, v[64:65]
	s_and_saveexec_b64 s[48:49], s[6:7]
	s_cbranch_execz .LBB0_1427
	flat_store_dwordx4 v[96:97], v[68:71]
; DEVI unsigned pk2(float lo, float hi) { unsigned r; asm("v_cvt_pk_bf16_f32 %0, %1, %2" : "=v"(r) : "v"(lo), "v"(hi)); return r; }
; DEVI float siluf_(float x) { return x * sigmoidf_(x); }
; template <int CTRL> DEVI float dppf(float old, float src) { return __int_as_float(__builtin_amdgcn_update_dpp(__float_as_int(old), __float_as_int(src), CTRL, 0xf, 0xf, false)); }
;     DEVI void operator()(const f32x4 (&acc)[2][2][4][2], const pg8::Unit& u, int wr, int wc, int fr, int fq) const {
;     ...
;             const int tc = u.pn * 256 + wc * 32 + 8 * fq + 4 * n;
;             const int j = u.pn * 128 + wc * 32 + 8 * fq + 4 * n;
;             const f32x4 sg = *(const f32x4*)(s + tc), cg_ = *(const f32x4*)(c + tc), su = *(const f32x4*)(s + tc + 128), cu = *(const f32x4*)(c + tc + 128);
;             const f32x4 w0 = *(const f32x4*)(cw + j), w1 = *(const f32x4*)(cw + DFF + j), w2 = *(const f32x4*)(cw + 2 * DFF + j), cbv = *(const f32x4*)(cb + j);
; #pragma unroll
;             for (int ai = 0; ai < 2; ++ai) {
;                 f32x4 gprev = (f32x4){0.f, 0.f, 0.f, 0.f};
; #pragma unroll
;                 for (int m = 0; m < 4; ++m) {
;                     const int row = u.pm * 256 + ai * 128 + wr * 64 + m * 16 + fr;
;                     const f32x4 g = (acc[ai][0][m][n] - mu[ai][m] * sg) * rs[ai][m] + cg_;
;                     const f32x4 uu = (acc[ai][1][m][n] - mu[ai][m] * su) * rs[ai][m] + cu;
;                     f32x4 p1, p2;
; #pragma unroll
;                     for (int e = 0; e < 4; ++e) {
;                         p1[e] = dppf<0x111>(dppf<0x121>(0.f, gprev[e]), g[e]);
;                         p2[e] = dppf<0x112>(dppf<0x122>(0.f, gprev[e]), g[e]);
;                     }
;                     const int blk = row >> 6;
;                     if (m == 0 && fr < 2) {
;                         const f32x4 pg = (fr == 0) ? (w2 * g + cbv) : (w1 * p1 + w2 * g + cbv);
;                         *(f32x4*)(headpg + ((size_t)blk * 2 + fr) * DFF + j) = pg;
;                         *(f32x4*)(headup + ((size_t)blk * 2 + fr) * DFF + j) = uu;
;                     } else {
;                         const f32x4 cv = w0 * p2 + w1 * p1 + w2 * g + cbv;
;                         u32x2 o; o.x = pk2(siluf_(cv[0]) * uu[0], siluf_(cv[1]) * uu[1]); o.y = pk2(siluf_(cv[2]) * uu[2], siluf_(cv[3]) * uu[3]);
;                         *(u32x2*)(H + (size_t)row * DFF + j) = o;
.LBB0_1427:
	s_or_b64 exec, exec, s[48:49]
	v_or_b32_e32 v64, 4, v198
	v_ashrrev_i32_e32 v65, 31, v64
	v_or_b32_e32 v68, 4, v184
	v_lshlrev_b64 v[64:65], 2, v[64:65]
	v_lshl_add_u64 v[66:67], s[16:17], 0, v[64:65]
	v_ashrrev_i32_e32 v69, 31, v68
	flat_load_dwordx4 v[92:95], v[66:67]
	v_lshl_add_u64 v[70:71], s[18:19], 0, v[64:65]
	v_lshlrev_b64 v[84:85], 2, v[68:69]
	flat_load_dwordx4 v[88:91], v[70:71]
	s_nop 0
	flat_load_dwordx4 v[64:67], v[66:67] offset:512
	s_nop 0
	flat_load_dwordx4 v[72:75], v[70:71] offset:512
	v_lshl_add_u64 v[68:69], s[0:1], 0, v[84:85]
	global_load_dwordx4 v[76:79], v[68:69], off
	v_lshl_add_u64 v[68:69], s[34:35], 0, v[84:85]
	global_load_dwordx4 v[80:83], v[68:69], off
	v_lshl_add_u64 v[68:69], s[36:37], 0, v[84:85]
	v_lshl_add_u64 v[84:85], s[20:21], 0, v[84:85]
	global_load_dwordx4 v[68:71], v[68:69], off
	v_xor_b32_e32 v102, 0x80000000, v196
	global_load_dwordx4 v[84:87], v[84:85], off
	v_mov_b32_e32 v103, v102
	v_mov_b32_e32 v197, v196
	v_mov_b32_e32 v191, v190
	v_mov_b32_e32 v108, v190
	v_mov_b32_e32 v109, v190
	v_mov_b32_dpp v105, v105 row_ror:2 row_mask:0xf bank_mask:0xf
	v_mov_b32_e32 v106, v105
	v_mov_b32_e32 v107, v105
	v_mov_b32_e32 v104, v105
	s_waitcnt vmcnt(0) lgkmcnt(0)
	v_pk_fma_f32 v[62:63], v[102:103], v[94:95], v[62:63]
	v_pk_fma_f32 v[60:61], v[196:197], v[92:93], v[60:61] neg_lo:[1,0,0] neg_hi:[1,0,0]
	v_pk_fma_f32 v[58:59], v[102:103], v[66:67], v[58:59]
	v_pk_fma_f32 v[62:63], v[108:109], v[62:63], v[90:91]
	v_pk_fma_f32 v[100:101], v[190:191], v[60:61], v[88:89]
	v_mov_b32_dpp v103, v103 row_ror:1 row_mask:0xf bank_mask:0xf
	v_pk_fma_f32 v[110:111], v[196:197], v[64:65], v[56:57] neg_lo:[1,0,0] neg_hi:[1,0,0]
	v_mov_b32_e32 v56, v103
	v_mov_b32_e32 v57, v103
	v_mov_b32_e32 v102, v103
	v_mov_b32_dpp v56, v100 row_shr:1 row_mask:0xf bank_mask:0xf
	v_mov_b32_dpp v106, v100 row_shr:2 row_mask:0xf bank_mask:0xf
	v_mov_b32_dpp v57, v101 row_shr:1 row_mask:0xf bank_mask:0xf
	v_mov_b32_dpp v107, v101 row_shr:2 row_mask:0xf bank_mask:0xf
	v_mov_b32_dpp v102, v62 row_shr:1 row_mask:0xf bank_mask:0xf
	v_mov_b32_dpp v104, v62 row_shr:2 row_mask:0xf bank_mask:0xf
	v_mov_b32_dpp v103, v63 row_shr:1 row_mask:0xf bank_mask:0xf
	v_mov_b32_dpp v105, v63 row_shr:2 row_mask:0xf bank_mask:0xf
	v_pk_fma_f32 v[60:61], v[108:109], v[58:59], v[74:75]
	v_pk_fma_f32 v[58:59], v[190:191], v[110:111], v[72:73]
	s_and_saveexec_b64 s[30:31], s[2:3]
	s_xor_b64 s[48:49], exec, s[30:31]
	s_cbranch_execz .LBB0_1429
	v_pk_mul_f32 v[106:107], v[76:77], v[106:107]
	v_pk_mul_f32 v[104:105], v[78:79], v[104:105]
	v_pk_fma_f32 v[56:57], v[80:81], v[56:57], v[106:107]
	v_pk_fma_f32 v[102:103], v[82:83], v[102:103], v[104:105]
	v_pk_fma_f32 v[56:57], v[100:101], v[68:69], v[56:57]
	v_pk_fma_f32 v[102:103], v[62:63], v[70:71], v[102:103]
	v_pk_add_f32 v[56:57], v[84:85], v[56:57]
	v_pk_add_f32 v[102:103], v[86:87], v[102:103]
	v_mul_f32_e32 v104, 0xbfb8aa3b, v56
	v_exp_f32_e32 v104, v104
	v_mul_f32_e32 v105, 0xbfb8aa3b, v57
	v_exp_f32_e32 v105, v105
	v_add_f32_e32 v104, 1.0, v104
	v_rcp_f32_e32 v104, v104
	v_add_f32_e32 v105, 1.0, v105
	v_rcp_f32_e32 v105, v105
	v_mul_f32_e32 v56, v56, v104
	v_mul_f32_e32 v56, v58, v56
	v_mul_f32_e32 v58, 0xbfb8aa3b, v102
	v_mul_f32_e32 v104, 0xbfb8aa3b, v103
	v_exp_f32_e32 v58, v58
	v_exp_f32_e32 v104, v104
	v_mul_f32_e32 v57, v57, v105
	v_mul_f32_e32 v57, v59, v57
	v_add_f32_e32 v58, 1.0, v58
	v_add_f32_e32 v59, 1.0, v104
	v_rcp_f32_e32 v58, v58
	v_rcp_f32_e32 v59, v59
	v_cvt_pk_bf16_f32 v56, v56, v57
	v_mul_f32_e32 v57, v102, v58
	v_mul_f32_e32 v58, v103, v59
	v_mul_f32_e32 v57, v60, v57
	v_mul_f32_e32 v58, v61, v58
	v_cvt_pk_bf16_f32 v57, v57, v58
	v_mov_b64_e32 v[58:59], s[14:15]
	v_mad_i64_i32 v[58:59], s[30:31], v188, s57, v[58:59]
	v_lshl_add_u64 v[58:59], v[184:185], 1, v[58:59]
	flat_store_dwordx2 v[58:59], v[56:57] offset:8

; DEVI unsigned pk2(float lo, float hi) { unsigned r; asm("v_cvt_pk_bf16_f32 %0, %1, %2" : "=v"(r) : "v"(lo), "v"(hi)); return r; }
; DEVI float siluf_(float x) { return x * sigmoidf_(x); }
; template <int CTRL> DEVI float dppf(float old, float src) { return __int_as_float(__builtin_amdgcn_update_dpp(__float_as_int(old), __float_as_int(src), CTRL, 0xf, 0xf, false)); }
;     DEVI void operator()(const f32x4 (&acc)[2][2][4][2], const pg8::Unit& u, int wr, int wc, int fr, int fq) const {
;     ...
;                     const int row = u.pm * 256 + ai * 128 + wr * 64 + m * 16 + fr;
;                     const f32x4 g = (acc[ai][0][m][n] - mu[ai][m] * sg) * rs[ai][m] + cg_;
;                     const f32x4 uu = (acc[ai][1][m][n] - mu[ai][m] * su) * rs[ai][m] + cu;
;                     f32x4 p1, p2;
; #pragma unroll
;                     for (int e = 0; e < 4; ++e) {
;                         p1[e] = dppf<0x111>(dppf<0x121>(0.f, gprev[e]), g[e]);
;                         p2[e] = dppf<0x112>(dppf<0x122>(0.f, gprev[e]), g[e]);
;                     }
;                     const int blk = row >> 6;
;                     if (m == 0 && fr < 2) {
;                         const f32x4 pg = (fr == 0) ? (w2 * g + cbv) : (w1 * p1 + w2 * g + cbv);
;                         *(f32x4*)(headpg + ((size_t)blk * 2 + fr) * DFF + j) = pg;
;                         *(f32x4*)(headup + ((size_t)blk * 2 + fr) * DFF + j) = uu;
;                     } else {
;                         const f32x4 cv = w0 * p2 + w1 * p1 + w2 * g + cbv;
;                         u32x2 o; o.x = pk2(siluf_(cv[0]) * uu[0], siluf_(cv[1]) * uu[1]); o.y = pk2(siluf_(cv[2]) * uu[2], siluf_(cv[3]) * uu[3]);
;                         *(u32x2*)(H + (size_t)row * DFF + j) = o;
.LBB0_1431:
	s_or_b64 exec, exec, s[48:49]
	v_mov_b32_e32 v161, v160
	v_mov_b32_e32 v163, v162
	v_pk_fma_f32 v[52:53], v[160:161], v[92:93], v[52:53] neg_lo:[1,0,0] neg_hi:[1,0,0]
	v_xor_b32_e32 v56, 0x80000000, v160
	v_pk_fma_f32 v[52:53], v[162:163], v[52:53], v[88:89]
	v_mov_b32_dpp v102, v100 row_ror:2 row_mask:0xf bank_mask:0xf
	v_mov_b32_dpp v103, v101 row_ror:2 row_mask:0xf bank_mask:0xf
	v_mov_b32_e32 v57, v56
	v_mov_b32_dpp v60, v100 row_ror:1 row_mask:0xf bank_mask:0xf
	v_mov_b32_dpp v102, v52 row_shr:2 row_mask:0xf bank_mask:0xf
	v_mov_b32_dpp v61, v101 row_ror:1 row_mask:0xf bank_mask:0xf
	v_mov_b32_dpp v103, v53 row_shr:2 row_mask:0xf bank_mask:0xf
	v_pk_fma_f32 v[54:55], v[56:57], v[94:95], v[54:55]
	v_mov_b32_dpp v60, v52 row_shr:1 row_mask:0xf bank_mask:0xf
	v_mov_b32_dpp v61, v53 row_shr:1 row_mask:0xf bank_mask:0xf
	v_pk_fma_f32 v[50:51], v[56:57], v[66:67], v[50:51]
	v_pk_mul_f32 v[56:57], v[76:77], v[102:103]
	v_mov_b32_e32 v58, v162
	v_pk_fma_f32 v[56:57], v[80:81], v[60:61], v[56:57]
	v_mov_b32_e32 v59, v162
	v_pk_fma_f32 v[56:57], v[52:53], v[68:69], v[56:57]
	v_pk_add_f32 v[56:57], v[84:85], v[56:57]
	v_mul_f32_e32 v60, 0xbfb8aa3b, v56
	v_exp_f32_e32 v60, v60
	v_mul_f32_e32 v61, 0xbfb8aa3b, v57
	v_exp_f32_e32 v61, v61
	v_pk_fma_f32 v[54:55], v[58:59], v[54:55], v[90:91]
	v_mov_b32_dpp v104, v62 row_ror:2 row_mask:0xf bank_mask:0xf
	v_mov_b32_dpp v105, v63 row_ror:2 row_mask:0xf bank_mask:0xf
	v_add_f32_e32 v60, 1.0, v60
	v_mov_b32_dpp v100, v62 row_ror:1 row_mask:0xf bank_mask:0xf
	v_mov_b32_dpp v104, v54 row_shr:2 row_mask:0xf bank_mask:0xf
	v_mov_b32_dpp v101, v63 row_ror:1 row_mask:0xf bank_mask:0xf
	v_mov_b32_dpp v105, v55 row_shr:2 row_mask:0xf bank_mask:0xf
	v_rcp_f32_e32 v60, v60
	v_add_f32_e32 v61, 1.0, v61
	v_mov_b32_dpp v100, v54 row_shr:1 row_mask:0xf bank_mask:0xf
	v_mov_b32_dpp v101, v55 row_shr:1 row_mask:0xf bank_mask:0xf
	v_pk_fma_f32 v[50:51], v[58:59], v[50:51], v[74:75]
	v_pk_mul_f32 v[58:59], v[78:79], v[104:105]
	v_rcp_f32_e32 v61, v61
	v_pk_fma_f32 v[58:59], v[82:83], v[100:101], v[58:59]
	v_pk_fma_f32 v[48:49], v[160:161], v[64:65], v[48:49] neg_lo:[1,0,0] neg_hi:[1,0,0]
	v_pk_fma_f32 v[58:59], v[54:55], v[70:71], v[58:59]
	v_pk_fma_f32 v[48:49], v[162:163], v[48:49], v[72:73]
	v_pk_add_f32 v[58:59], v[86:87], v[58:59]
	v_mul_f32_e32 v56, v56, v60
	v_mul_f32_e32 v48, v48, v56
	v_mul_f32_e32 v56, v57, v61
	v_mul_f32_e32 v57, 0xbfb8aa3b, v58
	v_exp_f32_e32 v57, v57
	v_mul_f32_e32 v60, 0xbfb8aa3b, v59
	v_exp_f32_e32 v60, v60
	v_mul_f32_e32 v49, v49, v56
	v_add_f32_e32 v56, 1.0, v57
	v_rcp_f32_e32 v56, v56
	v_add_f32_e32 v57, 1.0, v60
	v_rcp_f32_e32 v57, v57
	v_mov_b32_e32 v157, v156
	v_cvt_pk_bf16_f32 v48, v48, v49
	v_mul_f32_e32 v49, v58, v56
	v_mov_b32_e32 v159, v158
	v_mul_f32_e32 v49, v50, v49
	v_mul_f32_e32 v50, v59, v57
	v_pk_fma_f32 v[44:45], v[156:157], v[92:93], v[44:45] neg_lo:[1,0,0] neg_hi:[1,0,0]
	v_mul_f32_e32 v50, v51, v50
	v_cvt_pk_bf16_f32 v49, v49, v50
	flat_store_dwordx2 v[144:145], v[48:49] offset:8
	v_xor_b32_e32 v48, 0x80000000, v156
	v_pk_fma_f32 v[44:45], v[158:159], v[44:45], v[88:89]
	v_mov_b32_dpp v58, v52 row_ror:2 row_mask:0xf bank_mask:0xf
	v_mov_b32_dpp v59, v53 row_ror:2 row_mask:0xf bank_mask:0xf
	v_mov_b32_e32 v49, v48
	v_mov_b32_dpp v56, v52 row_ror:1 row_mask:0xf bank_mask:0xf
	v_mov_b32_dpp v58, v44 row_shr:2 row_mask:0xf bank_mask:0xf
	v_mov_b32_dpp v57, v53 row_ror:1 row_mask:0xf bank_mask:0xf
	v_mov_b32_dpp v59, v45 row_shr:2 row_mask:0xf bank_mask:0xf
	v_pk_fma_f32 v[46:47], v[48:49], v[94:95], v[46:47]
	v_mov_b32_e32 v50, v158
	v_mov_b32_e32 v51, v158
	v_mov_b32_dpp v56, v44 row_shr:1 row_mask:0xf bank_mask:0xf
	v_mov_b32_dpp v57, v45 row_shr:1 row_mask:0xf bank_mask:0xf
	v_pk_fma_f32 v[42:43], v[48:49], v[66:67], v[42:43]
	v_pk_mul_f32 v[48:49], v[76:77], v[58:59]
	v_pk_fma_f32 v[46:47], v[50:51], v[46:47], v[90:91]
	v_mov_b32_dpp v60, v54 row_ror:2 row_mask:0xf bank_mask:0xf
	v_mov_b32_dpp v61, v55 row_ror:2 row_mask:0xf bank_mask:0xf
	v_pk_fma_f32 v[48:49], v[80:81], v[56:57], v[48:49]
	v_mov_b32_dpp v52, v54 row_ror:1 row_mask:0xf bank_mask:0xf
	v_mov_b32_dpp v60, v46 row_shr:2 row_mask:0xf bank_mask:0xf
	v_mov_b32_dpp v53, v55 row_ror:1 row_mask:0xf bank_mask:0xf
	v_mov_b32_dpp v61, v47 row_shr:2 row_mask:0xf bank_mask:0xf
	v_pk_fma_f32 v[48:49], v[44:45], v[68:69], v[48:49]
	v_mov_b32_dpp v52, v46 row_shr:1 row_mask:0xf bank_mask:0xf
	v_mov_b32_dpp v53, v47 row_shr:1 row_mask:0xf bank_mask:0xf
	v_pk_fma_f32 v[42:43], v[50:51], v[42:43], v[74:75]
	v_pk_mul_f32 v[50:51], v[78:79], v[60:61]
	v_pk_add_f32 v[48:49], v[84:85], v[48:49]
	v_pk_fma_f32 v[50:51], v[82:83], v[52:53], v[50:51]
	v_mul_f32_e32 v52, 0xbfb8aa3b, v48
	v_exp_f32_e32 v52, v52
	v_mul_f32_e32 v53, 0xbfb8aa3b, v49
	v_exp_f32_e32 v53, v53
	v_pk_fma_f32 v[40:41], v[156:157], v[64:65], v[40:41] neg_lo:[1,0,0] neg_hi:[1,0,0]
	v_add_f32_e32 v52, 1.0, v52
	v_rcp_f32_e32 v52, v52
	v_add_f32_e32 v53, 1.0, v53
	v_rcp_f32_e32 v53, v53
	v_pk_fma_f32 v[50:51], v[46:47], v[70:71], v[50:51]
	v_pk_fma_f32 v[40:41], v[158:159], v[40:41], v[72:73]
	v_pk_add_f32 v[50:51], v[86:87], v[50:51]
	v_mul_f32_e32 v48, v48, v52
	v_mul_f32_e32 v40, v40, v48
	v_mul_f32_e32 v48, v49, v53
	v_mul_f32_e32 v49, 0xbfb8aa3b, v50
	v_exp_f32_e32 v49, v49
	v_mul_f32_e32 v52, 0xbfb8aa3b, v51
	v_exp_f32_e32 v52, v52
	v_mul_f32_e32 v41, v41, v48
	v_add_f32_e32 v48, 1.0, v49
	v_rcp_f32_e32 v48, v48
	v_add_f32_e32 v49, 1.0, v52
	v_rcp_f32_e32 v49, v49
	v_mov_b32_e32 v153, v152
	v_cvt_pk_bf16_f32 v40, v40, v41
	v_mul_f32_e32 v41, v50, v48
	v_mov_b32_e32 v155, v154
	v_mul_f32_e32 v41, v42, v41
	v_mul_f32_e32 v42, v51, v49
; DEVI unsigned pk2(float lo, float hi) { unsigned r; asm("v_cvt_pk_bf16_f32 %0, %1, %2" : "=v"(r) : "v"(lo), "v"(hi)); return r; }
; DEVI float siluf_(float x) { return x * sigmoidf_(x); }
; template <int CTRL> DEVI float dppf(float old, float src) { return __int_as_float(__builtin_amdgcn_update_dpp(__float_as_int(old), __float_as_int(src), CTRL, 0xf, 0xf, false)); }
;     DEVI void operator()(const f32x4 (&acc)[2][2][4][2], const pg8::Unit& u, int wr, int wc, int fr, int fq) const {
;     ...
;                     const int row = u.pm * 256 + ai * 128 + wr * 64 + m * 16 + fr;
;                     const f32x4 g = (acc[ai][0][m][n] - mu[ai][m] * sg) * rs[ai][m] + cg_;
;                     const f32x4 uu = (acc[ai][1][m][n] - mu[ai][m] * su) * rs[ai][m] + cu;
;                     f32x4 p1, p2;
; #pragma unroll
;                     for (int e = 0; e < 4; ++e) {
;                         p1[e] = dppf<0x111>(dppf<0x121>(0.f, gprev[e]), g[e]);
;                         p2[e] = dppf<0x112>(dppf<0x122>(0.f, gprev[e]), g[e]);
;                     }
;                     const int blk = row >> 6;
;                     if (m == 0 && fr < 2) {
;                         const f32x4 pg = (fr == 0) ? (w2 * g + cbv) : (w1 * p1 + w2 * g + cbv);
;                         *(f32x4*)(headpg + ((size_t)blk * 2 + fr) * DFF + j) = pg;
;                         *(f32x4*)(headup + ((size_t)blk * 2 + fr) * DFF + j) = uu;
;                     } else {
;                         const f32x4 cv = w0 * p2 + w1 * p1 + w2 * g + cbv;
;                         u32x2 o; o.x = pk2(siluf_(cv[0]) * uu[0], siluf_(cv[1]) * uu[1]); o.y = pk2(siluf_(cv[2]) * uu[2], siluf_(cv[3]) * uu[3]);
;                         *(u32x2*)(H + (size_t)row * DFF + j) = o;
;                     }
;                     if (m == 3 && fr >= 14) *(f32x4*)(tailg + ((size_t)blk * 2 + (fr - 14)) * DFF + j) = g;
	v_pk_fma_f32 v[36:37], v[152:153], v[92:93], v[36:37] neg_lo:[1,0,0] neg_hi:[1,0,0]
	v_mul_f32_e32 v42, v43, v42
	v_cvt_pk_bf16_f32 v41, v41, v42
	flat_store_dwordx2 v[136:137], v[40:41] offset:8
	v_xor_b32_e32 v40, 0x80000000, v152
	v_pk_fma_f32 v[36:37], v[154:155], v[36:37], v[88:89]
	v_mov_b32_dpp v50, v44 row_ror:2 row_mask:0xf bank_mask:0xf
	v_mov_b32_dpp v51, v45 row_ror:2 row_mask:0xf bank_mask:0xf
	v_mov_b32_e32 v41, v40
	v_mov_b32_dpp v48, v44 row_ror:1 row_mask:0xf bank_mask:0xf
	v_mov_b32_dpp v50, v36 row_shr:2 row_mask:0xf bank_mask:0xf
	v_mov_b32_dpp v49, v45 row_ror:1 row_mask:0xf bank_mask:0xf
	v_mov_b32_dpp v51, v37 row_shr:2 row_mask:0xf bank_mask:0xf
	v_pk_fma_f32 v[38:39], v[40:41], v[94:95], v[38:39]
	v_mov_b32_e32 v42, v154
	v_mov_b32_e32 v43, v154
	v_mov_b32_dpp v48, v36 row_shr:1 row_mask:0xf bank_mask:0xf
	v_mov_b32_dpp v49, v37 row_shr:1 row_mask:0xf bank_mask:0xf
	v_pk_fma_f32 v[34:35], v[40:41], v[66:67], v[34:35]
	v_pk_mul_f32 v[40:41], v[76:77], v[50:51]
	v_pk_fma_f32 v[38:39], v[42:43], v[38:39], v[90:91]
	v_mov_b32_dpp v52, v46 row_ror:2 row_mask:0xf bank_mask:0xf
	v_mov_b32_dpp v53, v47 row_ror:2 row_mask:0xf bank_mask:0xf
	v_pk_fma_f32 v[40:41], v[80:81], v[48:49], v[40:41]
	v_mov_b32_dpp v44, v46 row_ror:1 row_mask:0xf bank_mask:0xf
	v_mov_b32_dpp v52, v38 row_shr:2 row_mask:0xf bank_mask:0xf
	v_mov_b32_dpp v45, v47 row_ror:1 row_mask:0xf bank_mask:0xf
	v_mov_b32_dpp v53, v39 row_shr:2 row_mask:0xf bank_mask:0xf
	v_pk_fma_f32 v[40:41], v[36:37], v[68:69], v[40:41]
	v_mov_b32_dpp v44, v38 row_shr:1 row_mask:0xf bank_mask:0xf
	v_mov_b32_dpp v45, v39 row_shr:1 row_mask:0xf bank_mask:0xf
	v_pk_fma_f32 v[34:35], v[42:43], v[34:35], v[74:75]
	v_pk_mul_f32 v[42:43], v[78:79], v[52:53]
	v_pk_add_f32 v[40:41], v[84:85], v[40:41]
	v_pk_fma_f32 v[42:43], v[82:83], v[44:45], v[42:43]
	v_mul_f32_e32 v44, 0xbfb8aa3b, v40
	v_exp_f32_e32 v44, v44
	v_mul_f32_e32 v45, 0xbfb8aa3b, v41
	v_exp_f32_e32 v45, v45
	v_pk_fma_f32 v[32:33], v[152:153], v[64:65], v[32:33] neg_lo:[1,0,0] neg_hi:[1,0,0]
	v_add_f32_e32 v44, 1.0, v44
	v_rcp_f32_e32 v44, v44
	v_add_f32_e32 v45, 1.0, v45
	v_rcp_f32_e32 v45, v45
	v_pk_fma_f32 v[42:43], v[38:39], v[70:71], v[42:43]
	v_pk_fma_f32 v[32:33], v[154:155], v[32:33], v[72:73]
	v_pk_add_f32 v[42:43], v[86:87], v[42:43]
	v_mul_f32_e32 v40, v40, v44
	v_mul_f32_e32 v32, v32, v40
	v_mul_f32_e32 v40, v41, v45
	v_mul_f32_e32 v41, 0xbfb8aa3b, v42
	v_exp_f32_e32 v41, v41
	v_mul_f32_e32 v44, 0xbfb8aa3b, v43
	v_exp_f32_e32 v44, v44
	v_mul_f32_e32 v33, v33, v40
	v_add_f32_e32 v40, 1.0, v41
	v_rcp_f32_e32 v40, v40
	v_add_f32_e32 v41, 1.0, v44
	v_rcp_f32_e32 v41, v41
	v_cvt_pk_bf16_f32 v32, v32, v33
	v_mul_f32_e32 v33, v42, v40
	v_mul_f32_e32 v33, v34, v33
	v_mul_f32_e32 v34, v43, v41
	v_mul_f32_e32 v34, v35, v34
	v_cvt_pk_bf16_f32 v33, v33, v34
	flat_store_dwordx2 v[148:149], v[32:33] offset:8
	s_and_saveexec_b64 s[48:49], s[6:7]
	s_cbranch_execz .LBB0_1433
	flat_store_dwordx4 v[146:147], v[36:39] offset:16
.LBB0_1433:
	s_or_b64 exec, exec, s[48:49]
	s_nop 0
	v_xor_b32_e32 v36, 0x80000000, v140
	v_mov_b32_e32 v37, v36
	v_mov_b32_e32 v141, v140
	v_pk_fma_f32 v[30:31], v[36:37], v[94:95], v[30:31]
	v_pk_fma_f32 v[26:27], v[36:37], v[66:67], v[26:27]
	v_mov_b32_e32 v139, v138
	v_pk_fma_f32 v[28:29], v[140:141], v[92:93], v[28:29] neg_lo:[1,0,0] neg_hi:[1,0,0]
	v_mov_b32_e32 v40, v138
	v_mov_b32_e32 v41, v138
	v_mov_b32_dpp v37, v37 row_ror:1 row_mask:0xf bank_mask:0xf
	v_mov_b32_dpp v39, v39 row_ror:2 row_mask:0xf bank_mask:0xf
	v_pk_fma_f32 v[34:35], v[138:139], v[28:29], v[88:89]
	v_pk_fma_f32 v[32:33], v[40:41], v[30:31], v[90:91]
	v_pk_fma_f32 v[24:25], v[140:141], v[64:65], v[24:25] neg_lo:[1,0,0] neg_hi:[1,0,0]
	v_mov_b32_e32 v28, v37
	v_mov_b32_e32 v30, v39
	v_mov_b32_e32 v29, v37
	v_mov_b32_e32 v31, v39
	v_mov_b32_e32 v36, v37
	v_mov_b32_e32 v38, v39
	v_mov_b32_dpp v28, v34 row_shr:1 row_mask:0xf bank_mask:0xf
	v_mov_b32_dpp v30, v34 row_shr:2 row_mask:0xf bank_mask:0xf
	v_mov_b32_dpp v29, v35 row_shr:1 row_mask:0xf bank_mask:0xf
	v_mov_b32_dpp v31, v35 row_shr:2 row_mask:0xf bank_mask:0xf
	v_mov_b32_dpp v36, v32 row_shr:1 row_mask:0xf bank_mask:0xf
	v_mov_b32_dpp v38, v32 row_shr:2 row_mask:0xf bank_mask:0xf
	v_mov_b32_dpp v37, v33 row_shr:1 row_mask:0xf bank_mask:0xf
	v_mov_b32_dpp v39, v33 row_shr:2 row_mask:0xf bank_mask:0xf
	v_pk_fma_f32 v[24:25], v[138:139], v[24:25], v[72:73]
	v_pk_fma_f32 v[26:27], v[40:41], v[26:27], v[74:75]
	s_and_saveexec_b64 s[30:31], s[2:3]
	s_xor_b64 s[48:49], exec, s[30:31]
	s_cbranch_execz .LBB0_1435
	v_pk_mul_f32 v[30:31], v[76:77], v[30:31]
	v_pk_mul_f32 v[38:39], v[78:79], v[38:39]
	v_pk_fma_f32 v[28:29], v[80:81], v[28:29], v[30:31]
	v_pk_fma_f32 v[36:37], v[82:83], v[36:37], v[38:39]
	v_pk_fma_f32 v[28:29], v[34:35], v[68:69], v[28:29]
	s_nop 0
	v_pk_add_f32 v[28:29], v[84:85], v[28:29]
	s_nop 0
	v_mul_f32_e32 v30, 0xbfb8aa3b, v28
	v_exp_f32_e32 v38, v30
	v_mul_f32_e32 v30, 0xbfb8aa3b, v29
	v_exp_f32_e32 v39, v30
	v_pk_fma_f32 v[30:31], v[32:33], v[70:71], v[36:37]
	v_add_f32_e32 v36, 1.0, v38
	v_rcp_f32_e32 v36, v36
	v_add_f32_e32 v37, 1.0, v39
	v_rcp_f32_e32 v37, v37
	v_pk_add_f32 v[30:31], v[86:87], v[30:31]
	v_mul_f32_e32 v28, v28, v36
	v_mul_f32_e32 v24, v24, v28
	v_mul_f32_e32 v28, v29, v37
	v_mul_f32_e32 v29, 0xbfb8aa3b, v30
	v_exp_f32_e32 v29, v29
	v_mul_f32_e32 v36, 0xbfb8aa3b, v31
	v_exp_f32_e32 v36, v36
	v_mul_f32_e32 v25, v25, v28
	v_add_f32_e32 v28, 1.0, v29
	v_rcp_f32_e32 v28, v28
	v_add_f32_e32 v29, 1.0, v36
	v_rcp_f32_e32 v29, v29
	v_cvt_pk_bf16_f32 v24, v24, v25
	v_mul_f32_e32 v25, v30, v28
	v_mul_f32_e32 v25, v26, v25
	v_mul_f32_e32 v26, v31, v29
	v_mul_f32_e32 v26, v27, v26
	v_cvt_pk_bf16_f32 v25, v25, v26
	v_mov_b64_e32 v[26:27], s[14:15]
	v_mad_i64_i32 v[26:27], s[30:31], v135, s57, v[26:27]
	v_lshl_add_u64 v[26:27], v[184:185], 1, v[26:27]
	flat_store_dwordx2 v[26:27], v[24:25] offset:8

; DEVI unsigned pk2(float lo, float hi) { unsigned r; asm("v_cvt_pk_bf16_f32 %0, %1, %2" : "=v"(r) : "v"(lo), "v"(hi)); return r; }
; DEVI float siluf_(float x) { return x * sigmoidf_(x); }
; template <int CTRL> DEVI float dppf(float old, float src) { return __int_as_float(__builtin_amdgcn_update_dpp(__float_as_int(old), __float_as_int(src), CTRL, 0xf, 0xf, false)); }
;     DEVI void operator()(const f32x4 (&acc)[2][2][4][2], const pg8::Unit& u, int wr, int wc, int fr, int fq) const {
;     ...
;                     const int row = u.pm * 256 + ai * 128 + wr * 64 + m * 16 + fr;
;                     const f32x4 g = (acc[ai][0][m][n] - mu[ai][m] * sg) * rs[ai][m] + cg_;
;                     const f32x4 uu = (acc[ai][1][m][n] - mu[ai][m] * su) * rs[ai][m] + cu;
;                     f32x4 p1, p2;
; #pragma unroll
;                     for (int e = 0; e < 4; ++e) {
;                         p1[e] = dppf<0x111>(dppf<0x121>(0.f, gprev[e]), g[e]);
;                         p2[e] = dppf<0x112>(dppf<0x122>(0.f, gprev[e]), g[e]);
;                     }
;                     const int blk = row >> 6;
;                     if (m == 0 && fr < 2) {
;                         const f32x4 pg = (fr == 0) ? (w2 * g + cbv) : (w1 * p1 + w2 * g + cbv);
;                         *(f32x4*)(headpg + ((size_t)blk * 2 + fr) * DFF + j) = pg;
;                         *(f32x4*)(headup + ((size_t)blk * 2 + fr) * DFF + j) = uu;
;                     } else {
;                         const f32x4 cv = w0 * p2 + w1 * p1 + w2 * g + cbv;
;                         u32x2 o; o.x = pk2(siluf_(cv[0]) * uu[0], siluf_(cv[1]) * uu[1]); o.y = pk2(siluf_(cv[2]) * uu[2], siluf_(cv[3]) * uu[3]);
;                         *(u32x2*)(H + (size_t)row * DFF + j) = o;
.LBB0_1437:
	s_or_b64 exec, exec, s[48:49]
	v_mov_b32_e32 v143, v142
	v_mov_b32_e32 v151, v150
	v_pk_fma_f32 v[20:21], v[142:143], v[92:93], v[20:21] neg_lo:[1,0,0] neg_hi:[1,0,0]
	v_xor_b32_e32 v24, 0x80000000, v142
	v_pk_fma_f32 v[20:21], v[150:151], v[20:21], v[88:89]
	v_mov_b32_dpp v30, v34 row_ror:2 row_mask:0xf bank_mask:0xf
	v_mov_b32_dpp v31, v35 row_ror:2 row_mask:0xf bank_mask:0xf
	v_mov_b32_e32 v25, v24
	v_mov_b32_dpp v28, v34 row_ror:1 row_mask:0xf bank_mask:0xf
	v_mov_b32_dpp v30, v20 row_shr:2 row_mask:0xf bank_mask:0xf
	v_mov_b32_dpp v29, v35 row_ror:1 row_mask:0xf bank_mask:0xf
	v_mov_b32_dpp v31, v21 row_shr:2 row_mask:0xf bank_mask:0xf
	v_pk_fma_f32 v[22:23], v[24:25], v[94:95], v[22:23]
	v_mov_b32_dpp v28, v20 row_shr:1 row_mask:0xf bank_mask:0xf
	v_mov_b32_dpp v29, v21 row_shr:1 row_mask:0xf bank_mask:0xf
	v_pk_fma_f32 v[18:19], v[24:25], v[66:67], v[18:19]
	v_pk_mul_f32 v[24:25], v[76:77], v[30:31]
	v_mov_b32_e32 v26, v150
	v_pk_fma_f32 v[24:25], v[80:81], v[28:29], v[24:25]
	v_mov_b32_e32 v27, v150
	v_pk_fma_f32 v[24:25], v[20:21], v[68:69], v[24:25]
	v_pk_add_f32 v[24:25], v[84:85], v[24:25]
	v_mul_f32_e32 v28, 0xbfb8aa3b, v24
	v_exp_f32_e32 v28, v28
	v_mul_f32_e32 v29, 0xbfb8aa3b, v25
	v_exp_f32_e32 v29, v29
	v_pk_fma_f32 v[22:23], v[26:27], v[22:23], v[90:91]
	v_mov_b32_dpp v36, v32 row_ror:2 row_mask:0xf bank_mask:0xf
	v_mov_b32_dpp v37, v33 row_ror:2 row_mask:0xf bank_mask:0xf
	v_add_f32_e32 v28, 1.0, v28
	v_mov_b32_dpp v34, v32 row_ror:1 row_mask:0xf bank_mask:0xf
	v_mov_b32_dpp v36, v22 row_shr:2 row_mask:0xf bank_mask:0xf
	v_mov_b32_dpp v35, v33 row_ror:1 row_mask:0xf bank_mask:0xf
	v_mov_b32_dpp v37, v23 row_shr:2 row_mask:0xf bank_mask:0xf
	v_rcp_f32_e32 v28, v28
	v_add_f32_e32 v29, 1.0, v29
	v_mov_b32_dpp v34, v22 row_shr:1 row_mask:0xf bank_mask:0xf
	v_mov_b32_dpp v35, v23 row_shr:1 row_mask:0xf bank_mask:0xf
	v_pk_fma_f32 v[18:19], v[26:27], v[18:19], v[74:75]
	v_pk_mul_f32 v[26:27], v[78:79], v[36:37]
	v_rcp_f32_e32 v29, v29
	v_pk_fma_f32 v[26:27], v[82:83], v[34:35], v[26:27]
	v_pk_fma_f32 v[16:17], v[142:143], v[64:65], v[16:17] neg_lo:[1,0,0] neg_hi:[1,0,0]
	v_pk_fma_f32 v[26:27], v[22:23], v[70:71], v[26:27]
	v_pk_fma_f32 v[16:17], v[150:151], v[16:17], v[72:73]
	v_pk_add_f32 v[26:27], v[86:87], v[26:27]
	v_mul_f32_e32 v24, v24, v28
	v_mul_f32_e32 v16, v16, v24
	v_mul_f32_e32 v24, v25, v29
	v_mul_f32_e32 v25, 0xbfb8aa3b, v26
	v_exp_f32_e32 v25, v25
	v_mul_f32_e32 v28, 0xbfb8aa3b, v27
	v_exp_f32_e32 v28, v28
	v_mul_f32_e32 v17, v17, v24
	v_add_f32_e32 v24, 1.0, v25
	v_rcp_f32_e32 v24, v24
	v_add_f32_e32 v25, 1.0, v28
	v_rcp_f32_e32 v25, v25
	v_mov_b32_e32 v133, v132
	v_cvt_pk_bf16_f32 v16, v16, v17
	v_mul_f32_e32 v17, v26, v24
	v_mov_b32_e32 v135, v134
	v_mul_f32_e32 v17, v18, v17
	v_mul_f32_e32 v18, v27, v25
	v_pk_fma_f32 v[12:13], v[132:133], v[92:93], v[12:13] neg_lo:[1,0,0] neg_hi:[1,0,0]
	v_mul_f32_e32 v18, v19, v18
	v_cvt_pk_bf16_f32 v17, v17, v18
	flat_store_dwordx2 v[204:205], v[16:17] offset:8
	v_xor_b32_e32 v16, 0x80000000, v132
	v_pk_fma_f32 v[12:13], v[134:135], v[12:13], v[88:89]
	v_mov_b32_dpp v26, v20 row_ror:2 row_mask:0xf bank_mask:0xf
	v_mov_b32_dpp v27, v21 row_ror:2 row_mask:0xf bank_mask:0xf
	v_mov_b32_e32 v17, v16
	v_mov_b32_dpp v24, v20 row_ror:1 row_mask:0xf bank_mask:0xf
	v_mov_b32_dpp v26, v12 row_shr:2 row_mask:0xf bank_mask:0xf
	v_mov_b32_dpp v25, v21 row_ror:1 row_mask:0xf bank_mask:0xf
	v_mov_b32_dpp v27, v13 row_shr:2 row_mask:0xf bank_mask:0xf
	v_pk_fma_f32 v[14:15], v[16:17], v[94:95], v[14:15]
	v_mov_b32_e32 v18, v134
	v_mov_b32_e32 v19, v134
	v_mov_b32_dpp v24, v12 row_shr:1 row_mask:0xf bank_mask:0xf
	v_mov_b32_dpp v25, v13 row_shr:1 row_mask:0xf bank_mask:0xf
	v_pk_fma_f32 v[10:11], v[16:17], v[66:67], v[10:11]
	v_pk_mul_f32 v[16:17], v[76:77], v[26:27]
	v_pk_fma_f32 v[14:15], v[18:19], v[14:15], v[90:91]
	v_mov_b32_dpp v28, v22 row_ror:2 row_mask:0xf bank_mask:0xf
	v_mov_b32_dpp v29, v23 row_ror:2 row_mask:0xf bank_mask:0xf
	v_pk_fma_f32 v[16:17], v[80:81], v[24:25], v[16:17]
	v_mov_b32_dpp v20, v22 row_ror:1 row_mask:0xf bank_mask:0xf
	v_mov_b32_dpp v28, v14 row_shr:2 row_mask:0xf bank_mask:0xf
	v_mov_b32_dpp v21, v23 row_ror:1 row_mask:0xf bank_mask:0xf
; DEVI unsigned pk2(float lo, float hi) { unsigned r; asm("v_cvt_pk_bf16_f32 %0, %1, %2" : "=v"(r) : "v"(lo), "v"(hi)); return r; }
; DEVI float siluf_(float x) { return x * sigmoidf_(x); }
; template <int CTRL> DEVI float dppf(float old, float src) { return __int_as_float(__builtin_amdgcn_update_dpp(__float_as_int(old), __float_as_int(src), CTRL, 0xf, 0xf, false)); }
;     DEVI void operator()(const f32x4 (&acc)[2][2][4][2], const pg8::Unit& u, int wr, int wc, int fr, int fq) const {
;     ...
;                     const int row = u.pm * 256 + ai * 128 + wr * 64 + m * 16 + fr;
;                     const f32x4 g = (acc[ai][0][m][n] - mu[ai][m] * sg) * rs[ai][m] + cg_;
;                     const f32x4 uu = (acc[ai][1][m][n] - mu[ai][m] * su) * rs[ai][m] + cu;
;                     f32x4 p1, p2;
; #pragma unroll
;                     for (int e = 0; e < 4; ++e) {
;                         p1[e] = dppf<0x111>(dppf<0x121>(0.f, gprev[e]), g[e]);
;                         p2[e] = dppf<0x112>(dppf<0x122>(0.f, gprev[e]), g[e]);
;                     }
;                     const int blk = row >> 6;
;                     if (m == 0 && fr < 2) {
;                         const f32x4 pg = (fr == 0) ? (w2 * g + cbv) : (w1 * p1 + w2 * g + cbv);
;                         *(f32x4*)(headpg + ((size_t)blk * 2 + fr) * DFF + j) = pg;
;                         *(f32x4*)(headup + ((size_t)blk * 2 + fr) * DFF + j) = uu;
;                     } else {
;                         const f32x4 cv = w0 * p2 + w1 * p1 + w2 * g + cbv;
;                         u32x2 o; o.x = pk2(siluf_(cv[0]) * uu[0], siluf_(cv[1]) * uu[1]); o.y = pk2(siluf_(cv[2]) * uu[2], siluf_(cv[3]) * uu[3]);
;                         *(u32x2*)(H + (size_t)row * DFF + j) = o;
;                     }
;                     if (m == 3 && fr >= 14) *(f32x4*)(tailg + ((size_t)blk * 2 + (fr - 14)) * DFF + j) = g;
	v_mov_b32_dpp v29, v15 row_shr:2 row_mask:0xf bank_mask:0xf
	v_pk_fma_f32 v[16:17], v[12:13], v[68:69], v[16:17]
	v_mov_b32_dpp v20, v14 row_shr:1 row_mask:0xf bank_mask:0xf
	v_mov_b32_dpp v21, v15 row_shr:1 row_mask:0xf bank_mask:0xf
	v_pk_fma_f32 v[10:11], v[18:19], v[10:11], v[74:75]
	v_pk_mul_f32 v[18:19], v[78:79], v[28:29]
	v_pk_add_f32 v[16:17], v[84:85], v[16:17]
	v_pk_fma_f32 v[18:19], v[82:83], v[20:21], v[18:19]
	v_mul_f32_e32 v20, 0xbfb8aa3b, v16
	v_exp_f32_e32 v20, v20
	v_mul_f32_e32 v21, 0xbfb8aa3b, v17
	v_exp_f32_e32 v21, v21
	v_pk_fma_f32 v[8:9], v[132:133], v[64:65], v[8:9] neg_lo:[1,0,0] neg_hi:[1,0,0]
	v_add_f32_e32 v20, 1.0, v20
	v_rcp_f32_e32 v20, v20
	v_add_f32_e32 v21, 1.0, v21
	v_rcp_f32_e32 v21, v21
	v_pk_fma_f32 v[18:19], v[14:15], v[70:71], v[18:19]
	v_pk_fma_f32 v[8:9], v[134:135], v[8:9], v[72:73]
	v_pk_add_f32 v[18:19], v[86:87], v[18:19]
	v_mul_f32_e32 v16, v16, v20
	v_mul_f32_e32 v8, v8, v16
	v_mul_f32_e32 v16, v17, v21
	v_mul_f32_e32 v17, 0xbfb8aa3b, v18
	v_exp_f32_e32 v17, v17
	v_mul_f32_e32 v20, 0xbfb8aa3b, v19
	v_exp_f32_e32 v20, v20
	v_mul_f32_e32 v9, v9, v16
	v_add_f32_e32 v16, 1.0, v17
	v_rcp_f32_e32 v16, v16
	v_add_f32_e32 v17, 1.0, v20
	v_rcp_f32_e32 v17, v17
	v_mov_b32_e32 v129, v128
	v_cvt_pk_bf16_f32 v8, v8, v9
	v_mul_f32_e32 v9, v18, v16
	v_mov_b32_e32 v131, v130
	v_mul_f32_e32 v9, v10, v9
	v_mul_f32_e32 v10, v19, v17
	v_pk_fma_f32 v[4:5], v[128:129], v[92:93], v[4:5] neg_lo:[1,0,0] neg_hi:[1,0,0]
	v_mul_f32_e32 v10, v11, v10
	v_cvt_pk_bf16_f32 v9, v9, v10
	flat_store_dwordx2 v[206:207], v[8:9] offset:8
	v_xor_b32_e32 v8, 0x80000000, v128
	v_pk_fma_f32 v[4:5], v[130:131], v[4:5], v[88:89]
	v_mov_b32_dpp v18, v12 row_ror:2 row_mask:0xf bank_mask:0xf
	v_mov_b32_dpp v19, v13 row_ror:2 row_mask:0xf bank_mask:0xf
	v_mov_b32_e32 v9, v8
	v_mov_b32_dpp v16, v12 row_ror:1 row_mask:0xf bank_mask:0xf
	v_mov_b32_dpp v18, v4 row_shr:2 row_mask:0xf bank_mask:0xf
	v_mov_b32_dpp v17, v13 row_ror:1 row_mask:0xf bank_mask:0xf
	v_mov_b32_dpp v19, v5 row_shr:2 row_mask:0xf bank_mask:0xf
	v_pk_fma_f32 v[6:7], v[8:9], v[94:95], v[6:7]
	v_mov_b32_e32 v10, v130
	v_mov_b32_e32 v11, v130
	v_mov_b32_dpp v16, v4 row_shr:1 row_mask:0xf bank_mask:0xf
	v_mov_b32_dpp v17, v5 row_shr:1 row_mask:0xf bank_mask:0xf
	v_pk_fma_f32 v[2:3], v[8:9], v[66:67], v[2:3]
	v_pk_mul_f32 v[8:9], v[76:77], v[18:19]
	v_pk_fma_f32 v[6:7], v[10:11], v[6:7], v[90:91]
	v_mov_b32_dpp v20, v14 row_ror:2 row_mask:0xf bank_mask:0xf
	v_mov_b32_dpp v21, v15 row_ror:2 row_mask:0xf bank_mask:0xf
	v_pk_fma_f32 v[8:9], v[80:81], v[16:17], v[8:9]
	v_mov_b32_dpp v12, v14 row_ror:1 row_mask:0xf bank_mask:0xf
	v_mov_b32_dpp v20, v6 row_shr:2 row_mask:0xf bank_mask:0xf
	v_mov_b32_dpp v13, v15 row_ror:1 row_mask:0xf bank_mask:0xf
	v_mov_b32_dpp v21, v7 row_shr:2 row_mask:0xf bank_mask:0xf
	v_pk_fma_f32 v[8:9], v[4:5], v[68:69], v[8:9]
	v_mov_b32_dpp v12, v6 row_shr:1 row_mask:0xf bank_mask:0xf
	v_mov_b32_dpp v13, v7 row_shr:1 row_mask:0xf bank_mask:0xf
	v_pk_fma_f32 v[2:3], v[10:11], v[2:3], v[74:75]
	v_pk_mul_f32 v[10:11], v[78:79], v[20:21]
	v_pk_add_f32 v[8:9], v[84:85], v[8:9]
	v_pk_fma_f32 v[10:11], v[82:83], v[12:13], v[10:11]
	v_mul_f32_e32 v12, 0xbfb8aa3b, v8
	v_exp_f32_e32 v12, v12
	v_mul_f32_e32 v13, 0xbfb8aa3b, v9
	v_exp_f32_e32 v13, v13
	v_pk_fma_f32 v[0:1], v[128:129], v[64:65], v[0:1] neg_lo:[1,0,0] neg_hi:[1,0,0]
	v_add_f32_e32 v12, 1.0, v12
	v_rcp_f32_e32 v12, v12
	v_add_f32_e32 v13, 1.0, v13
	v_rcp_f32_e32 v13, v13
	v_pk_fma_f32 v[10:11], v[6:7], v[70:71], v[10:11]
	v_pk_fma_f32 v[0:1], v[130:131], v[0:1], v[72:73]
	v_pk_add_f32 v[10:11], v[86:87], v[10:11]
	v_mul_f32_e32 v8, v8, v12
	v_mul_f32_e32 v0, v0, v8
	v_mul_f32_e32 v8, v9, v13
	v_mul_f32_e32 v9, 0xbfb8aa3b, v10
	v_exp_f32_e32 v9, v9
	v_mul_f32_e32 v12, 0xbfb8aa3b, v11
	v_exp_f32_e32 v12, v12
	v_mul_f32_e32 v1, v1, v8
	v_add_f32_e32 v8, 1.0, v9
	v_rcp_f32_e32 v8, v8
	v_add_f32_e32 v9, 1.0, v12
	v_rcp_f32_e32 v9, v9
	v_cvt_pk_bf16_f32 v0, v0, v1
	v_mul_f32_e32 v1, v10, v8
	v_mul_f32_e32 v1, v2, v1
	v_mul_f32_e32 v2, v11, v9
	v_mul_f32_e32 v2, v3, v2
	v_cvt_pk_bf16_f32 v1, v1, v2
	flat_store_dwordx2 v[98:99], v[0:1] offset:8
	s_and_saveexec_b64 s[48:49], s[6:7]
	s_cbranch_execz .LBB0_1439
	flat_store_dwordx4 v[96:97], v[4:7] offset:16

; template <int CTRL> DEVI float dppf(float old, float src) { return __int_as_float(__builtin_amdgcn_update_dpp(__float_as_int(old), __float_as_int(src), CTRL, 0xf, 0xf, false)); }
; DEVI void row_stats(const float* stats, int row, float& mu, float& rs) {
;     if (stats) { const float2 st = *(const float2*)(stats + 2 * (size_t)row); mu = st.x * (1.0f / 1024.0f); const float var = st.y * (1.0f / 1024.0f) - mu * mu; rs = rsqrtf(fmaxf(var, 0.f) + LN_EPS); }
;     DEVI void operator()(const f32x4 (&acc)[2][2][4][2], const pg8::Unit& u, int wr, int wc, int fr, int fq) const {
;         float mu[2][4], rs[2][4];
; #pragma unroll
;         for (int ai = 0; ai < 2; ++ai)
; #pragma unroll
;             for (int m = 0; m < 4; ++m) row_stats(stats, u.pm * 256 + ai * 128 + wr * 64 + m * 16 + fr, mu[ai][m], rs[ai][m]);
; #pragma unroll
;         for (int n = 0; n < 2; ++n) {
;             const int tc = u.pn * 256 + wc * 32 + 8 * fq + 4 * n;
;             const int j = u.pn * 128 + wc * 32 + 8 * fq + 4 * n;
;             const f32x4 sg = *(const f32x4*)(s + tc), cg_ = *(const f32x4*)(c + tc), su = *(const f32x4*)(s + tc + 128), cu = *(const f32x4*)(c + tc + 128);
;             const f32x4 w0 = *(const f32x4*)(cw + j), w1 = *(const f32x4*)(cw + DFF + j), w2 = *(const f32x4*)(cw + 2 * DFF + j), cbv = *(const f32x4*)(cb + j);
; #pragma unroll
;             for (int ai = 0; ai < 2; ++ai) {
;                 f32x4 gprev = (f32x4){0.f, 0.f, 0.f, 0.f};
; #pragma unroll
;                 for (int m = 0; m < 4; ++m) {
;                     const int row = u.pm * 256 + ai * 128 + wr * 64 + m * 16 + fr;
;                     const f32x4 g = (acc[ai][0][m][n] - mu[ai][m] * sg) * rs[ai][m] + cg_;
;                     const f32x4 uu = (acc[ai][1][m][n] - mu[ai][m] * su) * rs[ai][m] + cu;
;                     f32x4 p1, p2;
; #pragma unroll
;                     for (int e = 0; e < 4; ++e) {
;                         p1[e] = dppf<0x111>(dppf<0x121>(0.f, gprev[e]), g[e]);
;                         p2[e] = dppf<0x112>(dppf<0x122>(0.f, gprev[e]), g[e]);
;                     }
;                     const int blk = row >> 6;
;                     if (m == 0 && fr < 2) {
;                         const f32x4 pg = (fr == 0) ? (w2 * g + cbv) : (w1 * p1 + w2 * g + cbv);
.LBB0_2722:
	s_lshl_b32 s50, s10, 8
	s_add_i32 s50, s50, s74
	v_or_b32_e32 v188, s50, v172
	v_ashrrev_i32_e32 v189, 31, v188
	v_or_b32_e32 v198, 16, v188
	v_or_b32_e32 v196, 32, v188
	v_or_b32_e32 v208, 48, v188
	v_lshl_add_u64 v[112:113], v[188:189], 3, s[16:17]
	v_ashrrev_i32_e32 v199, 31, v198
	v_ashrrev_i32_e32 v197, 31, v196
	v_ashrrev_i32_e32 v209, 31, v208
	v_lshl_add_u64 v[114:115], v[198:199], 3, s[16:17]
	v_lshl_add_u64 v[116:117], v[196:197], 3, s[16:17]
	v_lshl_add_u64 v[118:119], v[208:209], 3, s[16:17]
	s_waitcnt vmcnt(0)
	flat_load_dwordx2 v[190:191], v[112:113]
	flat_load_dwordx2 v[218:219], v[114:115]
	flat_load_dwordx2 v[216:217], v[116:117]
	flat_load_dwordx2 v[214:215], v[118:119]
	v_add_u32_e32 v112, 0x80, v188
	v_ashrrev_i32_e32 v113, 31, v112
	v_lshl_add_u64 v[160:161], v[112:113], 3, s[16:17]
	v_add_u32_e32 v112, 0x90, v188
	v_ashrrev_i32_e32 v113, 31, v112
	v_lshl_add_u64 v[162:163], v[112:113], 3, s[16:17]
	v_add_u32_e32 v112, 0xa0, v188
	v_lshl_or_b32 v194, s0, 8, v226
	v_ashrrev_i32_e32 v113, 31, v112
	v_ashrrev_i32_e32 v195, 31, v194
	v_lshl_add_u64 v[192:193], v[112:113], 3, s[16:17]
	v_add_u32_e32 v112, 0xb0, v188
	v_lshl_or_b32 v184, s0, 7, v226
	v_lshlrev_b64 v[114:115], 2, v[194:195]
	v_ashrrev_i32_e32 v113, 31, v112
	v_ashrrev_i32_e32 v185, 31, v184
	v_lshl_add_u64 v[116:117], s[20:21], 0, v[114:115]
	v_lshl_add_u64 v[200:201], v[112:113], 3, s[16:17]
	v_lshl_add_u64 v[112:113], s[22:23], 0, v[114:115]
	v_lshlrev_b64 v[186:187], 2, v[184:185]
	flat_load_dwordx4 v[140:143], v[116:117]
	flat_load_dwordx4 v[124:127], v[116:117] offset:512
	flat_load_dwordx4 v[144:147], v[112:113]
	flat_load_dwordx4 v[128:131], v[112:113] offset:512
	v_lshl_add_u64 v[112:113], s[12:13], 0, v[186:187]
	v_lshl_add_u64 v[114:115], s[38:39], 0, v[186:187]
	global_load_dwordx4 v[136:139], v[112:113], off
	global_load_dwordx4 v[120:123], v[114:115], off
	v_lshl_add_u64 v[112:113], s[40:41], 0, v[186:187]
	global_load_dwordx4 v[116:119], v[112:113], off
	v_lshl_add_u64 v[112:113], s[24:25], 0, v[186:187]
	global_load_dwordx4 v[112:115], v[112:113], off
	s_nop 0
	flat_load_dwordx2 v[210:211], v[160:161]
	flat_load_dwordx2 v[212:213], v[162:163]
	flat_load_dwordx2 v[206:207], v[192:193]
	flat_load_dwordx2 v[204:205], v[200:201]
	s_waitcnt vmcnt(0) lgkmcnt(0)
	v_pk_mul_f32 v[192:193], v[190:191], s[42:43] op_sel_hi:[1,0]
	s_nop 0
	v_fma_f32 v189, -v192, v192, v193
	v_max_f32_e32 v189, 0, v189
	v_add_f32_e32 v189, 0x3727c5ac, v189
	v_mul_f32_e32 v190, 0x4b800000, v189
	v_cmp_gt_f32_e32 vcc, s81, v189
	v_mov_b32_dpp v225, v225 row_ror:1 row_mask:0xf bank_mask:0xf
	v_mov_b32_dpp v163, v163 row_ror:2 row_mask:0xf bank_mask:0xf
	v_cndmask_b32_e32 v189, v189, v190, vcc
	v_rsq_f32_e32 v189, v189
	v_mov_b32_e32 v160, v225
	v_mov_b32_e32 v200, v163
	v_mov_b32_e32 v161, v225
	v_mul_f32_e32 v190, 0x45800000, v189
	v_cndmask_b32_e32 v190, v189, v190, vcc
	v_mov_b32_e32 v201, v163
	v_mov_b32_e32 v224, v225
	v_mov_b32_e32 v162, v163
	v_pk_fma_f32 v[154:155], v[192:193], v[126:127], v[154:155] op_sel_hi:[0,1,1] neg_lo:[1,0,0] neg_hi:[1,0,0]
	v_pk_fma_f32 v[158:159], v[192:193], v[142:143], v[158:159] op_sel_hi:[0,1,1] neg_lo:[1,0,0] neg_hi:[1,0,0]
	v_pk_fma_f32 v[156:157], v[192:193], v[140:141], v[156:157] op_sel_hi:[0,1,1] neg_lo:[1,0,0] neg_hi:[1,0,0]
	v_pk_fma_f32 v[152:153], v[192:193], v[124:125], v[152:153] op_sel_hi:[0,1,1] neg_lo:[1,0,0] neg_hi:[1,0,0]
	v_pk_fma_f32 v[220:221], v[190:191], v[158:159], v[146:147] op_sel_hi:[0,1,1]
	v_pk_fma_f32 v[222:223], v[190:191], v[156:157], v[144:145] op_sel_hi:[0,1,1]
	v_pk_fma_f32 v[154:155], v[190:191], v[154:155], v[130:131] op_sel_hi:[0,1,1]
	v_mov_b32_dpp v224, v220 row_shr:1 row_mask:0xf bank_mask:0xf
	v_mov_b32_dpp v160, v222 row_shr:1 row_mask:0xf bank_mask:0xf
	v_mov_b32_dpp v200, v222 row_shr:2 row_mask:0xf bank_mask:0xf
	v_mov_b32_dpp v161, v223 row_shr:1 row_mask:0xf bank_mask:0xf
	v_mov_b32_dpp v201, v223 row_shr:2 row_mask:0xf bank_mask:0xf
	v_mov_b32_dpp v162, v220 row_shr:2 row_mask:0xf bank_mask:0xf
	v_mov_b32_dpp v225, v221 row_shr:1 row_mask:0xf bank_mask:0xf
	v_mov_b32_dpp v163, v221 row_shr:2 row_mask:0xf bank_mask:0xf
	v_pk_fma_f32 v[152:153], v[190:191], v[152:153], v[128:129] op_sel_hi:[0,1,1]
	s_and_saveexec_b64 s[0:1], s[2:3]
	s_xor_b64 s[0:1], exec, s[0:1]
	s_cbranch_execz .LBB0_2724
	v_pk_mul_f32 v[158:159], v[136:137], v[200:201]
	v_pk_mul_f32 v[156:157], v[138:139], v[162:163]
	v_pk_fma_f32 v[158:159], v[120:121], v[160:161], v[158:159]
	v_pk_fma_f32 v[156:157], v[122:123], v[224:225], v[156:157]
	v_pk_fma_f32 v[158:159], v[222:223], v[116:117], v[158:159]
	v_pk_fma_f32 v[156:157], v[220:221], v[118:119], v[156:157]
	v_pk_add_f32 v[158:159], v[112:113], v[158:159]
	v_pk_add_f32 v[156:157], v[114:115], v[156:157]
	v_mul_f32_e32 v160, 0xbfb8aa3b, v158
	v_exp_f32_e32 v160, v160
	v_mul_f32_e32 v161, 0xbfb8aa3b, v159
	v_exp_f32_e32 v161, v161
	v_add_f32_e32 v160, 1.0, v160
	v_rcp_f32_e32 v160, v160
	v_add_f32_e32 v161, 1.0, v161
	v_rcp_f32_e32 v161, v161
	v_mul_f32_e32 v158, v158, v160
	v_mul_f32_e32 v152, v152, v158
	v_mul_f32_e32 v158, v159, v161
	v_mul_f32_e32 v159, 0xbfb8aa3b, v156
	v_exp_f32_e32 v159, v159
	v_mul_f32_e32 v160, 0xbfb8aa3b, v157
	v_exp_f32_e32 v160, v160
	v_mul_f32_e32 v153, v153, v158
	v_add_f32_e32 v158, 1.0, v159
	v_rcp_f32_e32 v158, v158
	v_add_f32_e32 v159, 1.0, v160
	v_rcp_f32_e32 v159, v159
	v_cvt_pk_bf16_f32 v152, v152, v153
	v_mul_f32_e32 v153, v156, v158
	v_mul_f32_e32 v153, v154, v153
	v_mul_f32_e32 v154, v157, v159
	v_mul_f32_e32 v154, v155, v154
	v_cvt_pk_bf16_f32 v153, v153, v154
	v_mov_b64_e32 v[154:155], s[18:19]
	v_mad_i64_i32 v[154:155], s[10:11], v188, s83, v[154:155]
	v_lshl_add_u64 v[154:155], v[184:185], 1, v[154:155]
	flat_store_dwordx2 v[154:155], v[152:153]

; DEVI unsigned pk2(float lo, float hi) { unsigned r; asm("v_cvt_pk_bf16_f32 %0, %1, %2" : "=v"(r) : "v"(lo), "v"(hi)); return r; }
; DEVI float siluf_(float x) { return x * sigmoidf_(x); }
;     DEVI void operator()(const f32x4 (&acc)[2][2][4][2], const pg8::Unit& u, int wr, int wc, int fr, int fq) const {
;     ...
;             for (int m = 0; m < 4; ++m) row_stats(stats, u.pm * 256 + ai * 128 + wr * 64 + m * 16 + fr, mu[ai][m], rs[ai][m]);
; #pragma unroll
;         for (int n = 0; n < 2; ++n) {
;             const int tc = u.pn * 256 + wc * 32 + 8 * fq + 4 * n;
;             const int j = u.pn * 128 + wc * 32 + 8 * fq + 4 * n;
;             const f32x4 sg = *(const f32x4*)(s + tc), cg_ = *(const f32x4*)(c + tc), su = *(const f32x4*)(s + tc + 128), cu = *(const f32x4*)(c + tc + 128);
;             const f32x4 w0 = *(const f32x4*)(cw + j), w1 = *(const f32x4*)(cw + DFF + j), w2 = *(const f32x4*)(cw + 2 * DFF + j), cbv = *(const f32x4*)(cb + j);
; #pragma unroll
;             for (int ai = 0; ai < 2; ++ai) {
;                 f32x4 gprev = (f32x4){0.f, 0.f, 0.f, 0.f};
; #pragma unroll
;                 for (int m = 0; m < 4; ++m) {
;                     const int row = u.pm * 256 + ai * 128 + wr * 64 + m * 16 + fr;
;                     const f32x4 g = (acc[ai][0][m][n] - mu[ai][m] * sg) * rs[ai][m] + cg_;
;                     const f32x4 uu = (acc[ai][1][m][n] - mu[ai][m] * su) * rs[ai][m] + cu;
;                     f32x4 p1, p2;
; #pragma unroll
;                     for (int e = 0; e < 4; ++e) {
;                         p1[e] = dppf<0x111>(dppf<0x121>(0.f, gprev[e]), g[e]);
;                         p2[e] = dppf<0x112>(dppf<0x122>(0.f, gprev[e]), g[e]);
;                     }
;                     const int blk = row >> 6;
;                     if (m == 0 && fr < 2) {
;                         const f32x4 pg = (fr == 0) ? (w2 * g + cbv) : (w1 * p1 + w2 * g + cbv);
;                         *(f32x4*)(headpg + ((size_t)blk * 2 + fr) * DFF + j) = pg;
;                         *(f32x4*)(headup + ((size_t)blk * 2 + fr) * DFF + j) = uu;
;                     } else {
;                         const f32x4 cv = w0 * p2 + w1 * p1 + w2 * g + cbv;
;                         u32x2 o; o.x = pk2(siluf_(cv[0]) * uu[0], siluf_(cv[1]) * uu[1]); o.y = pk2(siluf_(cv[2]) * uu[2], siluf_(cv[3]) * uu[3]);
;                         *(u32x2*)(H + (size_t)row * DFF + j) = o;
.LBB0_2726:
	s_or_b64 exec, exec, s[0:1]
	v_pk_mul_f32 v[160:161], v[218:219], s[42:43] op_sel_hi:[1,0]
	v_pk_mul_f32 v[156:157], v[216:217], s[42:43] op_sel_hi:[1,0]
	v_fma_f32 v152, -v160, v160, v161
	v_max_f32_e32 v152, 0, v152
	v_add_f32_e32 v152, 0x3727c5ac, v152
	v_mul_f32_e32 v153, 0x4b800000, v152
	v_cmp_gt_f32_e32 vcc, s81, v152
	v_pk_fma_f32 v[148:149], v[160:161], v[140:141], v[148:149] op_sel_hi:[0,1,1] neg_lo:[1,0,0] neg_hi:[1,0,0]
	v_mov_b32_e32 v218, 0
	v_cndmask_b32_e32 v152, v152, v153, vcc
	v_rsq_f32_e32 v154, v152
	v_fma_f32 v152, -v156, v156, v157
	v_max_f32_e32 v152, 0, v152
	v_add_f32_e32 v152, 0x3727c5ac, v152
	v_mul_f32_e32 v153, 0x4b800000, v152
	v_cmp_gt_f32_e64 s[0:1], s81, v152
	v_mul_f32_e32 v155, 0x45800000, v154
	v_mov_b32_e32 v219, 0
	v_cndmask_b32_e64 v152, v152, v153, s[0:1]
	v_rsq_f32_e32 v158, v152
	v_pk_mul_f32 v[152:153], v[214:215], s[42:43] op_sel_hi:[1,0]
	v_lshl_add_u64 v[214:215], s[48:49], 0, v[174:175]
	v_fma_f32 v159, -v152, v152, v153
	v_max_f32_e32 v159, 0, v159
	v_add_f32_e32 v159, 0x3727c5ac, v159
	v_mul_f32_e32 v162, 0x4b800000, v159
	v_cmp_gt_f32_e64 s[10:11], s81, v159
	v_mov_b32_dpp v218, v222 row_ror:2 row_mask:0xf bank_mask:0xf
	v_mov_b32_dpp v219, v223 row_ror:2 row_mask:0xf bank_mask:0xf
	v_cndmask_b32_e64 v159, v159, v162, s[10:11]
	v_cndmask_b32_e32 v162, v154, v155, vcc
	v_mul_f32_e32 v154, 0x45800000, v158
	v_cndmask_b32_e64 v158, v158, v154, s[0:1]
	v_mad_u64_u32 v[216:217], s[0:1], v214, s84, 0
	v_mad_i32_i24 v217, v215, s84, v217
	v_pk_fma_f32 v[148:149], v[162:163], v[148:149], v[144:145] op_sel_hi:[0,1,1]
	v_mov_b32_e32 v214, 0
	v_mov_b32_e32 v215, 0
	v_mov_b32_dpp v218, v148 row_shr:2 row_mask:0xf bank_mask:0xf
	v_mov_b32_dpp v214, v222 row_ror:1 row_mask:0xf bank_mask:0xf
	v_mov_b32_dpp v215, v223 row_ror:1 row_mask:0xf bank_mask:0xf
	v_mov_b32_dpp v219, v149 row_shr:2 row_mask:0xf bank_mask:0xf
	v_rsq_f32_e32 v159, v159
	v_mov_b32_dpp v214, v148 row_shr:1 row_mask:0xf bank_mask:0xf
	v_mov_b32_dpp v215, v149 row_shr:1 row_mask:0xf bank_mask:0xf
	v_pk_mul_f32 v[218:219], v[136:137], v[218:219]
	v_mul_f32_e32 v154, 0x45800000, v159
	v_pk_fma_f32 v[214:215], v[120:121], v[214:215], v[218:219]
	v_cndmask_b32_e64 v154, v159, v154, s[10:11]
	v_pk_fma_f32 v[214:215], v[148:149], v[116:117], v[214:215]
	v_pk_fma_f32 v[150:151], v[160:161], v[142:143], v[150:151] op_sel_hi:[0,1,1] neg_lo:[1,0,0] neg_hi:[1,0,0]
	v_pk_add_f32 v[214:215], v[112:113], v[214:215]
	v_mul_f32_e32 v155, 0xbfb8aa3b, v214
	v_exp_f32_e32 v155, v155
	v_mul_f32_e32 v159, 0xbfb8aa3b, v215
	v_exp_f32_e32 v159, v159
	v_pk_fma_f32 v[150:151], v[162:163], v[150:151], v[146:147] op_sel_hi:[0,1,1]
	v_mov_b32_dpp v224, v220 row_ror:2 row_mask:0xf bank_mask:0xf
	v_mov_b32_dpp v225, v221 row_ror:2 row_mask:0xf bank_mask:0xf
	v_add_f32_e32 v155, 1.0, v155
	v_mov_b32_dpp v222, v220 row_ror:1 row_mask:0xf bank_mask:0xf
	v_mov_b32_dpp v224, v150 row_shr:2 row_mask:0xf bank_mask:0xf
	v_mov_b32_dpp v223, v221 row_ror:1 row_mask:0xf bank_mask:0xf
	v_mov_b32_dpp v225, v151 row_shr:2 row_mask:0xf bank_mask:0xf
	v_rcp_f32_e32 v155, v155
	v_add_f32_e32 v159, 1.0, v159
	v_mov_b32_dpp v222, v150 row_shr:1 row_mask:0xf bank_mask:0xf
	v_mov_b32_dpp v223, v151 row_shr:1 row_mask:0xf bank_mask:0xf
	v_pk_mul_f32 v[220:221], v[138:139], v[224:225]
	v_rcp_f32_e32 v159, v159
	v_pk_fma_f32 v[220:221], v[122:123], v[222:223], v[220:221]
	v_pk_fma_f32 v[132:133], v[160:161], v[124:125], v[132:133] op_sel_hi:[0,1,1] neg_lo:[1,0,0] neg_hi:[1,0,0]
	v_pk_fma_f32 v[218:219], v[150:151], v[118:119], v[220:221]
	v_pk_fma_f32 v[132:133], v[162:163], v[132:133], v[128:129] op_sel_hi:[0,1,1]
	v_pk_add_f32 v[218:219], v[114:115], v[218:219]
	v_mul_f32_e32 v155, v214, v155
	v_mul_f32_e32 v132, v132, v155
	v_mul_f32_e32 v155, v215, v159
	v_mul_f32_e32 v159, 0xbfb8aa3b, v218
	v_pk_fma_f32 v[134:135], v[160:161], v[126:127], v[134:135] op_sel_hi:[0,1,1] neg_lo:[1,0,0] neg_hi:[1,0,0]
	v_exp_f32_e32 v159, v159
	v_mul_f32_e32 v161, 0xbfb8aa3b, v219
	v_exp_f32_e32 v161, v161
	v_mul_f32_e32 v133, v133, v155
	v_add_f32_e32 v155, 1.0, v159
	v_rcp_f32_e32 v155, v155
	v_add_f32_e32 v159, 1.0, v161
	v_rcp_f32_e32 v159, v159
	v_pk_fma_f32 v[134:135], v[162:163], v[134:135], v[130:131] op_sel_hi:[0,1,1]
	v_cvt_pk_bf16_f32 v132, v132, v133
	v_mul_f32_e32 v133, v218, v155
	v_mul_f32_e32 v133, v134, v133
	v_mul_f32_e32 v134, v219, v159
	v_mul_f32_e32 v134, v135, v134
	v_cvt_pk_bf16_f32 v133, v133, v134
	v_mov_b64_e32 v[134:135], s[18:19]
	v_mad_i64_i32 v[198:199], s[0:1], v198, s83, v[134:135]
	v_lshlrev_b64 v[214:215], 1, v[184:185]
	v_lshl_add_u64 v[198:199], v[198:199], 0, v[214:215]
	v_pk_fma_f32 v[108:109], v[156:157], v[140:141], v[108:109] op_sel_hi:[0,1,1] neg_lo:[1,0,0] neg_hi:[1,0,0]
	flat_store_dwordx2 v[198:199], v[132:133]
	v_pk_fma_f32 v[108:109], v[158:159], v[108:109], v[144:145] op_sel_hi:[0,1,1]
	v_mov_b32_dpp v218, v148 row_ror:2 row_mask:0xf bank_mask:0xf
	v_mov_b32_dpp v219, v149 row_ror:2 row_mask:0xf bank_mask:0xf
	v_mov_b32_dpp v132, v148 row_ror:1 row_mask:0xf bank_mask:0xf
	v_mov_b32_dpp v218, v108 row_shr:2 row_mask:0xf bank_mask:0xf
	v_mov_b32_dpp v133, v149 row_ror:1 row_mask:0xf bank_mask:0xf
	v_mov_b32_dpp v219, v109 row_shr:2 row_mask:0xf bank_mask:0xf
	v_mov_b32_dpp v132, v108 row_shr:1 row_mask:0xf bank_mask:0xf
	v_mov_b32_dpp v133, v109 row_shr:1 row_mask:0xf bank_mask:0xf
	v_mov_b32_dpp v148, v150 row_ror:1 row_mask:0xf bank_mask:0xf
	v_mov_b32_dpp v220, v150 row_ror:2 row_mask:0xf bank_mask:0xf
	v_mov_b32_dpp v149, v151 row_ror:1 row_mask:0xf bank_mask:0xf
	v_mov_b32_dpp v221, v151 row_ror:2 row_mask:0xf bank_mask:0xf
; DEVI unsigned pk2(float lo, float hi) { unsigned r; asm("v_cvt_pk_bf16_f32 %0, %1, %2" : "=v"(r) : "v"(lo), "v"(hi)); return r; }
; DEVI float siluf_(float x) { return x * sigmoidf_(x); }
; template <int CTRL> DEVI float dppf(float old, float src) { return __int_as_float(__builtin_amdgcn_update_dpp(__float_as_int(old), __float_as_int(src), CTRL, 0xf, 0xf, false)); }
;     DEVI void operator()(const f32x4 (&acc)[2][2][4][2], const pg8::Unit& u, int wr, int wc, int fr, int fq) const {
;     ...
;                     const int row = u.pm * 256 + ai * 128 + wr * 64 + m * 16 + fr;
;                     const f32x4 g = (acc[ai][0][m][n] - mu[ai][m] * sg) * rs[ai][m] + cg_;
;                     const f32x4 uu = (acc[ai][1][m][n] - mu[ai][m] * su) * rs[ai][m] + cu;
;                     f32x4 p1, p2;
; #pragma unroll
;                     for (int e = 0; e < 4; ++e) {
;                         p1[e] = dppf<0x111>(dppf<0x121>(0.f, gprev[e]), g[e]);
;                         p2[e] = dppf<0x112>(dppf<0x122>(0.f, gprev[e]), g[e]);
;                     }
;                     const int blk = row >> 6;
;                     if (m == 0 && fr < 2) {
;                         const f32x4 pg = (fr == 0) ? (w2 * g + cbv) : (w1 * p1 + w2 * g + cbv);
;                         *(f32x4*)(headpg + ((size_t)blk * 2 + fr) * DFF + j) = pg;
;                         *(f32x4*)(headup + ((size_t)blk * 2 + fr) * DFF + j) = uu;
;                     } else {
;                         const f32x4 cv = w0 * p2 + w1 * p1 + w2 * g + cbv;
;                         u32x2 o; o.x = pk2(siluf_(cv[0]) * uu[0], siluf_(cv[1]) * uu[1]); o.y = pk2(siluf_(cv[2]) * uu[2], siluf_(cv[3]) * uu[3]);
;                         *(u32x2*)(H + (size_t)row * DFF + j) = o;
;                     }
;                     if (m == 3 && fr >= 14) *(f32x4*)(tailg + ((size_t)blk * 2 + (fr - 14)) * DFF + j) = g;
	v_pk_mul_f32 v[150:151], v[136:137], v[218:219]
	v_pk_fma_f32 v[110:111], v[156:157], v[142:143], v[110:111] op_sel_hi:[0,1,1] neg_lo:[1,0,0] neg_hi:[1,0,0]
	v_pk_fma_f32 v[132:133], v[120:121], v[132:133], v[150:151]
	v_pk_fma_f32 v[110:111], v[158:159], v[110:111], v[146:147] op_sel_hi:[0,1,1]
	v_pk_fma_f32 v[132:133], v[108:109], v[116:117], v[132:133]
	v_pk_fma_f32 v[104:105], v[156:157], v[124:125], v[104:105] op_sel_hi:[0,1,1] neg_lo:[1,0,0] neg_hi:[1,0,0]
	v_pk_add_f32 v[132:133], v[112:113], v[132:133]
	v_mov_b32_dpp v220, v110 row_shr:2 row_mask:0xf bank_mask:0xf
	v_mul_f32_e32 v150, 0xbfb8aa3b, v132
	v_exp_f32_e32 v150, v150
	v_mul_f32_e32 v151, 0xbfb8aa3b, v133
	v_exp_f32_e32 v151, v151
	v_mov_b32_dpp v221, v111 row_shr:2 row_mask:0xf bank_mask:0xf
	v_add_f32_e32 v150, 1.0, v150
	v_rcp_f32_e32 v150, v150
	v_add_f32_e32 v151, 1.0, v151
	v_mov_b32_dpp v148, v110 row_shr:1 row_mask:0xf bank_mask:0xf
	v_mov_b32_dpp v149, v111 row_shr:1 row_mask:0xf bank_mask:0xf
	v_pk_mul_f32 v[218:219], v[138:139], v[220:221]
	v_rcp_f32_e32 v151, v151
	v_pk_fma_f32 v[148:149], v[122:123], v[148:149], v[218:219]
	v_pk_fma_f32 v[104:105], v[158:159], v[104:105], v[128:129] op_sel_hi:[0,1,1]
	v_pk_fma_f32 v[148:149], v[110:111], v[118:119], v[148:149]
	v_mul_f32_e32 v132, v132, v150
	v_pk_add_f32 v[148:149], v[114:115], v[148:149]
	v_mul_f32_e32 v104, v104, v132
	v_mul_f32_e32 v132, v133, v151
	v_mul_f32_e32 v133, 0xbfb8aa3b, v148
	v_exp_f32_e32 v133, v133
	v_mul_f32_e32 v150, 0xbfb8aa3b, v149
	v_exp_f32_e32 v150, v150
	v_mul_f32_e32 v105, v105, v132
	v_add_f32_e32 v132, 1.0, v133
	v_rcp_f32_e32 v132, v132
	v_add_f32_e32 v133, 1.0, v150
	v_rcp_f32_e32 v133, v133
	v_pk_fma_f32 v[106:107], v[156:157], v[126:127], v[106:107] op_sel_hi:[0,1,1] neg_lo:[1,0,0] neg_hi:[1,0,0]
	v_pk_fma_f32 v[106:107], v[158:159], v[106:107], v[130:131] op_sel_hi:[0,1,1]
	v_cvt_pk_bf16_f32 v104, v104, v105
	v_mul_f32_e32 v105, v148, v132
	v_mul_f32_e32 v105, v106, v105
	v_mul_f32_e32 v106, v149, v133
	v_mul_f32_e32 v106, v107, v106
	v_cvt_pk_bf16_f32 v105, v105, v106
	v_mad_i64_i32 v[106:107], s[0:1], v196, s83, v[134:135]
	v_lshl_add_u64 v[196:197], v[106:107], 0, v[214:215]
	v_pk_fma_f32 v[100:101], v[152:153], v[140:141], v[100:101] op_sel_hi:[0,1,1] neg_lo:[1,0,0] neg_hi:[1,0,0]
	flat_store_dwordx2 v[196:197], v[104:105]
	v_pk_fma_f32 v[100:101], v[154:155], v[100:101], v[144:145] op_sel_hi:[0,1,1]
	v_mov_b32_dpp v106, v108 row_ror:2 row_mask:0xf bank_mask:0xf
	v_mov_b32_dpp v107, v109 row_ror:2 row_mask:0xf bank_mask:0xf
	v_mov_b32_dpp v104, v108 row_ror:1 row_mask:0xf bank_mask:0xf
	v_mov_b32_dpp v106, v100 row_shr:2 row_mask:0xf bank_mask:0xf
	v_mov_b32_dpp v105, v109 row_ror:1 row_mask:0xf bank_mask:0xf
	v_mov_b32_dpp v107, v101 row_shr:2 row_mask:0xf bank_mask:0xf
	v_mov_b32_dpp v104, v100 row_shr:1 row_mask:0xf bank_mask:0xf
	v_mov_b32_dpp v105, v101 row_shr:1 row_mask:0xf bank_mask:0xf
	v_pk_mul_f32 v[106:107], v[136:137], v[106:107]
	v_pk_fma_f32 v[102:103], v[152:153], v[142:143], v[102:103] op_sel_hi:[0,1,1] neg_lo:[1,0,0] neg_hi:[1,0,0]
	v_pk_fma_f32 v[104:105], v[120:121], v[104:105], v[106:107]
	v_pk_fma_f32 v[102:103], v[154:155], v[102:103], v[146:147] op_sel_hi:[0,1,1]
	v_mov_b32_dpp v132, v110 row_ror:2 row_mask:0xf bank_mask:0xf
	v_mov_b32_dpp v133, v111 row_ror:2 row_mask:0xf bank_mask:0xf
	v_pk_fma_f32 v[104:105], v[100:101], v[116:117], v[104:105]
	v_mov_b32_dpp v108, v110 row_ror:1 row_mask:0xf bank_mask:0xf
	v_mov_b32_dpp v132, v102 row_shr:2 row_mask:0xf bank_mask:0xf
	v_mov_b32_dpp v109, v111 row_ror:1 row_mask:0xf bank_mask:0xf
	v_mov_b32_dpp v133, v103 row_shr:2 row_mask:0xf bank_mask:0xf
	v_pk_add_f32 v[104:105], v[112:113], v[104:105]
	v_mov_b32_dpp v108, v102 row_shr:1 row_mask:0xf bank_mask:0xf
	v_mov_b32_dpp v109, v103 row_shr:1 row_mask:0xf bank_mask:0xf
	v_pk_mul_f32 v[110:111], v[138:139], v[132:133]
	v_mul_f32_e32 v106, 0xbfb8aa3b, v104
	v_pk_fma_f32 v[108:109], v[122:123], v[108:109], v[110:111]
	v_exp_f32_e32 v110, v106
	v_mul_f32_e32 v106, 0xbfb8aa3b, v105
	v_exp_f32_e32 v111, v106
	v_pk_fma_f32 v[106:107], v[102:103], v[118:119], v[108:109]
	v_add_f32_e32 v108, 1.0, v110
	v_rcp_f32_e32 v108, v108
	v_add_f32_e32 v109, 1.0, v111
	v_rcp_f32_e32 v109, v109
	v_pk_fma_f32 v[96:97], v[152:153], v[124:125], v[96:97] op_sel_hi:[0,1,1] neg_lo:[1,0,0] neg_hi:[1,0,0]
	v_pk_fma_f32 v[96:97], v[154:155], v[96:97], v[128:129] op_sel_hi:[0,1,1]
	v_pk_add_f32 v[106:107], v[114:115], v[106:107]
	v_mul_f32_e32 v104, v104, v108
	v_mul_f32_e32 v96, v96, v104
	v_mul_f32_e32 v104, v105, v109
	v_mul_f32_e32 v105, 0xbfb8aa3b, v106
	v_exp_f32_e32 v105, v105
	v_mul_f32_e32 v108, 0xbfb8aa3b, v107
	v_exp_f32_e32 v108, v108
	v_mul_f32_e32 v97, v97, v104
	v_add_f32_e32 v104, 1.0, v105
	v_rcp_f32_e32 v104, v104
	v_add_f32_e32 v105, 1.0, v108
	v_rcp_f32_e32 v105, v105
	v_pk_fma_f32 v[98:99], v[152:153], v[126:127], v[98:99] op_sel_hi:[0,1,1] neg_lo:[1,0,0] neg_hi:[1,0,0]
	v_pk_fma_f32 v[98:99], v[154:155], v[98:99], v[130:131] op_sel_hi:[0,1,1]
	v_cvt_pk_bf16_f32 v96, v96, v97
	v_mul_f32_e32 v97, v106, v104
	v_mul_f32_e32 v97, v98, v97
	v_mul_f32_e32 v98, v107, v105
	v_mul_f32_e32 v98, v99, v98
	v_cvt_pk_bf16_f32 v97, v97, v98
	v_mad_i64_i32 v[98:99], s[0:1], v208, s83, v[134:135]
	v_lshl_add_u64 v[150:151], v[98:99], 0, v[214:215]
	flat_store_dwordx2 v[150:151], v[96:97]
	v_lshl_add_u64 v[96:97], s[26:27], 0, v[216:217]
	v_lshl_add_u64 v[148:149], v[184:185], 2, v[96:97]
	s_and_saveexec_b64 s[0:1], s[6:7]
	s_cbranch_execz .LBB0_2728
	flat_store_dwordx4 v[148:149], v[100:103]
; DEVI unsigned pk2(float lo, float hi) { unsigned r; asm("v_cvt_pk_bf16_f32 %0, %1, %2" : "=v"(r) : "v"(lo), "v"(hi)); return r; }
; DEVI float siluf_(float x) { return x * sigmoidf_(x); }
; DEVI void row_stats(const float* stats, int row, float& mu, float& rs) {
;     if (stats) { const float2 st = *(const float2*)(stats + 2 * (size_t)row); mu = st.x * (1.0f / 1024.0f); const float var = st.y * (1.0f / 1024.0f) - mu * mu; rs = rsqrtf(fmaxf(var, 0.f) + LN_EPS); }
;     else { mu = 0.f; rs = 1.f; }
; }
;     DEVI void operator()(const f32x4 (&acc)[2][2][4][2], const pg8::Unit& u, int wr, int wc, int fr, int fq) const {
;     ...
; #pragma unroll
;             for (int ai = 0; ai < 2; ++ai) {
;                 f32x4 gprev = (f32x4){0.f, 0.f, 0.f, 0.f};
; #pragma unroll
;                 for (int m = 0; m < 4; ++m) {
;                     const int row = u.pm * 256 + ai * 128 + wr * 64 + m * 16 + fr;
;                     const f32x4 g = (acc[ai][0][m][n] - mu[ai][m] * sg) * rs[ai][m] + cg_;
;                     const f32x4 uu = (acc[ai][1][m][n] - mu[ai][m] * su) * rs[ai][m] + cu;
;                     f32x4 p1, p2;
; #pragma unroll
;                     for (int e = 0; e < 4; ++e) {
;                         p1[e] = dppf<0x111>(dppf<0x121>(0.f, gprev[e]), g[e]);
;                         p2[e] = dppf<0x112>(dppf<0x122>(0.f, gprev[e]), g[e]);
;                     }
;                     const int blk = row >> 6;
;                     if (m == 0 && fr < 2) {
;                         const f32x4 pg = (fr == 0) ? (w2 * g + cbv) : (w1 * p1 + w2 * g + cbv);
;                         *(f32x4*)(headpg + ((size_t)blk * 2 + fr) * DFF + j) = pg;
;                         *(f32x4*)(headup + ((size_t)blk * 2 + fr) * DFF + j) = uu;
;                     } else {
;                         const f32x4 cv = w0 * p2 + w1 * p1 + w2 * g + cbv;
;                         u32x2 o; o.x = pk2(siluf_(cv[0]) * uu[0], siluf_(cv[1]) * uu[1]); o.y = pk2(siluf_(cv[2]) * uu[2], siluf_(cv[3]) * uu[3]);
;                         *(u32x2*)(H + (size_t)row * DFF + j) = o;
;                     }
;                     if (m == 3 && fr >= 14) *(f32x4*)(tailg + ((size_t)blk * 2 + (fr - 14)) * DFF + j) = g;
;                     gprev = g;
.LBB0_2728:
	s_or_b64 exec, exec, s[0:1]
	v_pk_mul_f32 v[132:133], v[210:211], s[42:43] op_sel_hi:[1,0]
	v_fma_f32 v96, -v132, v132, v133
	v_max_f32_e32 v96, 0, v96
	v_add_f32_e32 v96, 0x3727c5ac, v96
	v_mul_f32_e32 v97, 0x4b800000, v96
	v_cmp_gt_f32_e32 vcc, s81, v96
	v_mov_b32_e32 v103, 0
	v_pk_fma_f32 v[94:95], v[132:133], v[142:143], v[94:95] op_sel_hi:[0,1,1] neg_lo:[1,0,0] neg_hi:[1,0,0]
	v_cndmask_b32_e32 v96, v96, v97, vcc
	v_rsq_f32_e32 v96, v96
	v_pk_fma_f32 v[92:93], v[132:133], v[140:141], v[92:93] op_sel_hi:[0,1,1] neg_lo:[1,0,0] neg_hi:[1,0,0]
	v_mov_b32_dpp v101, v101 row_ror:1 row_mask:0xf bank_mask:0xf
	v_mov_b32_dpp v103, v103 row_ror:2 row_mask:0xf bank_mask:0xf
	v_mul_f32_e32 v97, 0x45800000, v96
	v_cndmask_b32_e32 v110, v96, v97, vcc
	s_addk_i32 s50, 0x80
	v_pk_fma_f32 v[96:97], v[94:95], v[110:111], v[146:147] op_sel_hi:[1,0,1]
	v_pk_fma_f32 v[98:99], v[92:93], v[110:111], v[144:145] op_sel_hi:[1,0,1]
	v_pk_fma_f32 v[90:91], v[132:133], v[126:127], v[90:91] op_sel_hi:[0,1,1] neg_lo:[1,0,0] neg_hi:[1,0,0]
	v_pk_fma_f32 v[88:89], v[132:133], v[124:125], v[88:89] op_sel_hi:[0,1,1] neg_lo:[1,0,0] neg_hi:[1,0,0]
	v_mov_b32_e32 v92, v101
	v_mov_b32_e32 v94, v103
	v_mov_b32_e32 v93, v101
	v_mov_b32_e32 v95, v103
	v_mov_b32_e32 v100, v101
	v_mov_b32_e32 v102, v103
	v_or_b32_e32 v107, s50, v172
	v_mov_b32_dpp v92, v98 row_shr:1 row_mask:0xf bank_mask:0xf
	v_mov_b32_dpp v94, v98 row_shr:2 row_mask:0xf bank_mask:0xf
	v_mov_b32_dpp v93, v99 row_shr:1 row_mask:0xf bank_mask:0xf
	v_mov_b32_dpp v95, v99 row_shr:2 row_mask:0xf bank_mask:0xf
	v_mov_b32_dpp v100, v96 row_shr:1 row_mask:0xf bank_mask:0xf
	v_mov_b32_dpp v102, v96 row_shr:2 row_mask:0xf bank_mask:0xf
	v_mov_b32_dpp v101, v97 row_shr:1 row_mask:0xf bank_mask:0xf
	v_mov_b32_dpp v103, v97 row_shr:2 row_mask:0xf bank_mask:0xf
	v_pk_fma_f32 v[90:91], v[110:111], v[90:91], v[130:131] op_sel_hi:[0,1,1]
	v_pk_fma_f32 v[88:89], v[110:111], v[88:89], v[128:129] op_sel_hi:[0,1,1]
	s_and_saveexec_b64 s[0:1], s[2:3]
	s_xor_b64 s[0:1], exec, s[0:1]
	s_cbranch_execz .LBB0_2730
	v_pk_mul_f32 v[94:95], v[136:137], v[94:95]
	v_pk_mul_f32 v[102:103], v[138:139], v[102:103]
	v_pk_fma_f32 v[92:93], v[120:121], v[92:93], v[94:95]
	v_pk_fma_f32 v[100:101], v[122:123], v[100:101], v[102:103]
	v_pk_fma_f32 v[92:93], v[116:117], v[98:99], v[92:93]
	s_nop 0
	v_pk_add_f32 v[92:93], v[112:113], v[92:93]
	s_nop 0
	v_mul_f32_e32 v94, 0xbfb8aa3b, v92
	v_exp_f32_e32 v102, v94
	v_mul_f32_e32 v94, 0xbfb8aa3b, v93
	v_exp_f32_e32 v103, v94
	v_pk_fma_f32 v[94:95], v[118:119], v[96:97], v[100:101]
	v_add_f32_e32 v100, 1.0, v102
	v_rcp_f32_e32 v100, v100
	v_add_f32_e32 v101, 1.0, v103
	v_rcp_f32_e32 v101, v101
	v_pk_add_f32 v[94:95], v[114:115], v[94:95]
	v_mul_f32_e32 v92, v92, v100
	v_mul_f32_e32 v88, v88, v92
	v_mul_f32_e32 v92, v93, v101
	v_mul_f32_e32 v93, 0xbfb8aa3b, v94
	v_exp_f32_e32 v93, v93
	v_mul_f32_e32 v100, 0xbfb8aa3b, v95
	v_exp_f32_e32 v100, v100
	v_mul_f32_e32 v89, v89, v92
	v_add_f32_e32 v92, 1.0, v93
	v_rcp_f32_e32 v92, v92
	v_add_f32_e32 v93, 1.0, v100
	v_rcp_f32_e32 v93, v93
	v_cvt_pk_bf16_f32 v88, v88, v89
	v_mul_f32_e32 v89, v94, v92
	v_mul_f32_e32 v89, v90, v89
	v_mul_f32_e32 v90, v95, v93
	v_mul_f32_e32 v90, v91, v90
	v_cvt_pk_bf16_f32 v89, v89, v90
	v_mov_b64_e32 v[90:91], s[18:19]
	v_mad_i64_i32 v[90:91], s[10:11], v107, s83, v[90:91]
	v_lshl_add_u64 v[90:91], v[184:185], 1, v[90:91]
	flat_store_dwordx2 v[90:91], v[88:89]

; DEVI unsigned pk2(float lo, float hi) { unsigned r; asm("v_cvt_pk_bf16_f32 %0, %1, %2" : "=v"(r) : "v"(lo), "v"(hi)); return r; }
; DEVI float siluf_(float x) { return x * sigmoidf_(x); }
; DEVI void row_stats(const float* stats, int row, float& mu, float& rs) {
;     if (stats) { const float2 st = *(const float2*)(stats + 2 * (size_t)row); mu = st.x * (1.0f / 1024.0f); const float var = st.y * (1.0f / 1024.0f) - mu * mu; rs = rsqrtf(fmaxf(var, 0.f) + LN_EPS); }
;     else { mu = 0.f; rs = 1.f; }
; }
;     DEVI void operator()(const f32x4 (&acc)[2][2][4][2], const pg8::Unit& u, int wr, int wc, int fr, int fq) const {
;     ...
; #pragma unroll
;             for (int ai = 0; ai < 2; ++ai) {
;                 f32x4 gprev = (f32x4){0.f, 0.f, 0.f, 0.f};
; #pragma unroll
;                 for (int m = 0; m < 4; ++m) {
;                     const int row = u.pm * 256 + ai * 128 + wr * 64 + m * 16 + fr;
;                     const f32x4 g = (acc[ai][0][m][n] - mu[ai][m] * sg) * rs[ai][m] + cg_;
;                     const f32x4 uu = (acc[ai][1][m][n] - mu[ai][m] * su) * rs[ai][m] + cu;
;                     f32x4 p1, p2;
; #pragma unroll
;                     for (int e = 0; e < 4; ++e) {
;                         p1[e] = dppf<0x111>(dppf<0x121>(0.f, gprev[e]), g[e]);
;                         p2[e] = dppf<0x112>(dppf<0x122>(0.f, gprev[e]), g[e]);
;                     }
;                     const int blk = row >> 6;
;                     if (m == 0 && fr < 2) {
;                         const f32x4 pg = (fr == 0) ? (w2 * g + cbv) : (w1 * p1 + w2 * g + cbv);
;                         *(f32x4*)(headpg + ((size_t)blk * 2 + fr) * DFF + j) = pg;
;                         *(f32x4*)(headup + ((size_t)blk * 2 + fr) * DFF + j) = uu;
;                     } else {
;                         const f32x4 cv = w0 * p2 + w1 * p1 + w2 * g + cbv;
;                         u32x2 o; o.x = pk2(siluf_(cv[0]) * uu[0], siluf_(cv[1]) * uu[1]); o.y = pk2(siluf_(cv[2]) * uu[2], siluf_(cv[3]) * uu[3]);
;                         *(u32x2*)(H + (size_t)row * DFF + j) = o;
;                     }
;                     if (m == 3 && fr >= 14) *(f32x4*)(tailg + ((size_t)blk * 2 + (fr - 14)) * DFF + j) = g;
;                     gprev = g;
.LBB0_2732:
	s_or_b64 exec, exec, s[0:1]
	v_pk_mul_f32 v[108:109], v[212:213], s[42:43] op_sel_hi:[1,0]
	v_lshl_add_u64 v[90:91], s[10:11], 0, v[174:175]
	v_fma_f32 v88, -v108, v108, v109
	v_max_f32_e32 v88, 0, v88
	v_add_f32_e32 v88, 0x3727c5ac, v88
	v_mul_f32_e32 v89, 0x4b800000, v88
	v_cmp_gt_f32_e32 vcc, s81, v88
	v_pk_mul_f32 v[104:105], v[206:207], s[42:43] op_sel_hi:[1,0]
	v_pk_mul_f32 v[100:101], v[204:205], s[42:43] op_sel_hi:[1,0]
	v_cndmask_b32_e32 v88, v88, v89, vcc
	v_rsq_f32_e32 v92, v88
	v_mad_u64_u32 v[88:89], s[0:1], v90, s84, 0
	v_mad_i32_i24 v89, v91, s84, v89
	v_fma_f32 v91, -v104, v104, v105
	v_max_f32_e32 v91, 0, v91
	v_add_f32_e32 v91, 0x3727c5ac, v91
	v_mul_f32_e32 v93, 0x4b800000, v91
	v_cmp_gt_f32_e64 s[0:1], s81, v91
	v_mul_f32_e32 v90, 0x45800000, v92
	v_cndmask_b32_e32 v134, v92, v90, vcc
	v_cndmask_b32_e64 v91, v91, v93, s[0:1]
	v_fma_f32 v93, -v100, v100, v101
	v_max_f32_e32 v93, 0, v93
	v_add_f32_e32 v93, 0x3727c5ac, v93
	v_mul_f32_e32 v94, 0x4b800000, v93
	v_cmp_gt_f32_e64 s[10:11], s81, v93
	v_rsq_f32_e32 v91, v91
	v_pk_fma_f32 v[84:85], v[108:109], v[140:141], v[84:85] op_sel_hi:[0,1,1] neg_lo:[1,0,0] neg_hi:[1,0,0]
	v_cndmask_b32_e64 v93, v93, v94, s[10:11]
	v_rsq_f32_e32 v93, v93
	v_mul_f32_e32 v90, 0x45800000, v91
	v_cndmask_b32_e64 v106, v91, v90, s[0:1]
	v_mul_f32_e32 v90, 0x45800000, v93
	v_cndmask_b32_e64 v102, v93, v90, s[10:11]
	v_pk_fma_f32 v[84:85], v[84:85], v[134:135], v[144:145] op_sel_hi:[1,0,1]
	v_mov_b32_dpp v92, v98 row_ror:2 row_mask:0xf bank_mask:0xf
	v_mov_b32_dpp v93, v99 row_ror:2 row_mask:0xf bank_mask:0xf
	v_mov_b32_dpp v90, v98 row_ror:1 row_mask:0xf bank_mask:0xf
	v_mov_b32_dpp v92, v84 row_shr:2 row_mask:0xf bank_mask:0xf
	v_mov_b32_dpp v91, v99 row_ror:1 row_mask:0xf bank_mask:0xf
	v_mov_b32_dpp v93, v85 row_shr:2 row_mask:0xf bank_mask:0xf
	v_mov_b32_dpp v90, v84 row_shr:1 row_mask:0xf bank_mask:0xf
	v_mov_b32_dpp v91, v85 row_shr:1 row_mask:0xf bank_mask:0xf
	v_pk_mul_f32 v[92:93], v[136:137], v[92:93]
	v_pk_fma_f32 v[86:87], v[108:109], v[142:143], v[86:87] op_sel_hi:[0,1,1] neg_lo:[1,0,0] neg_hi:[1,0,0]
	v_pk_fma_f32 v[90:91], v[120:121], v[90:91], v[92:93]
	v_pk_fma_f32 v[86:87], v[86:87], v[134:135], v[146:147] op_sel_hi:[1,0,1]
	v_mov_b32_dpp v98, v96 row_ror:2 row_mask:0xf bank_mask:0xf
	v_mov_b32_dpp v99, v97 row_ror:2 row_mask:0xf bank_mask:0xf
	v_pk_fma_f32 v[90:91], v[116:117], v[84:85], v[90:91]
	v_mov_b32_dpp v94, v96 row_ror:1 row_mask:0xf bank_mask:0xf
	v_mov_b32_dpp v98, v86 row_shr:2 row_mask:0xf bank_mask:0xf
	v_mov_b32_dpp v95, v97 row_ror:1 row_mask:0xf bank_mask:0xf
	v_mov_b32_dpp v99, v87 row_shr:2 row_mask:0xf bank_mask:0xf
	v_pk_add_f32 v[90:91], v[112:113], v[90:91]
	v_mov_b32_dpp v94, v86 row_shr:1 row_mask:0xf bank_mask:0xf
	v_mov_b32_dpp v95, v87 row_shr:1 row_mask:0xf bank_mask:0xf
	v_pk_mul_f32 v[96:97], v[138:139], v[98:99]
	v_mul_f32_e32 v92, 0xbfb8aa3b, v90
	v_pk_fma_f32 v[94:95], v[122:123], v[94:95], v[96:97]
	v_exp_f32_e32 v96, v92
	v_mul_f32_e32 v92, 0xbfb8aa3b, v91
	v_exp_f32_e32 v97, v92
	v_pk_fma_f32 v[92:93], v[118:119], v[86:87], v[94:95]
	v_add_f32_e32 v94, 1.0, v96
	v_rcp_f32_e32 v94, v94
	v_add_f32_e32 v95, 1.0, v97
	v_rcp_f32_e32 v95, v95
	v_pk_fma_f32 v[80:81], v[108:109], v[124:125], v[80:81] op_sel_hi:[0,1,1] neg_lo:[1,0,0] neg_hi:[1,0,0]
	v_pk_fma_f32 v[80:81], v[80:81], v[134:135], v[128:129] op_sel_hi:[1,0,1]
	v_pk_add_f32 v[92:93], v[114:115], v[92:93]
	v_mul_f32_e32 v90, v90, v94
	v_mul_f32_e32 v80, v80, v90
	v_mul_f32_e32 v90, v91, v95
	v_mul_f32_e32 v91, 0xbfb8aa3b, v92
	v_exp_f32_e32 v91, v91
	v_mul_f32_e32 v94, 0xbfb8aa3b, v93
	v_exp_f32_e32 v94, v94
	v_mul_f32_e32 v81, v81, v90
	v_add_f32_e32 v90, 1.0, v91
	v_rcp_f32_e32 v90, v90
	v_add_f32_e32 v91, 1.0, v94
	v_rcp_f32_e32 v91, v91
	v_pk_fma_f32 v[82:83], v[108:109], v[126:127], v[82:83] op_sel_hi:[0,1,1] neg_lo:[1,0,0] neg_hi:[1,0,0]
	v_pk_fma_f32 v[82:83], v[82:83], v[134:135], v[130:131] op_sel_hi:[1,0,1]
	v_cvt_pk_bf16_f32 v80, v80, v81
	v_mul_f32_e32 v81, v92, v90
	v_mul_f32_e32 v81, v82, v81
	v_mul_f32_e32 v82, v93, v91
	v_mul_f32_e32 v82, v83, v82
	v_or_b32_e32 v103, 16, v107
	v_cvt_pk_bf16_f32 v81, v81, v82
	v_mov_b64_e32 v[82:83], s[18:19]
	v_mad_i64_i32 v[90:91], s[0:1], v103, s83, v[82:83]
	v_lshl_add_u64 v[206:207], v[90:91], 0, v[214:215]
	v_pk_fma_f32 v[76:77], v[104:105], v[140:141], v[76:77] op_sel_hi:[0,1,1] neg_lo:[1,0,0] neg_hi:[1,0,0]
	flat_store_dwordx2 v[206:207], v[80:81]
	v_pk_fma_f32 v[76:77], v[76:77], v[106:107], v[144:145] op_sel_hi:[1,0,1]
	v_mov_b32_dpp v90, v84 row_ror:2 row_mask:0xf bank_mask:0xf
	v_mov_b32_dpp v91, v85 row_ror:2 row_mask:0xf bank_mask:0xf
	v_mov_b32_dpp v80, v84 row_ror:1 row_mask:0xf bank_mask:0xf
	v_mov_b32_dpp v90, v76 row_shr:2 row_mask:0xf bank_mask:0xf
	v_mov_b32_dpp v81, v85 row_ror:1 row_mask:0xf bank_mask:0xf
	v_mov_b32_dpp v91, v77 row_shr:2 row_mask:0xf bank_mask:0xf
	v_mov_b32_dpp v80, v76 row_shr:1 row_mask:0xf bank_mask:0xf
	v_mov_b32_dpp v81, v77 row_shr:1 row_mask:0xf bank_mask:0xf
	v_mov_b32_dpp v84, v86 row_ror:1 row_mask:0xf bank_mask:0xf
	v_mov_b32_dpp v92, v86 row_ror:2 row_mask:0xf bank_mask:0xf
	v_mov_b32_dpp v85, v87 row_ror:1 row_mask:0xf bank_mask:0xf
	v_mov_b32_dpp v93, v87 row_ror:2 row_mask:0xf bank_mask:0xf
	v_pk_mul_f32 v[86:87], v[136:137], v[90:91]
	v_pk_fma_f32 v[78:79], v[104:105], v[142:143], v[78:79] op_sel_hi:[0,1,1] neg_lo:[1,0,0] neg_hi:[1,0,0]
	v_pk_fma_f32 v[80:81], v[120:121], v[80:81], v[86:87]
	v_pk_fma_f32 v[78:79], v[78:79], v[106:107], v[146:147] op_sel_hi:[1,0,1]
	v_pk_fma_f32 v[80:81], v[116:117], v[76:77], v[80:81]
; DEVI unsigned pk2(float lo, float hi) { unsigned r; asm("v_cvt_pk_bf16_f32 %0, %1, %2" : "=v"(r) : "v"(lo), "v"(hi)); return r; }
; DEVI float siluf_(float x) { return x * sigmoidf_(x); }
; template <int CTRL> DEVI float dppf(float old, float src) { return __int_as_float(__builtin_amdgcn_update_dpp(__float_as_int(old), __float_as_int(src), CTRL, 0xf, 0xf, false)); }
;     DEVI void operator()(const f32x4 (&acc)[2][2][4][2], const pg8::Unit& u, int wr, int wc, int fr, int fq) const {
;     ...
; #pragma unroll
;             for (int ai = 0; ai < 2; ++ai) {
;                 f32x4 gprev = (f32x4){0.f, 0.f, 0.f, 0.f};
; #pragma unroll
;                 for (int m = 0; m < 4; ++m) {
;                     const int row = u.pm * 256 + ai * 128 + wr * 64 + m * 16 + fr;
;                     const f32x4 g = (acc[ai][0][m][n] - mu[ai][m] * sg) * rs[ai][m] + cg_;
;                     const f32x4 uu = (acc[ai][1][m][n] - mu[ai][m] * su) * rs[ai][m] + cu;
;                     f32x4 p1, p2;
; #pragma unroll
;                     for (int e = 0; e < 4; ++e) {
;                         p1[e] = dppf<0x111>(dppf<0x121>(0.f, gprev[e]), g[e]);
;                         p2[e] = dppf<0x112>(dppf<0x122>(0.f, gprev[e]), g[e]);
;                     }
;                     const int blk = row >> 6;
;                     if (m == 0 && fr < 2) {
;                         const f32x4 pg = (fr == 0) ? (w2 * g + cbv) : (w1 * p1 + w2 * g + cbv);
;                         *(f32x4*)(headpg + ((size_t)blk * 2 + fr) * DFF + j) = pg;
;                         *(f32x4*)(headup + ((size_t)blk * 2 + fr) * DFF + j) = uu;
;                     } else {
;                         const f32x4 cv = w0 * p2 + w1 * p1 + w2 * g + cbv;
;                         u32x2 o; o.x = pk2(siluf_(cv[0]) * uu[0], siluf_(cv[1]) * uu[1]); o.y = pk2(siluf_(cv[2]) * uu[2], siluf_(cv[3]) * uu[3]);
;                         *(u32x2*)(H + (size_t)row * DFF + j) = o;
;                     }
;                     if (m == 3 && fr >= 14) *(f32x4*)(tailg + ((size_t)blk * 2 + (fr - 14)) * DFF + j) = g;
;                     gprev = g;
	v_pk_fma_f32 v[72:73], v[104:105], v[124:125], v[72:73] op_sel_hi:[0,1,1] neg_lo:[1,0,0] neg_hi:[1,0,0]
	v_pk_add_f32 v[80:81], v[112:113], v[80:81]
	v_mov_b32_dpp v92, v78 row_shr:2 row_mask:0xf bank_mask:0xf
	v_mul_f32_e32 v86, 0xbfb8aa3b, v80
	v_exp_f32_e32 v86, v86
	v_mul_f32_e32 v87, 0xbfb8aa3b, v81
	v_exp_f32_e32 v87, v87
	v_mov_b32_dpp v93, v79 row_shr:2 row_mask:0xf bank_mask:0xf
	v_add_f32_e32 v86, 1.0, v86
	v_rcp_f32_e32 v86, v86
	v_add_f32_e32 v87, 1.0, v87
	v_mov_b32_dpp v84, v78 row_shr:1 row_mask:0xf bank_mask:0xf
	v_mov_b32_dpp v85, v79 row_shr:1 row_mask:0xf bank_mask:0xf
	v_pk_mul_f32 v[90:91], v[138:139], v[92:93]
	v_rcp_f32_e32 v87, v87
	v_pk_fma_f32 v[84:85], v[122:123], v[84:85], v[90:91]
	v_pk_fma_f32 v[72:73], v[72:73], v[106:107], v[128:129] op_sel_hi:[1,0,1]
	v_pk_fma_f32 v[84:85], v[118:119], v[78:79], v[84:85]
	v_mul_f32_e32 v80, v80, v86
	v_pk_add_f32 v[84:85], v[114:115], v[84:85]
	v_mul_f32_e32 v72, v72, v80
	v_mul_f32_e32 v80, v81, v87
	v_mul_f32_e32 v81, 0xbfb8aa3b, v84
	v_exp_f32_e32 v81, v81
	v_mul_f32_e32 v86, 0xbfb8aa3b, v85
	v_exp_f32_e32 v86, v86
	v_mul_f32_e32 v73, v73, v80
	v_add_f32_e32 v80, 1.0, v81
	v_rcp_f32_e32 v80, v80
	v_add_f32_e32 v81, 1.0, v86
	v_rcp_f32_e32 v81, v81
	v_pk_fma_f32 v[74:75], v[104:105], v[126:127], v[74:75] op_sel_hi:[0,1,1] neg_lo:[1,0,0] neg_hi:[1,0,0]
	v_pk_fma_f32 v[74:75], v[74:75], v[106:107], v[130:131] op_sel_hi:[1,0,1]
	v_cvt_pk_bf16_f32 v72, v72, v73
	v_mul_f32_e32 v73, v84, v80
	v_mul_f32_e32 v73, v74, v73
	v_mul_f32_e32 v74, v85, v81
	v_or_b32_e32 v94, 32, v107
	v_mul_f32_e32 v74, v75, v74
	v_cvt_pk_bf16_f32 v73, v73, v74
	v_mad_i64_i32 v[74:75], s[0:1], v94, s83, v[82:83]
	v_lshl_add_u64 v[204:205], v[74:75], 0, v[214:215]
	flat_store_dwordx2 v[204:205], v[72:73]
	v_xor_b32_e32 v73, 0x80000000, v143
	v_xor_b32_e32 v72, 0x80000000, v142
	v_pk_fma_f32 v[68:69], v[140:141], v[100:101], v[68:69] op_sel_hi:[1,0,1] neg_lo:[1,0,0] neg_hi:[1,0,0]
	v_pk_fma_f32 v[70:71], v[72:73], v[100:101], v[70:71] op_sel_hi:[1,0,1]
	v_pk_fma_f32 v[68:69], v[68:69], v[102:103], v[144:145] op_sel_hi:[1,0,1]
	v_mov_b32_dpp v74, v76 row_ror:2 row_mask:0xf bank_mask:0xf
	v_mov_b32_dpp v75, v77 row_ror:2 row_mask:0xf bank_mask:0xf
	v_mov_b32_dpp v72, v76 row_ror:1 row_mask:0xf bank_mask:0xf
	v_mov_b32_dpp v74, v68 row_shr:2 row_mask:0xf bank_mask:0xf
	v_mov_b32_dpp v73, v77 row_ror:1 row_mask:0xf bank_mask:0xf
	v_mov_b32_dpp v75, v69 row_shr:2 row_mask:0xf bank_mask:0xf
	v_mov_b32_dpp v72, v68 row_shr:1 row_mask:0xf bank_mask:0xf
	v_mov_b32_dpp v73, v69 row_shr:1 row_mask:0xf bank_mask:0xf
	v_pk_mul_f32 v[74:75], v[136:137], v[74:75]
	v_pk_fma_f32 v[72:73], v[120:121], v[72:73], v[74:75]
	v_pk_fma_f32 v[70:71], v[70:71], v[102:103], v[146:147] op_sel_hi:[1,0,1]
	v_mov_b32_dpp v80, v78 row_ror:2 row_mask:0xf bank_mask:0xf
	v_mov_b32_dpp v81, v79 row_ror:2 row_mask:0xf bank_mask:0xf
	v_pk_fma_f32 v[72:73], v[116:117], v[68:69], v[72:73]
	v_mov_b32_dpp v76, v78 row_ror:1 row_mask:0xf bank_mask:0xf
	v_mov_b32_dpp v80, v70 row_shr:2 row_mask:0xf bank_mask:0xf
	v_mov_b32_dpp v77, v79 row_ror:1 row_mask:0xf bank_mask:0xf
	v_mov_b32_dpp v81, v71 row_shr:2 row_mask:0xf bank_mask:0xf
	v_pk_add_f32 v[72:73], v[112:113], v[72:73]
	v_mov_b32_dpp v76, v70 row_shr:1 row_mask:0xf bank_mask:0xf
	v_mov_b32_dpp v77, v71 row_shr:1 row_mask:0xf bank_mask:0xf
	v_pk_mul_f32 v[78:79], v[138:139], v[80:81]
	v_mul_f32_e32 v74, 0xbfb8aa3b, v72
	v_pk_fma_f32 v[76:77], v[122:123], v[76:77], v[78:79]
	v_exp_f32_e32 v78, v74
	v_mul_f32_e32 v74, 0xbfb8aa3b, v73
	v_exp_f32_e32 v79, v74
	v_pk_fma_f32 v[74:75], v[118:119], v[70:71], v[76:77]
	v_add_f32_e32 v76, 1.0, v78
	v_rcp_f32_e32 v76, v76
	v_add_f32_e32 v77, 1.0, v79
	v_rcp_f32_e32 v77, v77
	v_pk_fma_f32 v[64:65], v[100:101], v[124:125], v[64:65] op_sel_hi:[0,1,1] neg_lo:[1,0,0] neg_hi:[1,0,0]
	v_pk_fma_f32 v[64:65], v[64:65], v[102:103], v[128:129] op_sel_hi:[1,0,1]
	v_pk_add_f32 v[74:75], v[114:115], v[74:75]
	v_mul_f32_e32 v72, v72, v76
	v_mul_f32_e32 v64, v64, v72
	v_mul_f32_e32 v72, v73, v77
	v_mul_f32_e32 v73, 0xbfb8aa3b, v74
	v_exp_f32_e32 v73, v73
	v_mul_f32_e32 v76, 0xbfb8aa3b, v75
	v_exp_f32_e32 v76, v76
	v_mul_f32_e32 v65, v65, v72
	v_add_f32_e32 v72, 1.0, v73
	v_rcp_f32_e32 v72, v72
	v_add_f32_e32 v73, 1.0, v76
	v_rcp_f32_e32 v73, v73
	v_pk_fma_f32 v[66:67], v[100:101], v[126:127], v[66:67] op_sel_hi:[0,1,1] neg_lo:[1,0,0] neg_hi:[1,0,0]
	v_pk_fma_f32 v[66:67], v[66:67], v[102:103], v[130:131] op_sel_hi:[1,0,1]
	v_cvt_pk_bf16_f32 v64, v64, v65
	v_mul_f32_e32 v65, v74, v72
	v_mul_f32_e32 v65, v66, v65
	v_mul_f32_e32 v66, v75, v73
	v_or_b32_e32 v84, 48, v107
	v_mul_f32_e32 v66, v67, v66
	v_cvt_pk_bf16_f32 v65, v65, v66
	v_mad_i64_i32 v[66:67], s[0:1], v84, s83, v[82:83]
	v_lshl_add_u64 v[114:115], v[66:67], 0, v[214:215]
	flat_store_dwordx2 v[114:115], v[64:65]
	v_lshl_add_u64 v[64:65], s[26:27], 0, v[88:89]
	v_lshl_add_u64 v[112:113], v[184:185], 2, v[64:65]
	s_and_saveexec_b64 s[0:1], s[6:7]
	s_cbranch_execz .LBB0_2734
	flat_store_dwordx4 v[112:113], v[68:71]
; DEVI unsigned pk2(float lo, float hi) { unsigned r; asm("v_cvt_pk_bf16_f32 %0, %1, %2" : "=v"(r) : "v"(lo), "v"(hi)); return r; }
;     DEVI void operator()(const f32x4 (&acc)[2][2][4][2], const pg8::Unit& u, int wr, int wc, int fr, int fq) const {
;     ...
;         for (int n = 0; n < 2; ++n) {
;             const int tc = u.pn * 256 + wc * 32 + 8 * fq + 4 * n;
;             const int j = u.pn * 128 + wc * 32 + 8 * fq + 4 * n;
;             const f32x4 sg = *(const f32x4*)(s + tc), cg_ = *(const f32x4*)(c + tc), su = *(const f32x4*)(s + tc + 128), cu = *(const f32x4*)(c + tc + 128);
;             const f32x4 w0 = *(const f32x4*)(cw + j), w1 = *(const f32x4*)(cw + DFF + j), w2 = *(const f32x4*)(cw + 2 * DFF + j), cbv = *(const f32x4*)(cb + j);
; #pragma unroll
;             for (int ai = 0; ai < 2; ++ai) {
;                 f32x4 gprev = (f32x4){0.f, 0.f, 0.f, 0.f};
; #pragma unroll
;                 for (int m = 0; m < 4; ++m) {
;                     const int row = u.pm * 256 + ai * 128 + wr * 64 + m * 16 + fr;
;                     const f32x4 g = (acc[ai][0][m][n] - mu[ai][m] * sg) * rs[ai][m] + cg_;
;                     const f32x4 uu = (acc[ai][1][m][n] - mu[ai][m] * su) * rs[ai][m] + cu;
;                     f32x4 p1, p2;
; #pragma unroll
;                     for (int e = 0; e < 4; ++e) {
;                         p1[e] = dppf<0x111>(dppf<0x121>(0.f, gprev[e]), g[e]);
;                         p2[e] = dppf<0x112>(dppf<0x122>(0.f, gprev[e]), g[e]);
;                     }
;                     const int blk = row >> 6;
;                     if (m == 0 && fr < 2) {
;                         const f32x4 pg = (fr == 0) ? (w2 * g + cbv) : (w1 * p1 + w2 * g + cbv);
;                         *(f32x4*)(headpg + ((size_t)blk * 2 + fr) * DFF + j) = pg;
;                         *(f32x4*)(headup + ((size_t)blk * 2 + fr) * DFF + j) = uu;
;                     } else {
;                         const f32x4 cv = w0 * p2 + w1 * p1 + w2 * g + cbv;
;                         u32x2 o; o.x = pk2(siluf_(cv[0]) * uu[0], siluf_(cv[1]) * uu[1]); o.y = pk2(siluf_(cv[2]) * uu[2], siluf_(cv[3]) * uu[3]);
;                         *(u32x2*)(H + (size_t)row * DFF + j) = o;
;                     }
;                     if (m == 3 && fr >= 14) *(f32x4*)(tailg + ((size_t)blk * 2 + (fr - 14)) * DFF + j) = g;
;                     gprev = g;
.LBB0_2734:
	s_or_b64 exec, exec, s[0:1]
	v_or_b32_e32 v64, 4, v194
	v_ashrrev_i32_e32 v65, 31, v64
	v_lshlrev_b64 v[64:65], 2, v[64:65]
	v_lshl_add_u64 v[66:67], s[20:21], 0, v[64:65]
	flat_load_dwordx4 v[88:91], v[66:67]
	flat_load_dwordx4 v[72:75], v[66:67] offset:512
	v_or_b32_e32 v66, 4, v184
	v_lshl_add_u64 v[64:65], s[22:23], 0, v[64:65]
	v_ashrrev_i32_e32 v67, 31, v66
	flat_load_dwordx4 v[92:95], v[64:65]
	flat_load_dwordx4 v[76:79], v[64:65] offset:512
	v_lshlrev_b64 v[64:65], 2, v[66:67]
	v_lshl_add_u64 v[66:67], s[12:13], 0, v[64:65]
	v_lshl_add_u64 v[68:69], s[38:39], 0, v[64:65]
	v_lshl_add_u64 v[70:71], s[40:41], 0, v[64:65]
	v_lshl_add_u64 v[64:65], s[24:25], 0, v[64:65]
	global_load_dwordx4 v[84:87], v[66:67], off
	global_load_dwordx4 v[80:83], v[68:69], off
	s_nop 0
	global_load_dwordx4 v[68:71], v[70:71], off
	s_nop 0
	global_load_dwordx4 v[64:67], v[64:65], off
	v_xor_b32_e32 v120, 0x80000000, v192
	v_mov_b32_e32 v193, v192
	v_mov_b32_e32 v121, v120
	v_mov_b32_e32 v191, v190
	v_mov_b32_e32 v122, v190
	v_mov_b32_e32 v123, v190
	v_mov_b32_dpp v117, v117 row_ror:1 row_mask:0xf bank_mask:0xf
	v_mov_b32_dpp v99, v99 row_ror:2 row_mask:0xf bank_mask:0xf
	v_mov_b32_e32 v96, v117
	v_mov_b32_e32 v118, v99
	v_mov_b32_e32 v97, v117
	v_mov_b32_e32 v119, v99
	v_mov_b32_e32 v116, v117
	v_mov_b32_e32 v98, v99
	s_waitcnt vmcnt(0) lgkmcnt(0)
	v_pk_fma_f32 v[62:63], v[120:121], v[90:91], v[62:63]
	v_pk_fma_f32 v[124:125], v[192:193], v[88:89], v[60:61] neg_lo:[1,0,0] neg_hi:[1,0,0]
	v_pk_fma_f32 v[58:59], v[120:121], v[74:75], v[58:59]
	v_pk_fma_f32 v[56:57], v[192:193], v[72:73], v[56:57] neg_lo:[1,0,0] neg_hi:[1,0,0]
	v_pk_fma_f32 v[60:61], v[122:123], v[62:63], v[94:95]
	v_pk_fma_f32 v[62:63], v[190:191], v[124:125], v[92:93]
	v_pk_fma_f32 v[58:59], v[122:123], v[58:59], v[78:79]
	v_mov_b32_dpp v116, v60 row_shr:1 row_mask:0xf bank_mask:0xf
	v_mov_b32_dpp v96, v62 row_shr:1 row_mask:0xf bank_mask:0xf
	v_mov_b32_dpp v118, v62 row_shr:2 row_mask:0xf bank_mask:0xf
	v_mov_b32_dpp v97, v63 row_shr:1 row_mask:0xf bank_mask:0xf
	v_mov_b32_dpp v119, v63 row_shr:2 row_mask:0xf bank_mask:0xf
	v_mov_b32_dpp v98, v60 row_shr:2 row_mask:0xf bank_mask:0xf
	v_mov_b32_dpp v117, v61 row_shr:1 row_mask:0xf bank_mask:0xf
	v_mov_b32_dpp v99, v61 row_shr:2 row_mask:0xf bank_mask:0xf
	v_pk_fma_f32 v[56:57], v[190:191], v[56:57], v[76:77]
	s_and_saveexec_b64 s[0:1], s[2:3]
	s_xor_b64 s[0:1], exec, s[0:1]
	s_cbranch_execz .LBB0_2736
	v_pk_mul_f32 v[118:119], v[84:85], v[118:119]
	v_pk_mul_f32 v[98:99], v[86:87], v[98:99]
	v_pk_fma_f32 v[96:97], v[80:81], v[96:97], v[118:119]
	v_pk_fma_f32 v[98:99], v[82:83], v[116:117], v[98:99]
	v_pk_fma_f32 v[96:97], v[62:63], v[68:69], v[96:97]
	v_pk_fma_f32 v[98:99], v[60:61], v[70:71], v[98:99]
	v_pk_add_f32 v[96:97], v[64:65], v[96:97]
	v_pk_add_f32 v[98:99], v[66:67], v[98:99]
	v_mul_f32_e32 v101, 0xbfb8aa3b, v96
	v_exp_f32_e32 v101, v101
	v_mul_f32_e32 v103, 0xbfb8aa3b, v97
	v_exp_f32_e32 v103, v103
	v_add_f32_e32 v101, 1.0, v101
	v_rcp_f32_e32 v101, v101
	v_add_f32_e32 v103, 1.0, v103
	v_rcp_f32_e32 v103, v103
	v_mul_f32_e32 v96, v96, v101
	v_mul_f32_e32 v56, v56, v96
	v_mul_f32_e32 v96, v97, v103
	v_mul_f32_e32 v97, 0xbfb8aa3b, v98
	v_exp_f32_e32 v97, v97
	v_mul_f32_e32 v101, 0xbfb8aa3b, v99
	v_exp_f32_e32 v101, v101
	v_mul_f32_e32 v57, v57, v96
	v_add_f32_e32 v96, 1.0, v97
	v_rcp_f32_e32 v96, v96
	v_add_f32_e32 v97, 1.0, v101
	v_rcp_f32_e32 v97, v97
	v_cvt_pk_bf16_f32 v56, v56, v57
	v_mul_f32_e32 v57, v98, v96
	v_mul_f32_e32 v57, v58, v57
	v_mul_f32_e32 v58, v99, v97
	v_mul_f32_e32 v58, v59, v58
	v_cvt_pk_bf16_f32 v57, v57, v58
	v_mov_b64_e32 v[58:59], s[18:19]
	v_mad_i64_i32 v[58:59], s[10:11], v188, s83, v[58:59]
	v_lshl_add_u64 v[58:59], v[184:185], 1, v[58:59]
	flat_store_dwordx2 v[58:59], v[56:57] offset:8

; DEVI unsigned pk2(float lo, float hi) { unsigned r; asm("v_cvt_pk_bf16_f32 %0, %1, %2" : "=v"(r) : "v"(lo), "v"(hi)); return r; }
; DEVI float siluf_(float x) { return x * sigmoidf_(x); }
; template <int CTRL> DEVI float dppf(float old, float src) { return __int_as_float(__builtin_amdgcn_update_dpp(__float_as_int(old), __float_as_int(src), CTRL, 0xf, 0xf, false)); }
;     DEVI void operator()(const f32x4 (&acc)[2][2][4][2], const pg8::Unit& u, int wr, int wc, int fr, int fq) const {
;     ...
; #pragma unroll
;             for (int ai = 0; ai < 2; ++ai) {
;                 f32x4 gprev = (f32x4){0.f, 0.f, 0.f, 0.f};
; #pragma unroll
;                 for (int m = 0; m < 4; ++m) {
;                     const int row = u.pm * 256 + ai * 128 + wr * 64 + m * 16 + fr;
;                     const f32x4 g = (acc[ai][0][m][n] - mu[ai][m] * sg) * rs[ai][m] + cg_;
;                     const f32x4 uu = (acc[ai][1][m][n] - mu[ai][m] * su) * rs[ai][m] + cu;
;                     f32x4 p1, p2;
; #pragma unroll
;                     for (int e = 0; e < 4; ++e) {
;                         p1[e] = dppf<0x111>(dppf<0x121>(0.f, gprev[e]), g[e]);
;                         p2[e] = dppf<0x112>(dppf<0x122>(0.f, gprev[e]), g[e]);
;                     }
;                     const int blk = row >> 6;
;                     if (m == 0 && fr < 2) {
;                         const f32x4 pg = (fr == 0) ? (w2 * g + cbv) : (w1 * p1 + w2 * g + cbv);
;                         *(f32x4*)(headpg + ((size_t)blk * 2 + fr) * DFF + j) = pg;
;                         *(f32x4*)(headup + ((size_t)blk * 2 + fr) * DFF + j) = uu;
;                     } else {
;                         const f32x4 cv = w0 * p2 + w1 * p1 + w2 * g + cbv;
;                         u32x2 o; o.x = pk2(siluf_(cv[0]) * uu[0], siluf_(cv[1]) * uu[1]); o.y = pk2(siluf_(cv[2]) * uu[2], siluf_(cv[3]) * uu[3]);
;                         *(u32x2*)(H + (size_t)row * DFF + j) = o;
;                     }
;                     if (m == 3 && fr >= 14) *(f32x4*)(tailg + ((size_t)blk * 2 + (fr - 14)) * DFF + j) = g;
;                     gprev = g;
.LBB0_2738:
	s_or_b64 exec, exec, s[0:1]
	v_mov_b32_e32 v161, v160
	v_mov_b32_e32 v163, v162
	v_pk_fma_f32 v[52:53], v[160:161], v[88:89], v[52:53] neg_lo:[1,0,0] neg_hi:[1,0,0]
	v_xor_b32_e32 v56, 0x80000000, v160
	v_pk_fma_f32 v[52:53], v[162:163], v[52:53], v[92:93]
	v_mov_b32_dpp v98, v62 row_ror:2 row_mask:0xf bank_mask:0xf
	v_mov_b32_dpp v99, v63 row_ror:2 row_mask:0xf bank_mask:0xf
	v_mov_b32_e32 v57, v56
	v_mov_b32_dpp v96, v62 row_ror:1 row_mask:0xf bank_mask:0xf
	v_mov_b32_dpp v98, v52 row_shr:2 row_mask:0xf bank_mask:0xf
	v_mov_b32_dpp v97, v63 row_ror:1 row_mask:0xf bank_mask:0xf
	v_mov_b32_dpp v99, v53 row_shr:2 row_mask:0xf bank_mask:0xf
	v_pk_fma_f32 v[54:55], v[56:57], v[90:91], v[54:55]
	v_mov_b32_dpp v96, v52 row_shr:1 row_mask:0xf bank_mask:0xf
	v_mov_b32_dpp v97, v53 row_shr:1 row_mask:0xf bank_mask:0xf
	v_pk_fma_f32 v[50:51], v[56:57], v[74:75], v[50:51]
	v_pk_mul_f32 v[56:57], v[84:85], v[98:99]
	v_pk_fma_f32 v[56:57], v[80:81], v[96:97], v[56:57]
	v_pk_fma_f32 v[56:57], v[52:53], v[68:69], v[56:57]
	v_mov_b32_dpp v62, v60 row_ror:1 row_mask:0xf bank_mask:0xf
	v_pk_add_f32 v[56:57], v[64:65], v[56:57]
	v_mov_b32_dpp v116, v60 row_ror:2 row_mask:0xf bank_mask:0xf
	v_mul_f32_e32 v60, 0xbfb8aa3b, v56
	v_mov_b32_dpp v63, v61 row_ror:1 row_mask:0xf bank_mask:0xf
	v_mov_b32_dpp v117, v61 row_ror:2 row_mask:0xf bank_mask:0xf
	v_exp_f32_e32 v60, v60
	v_mul_f32_e32 v61, 0xbfb8aa3b, v57
	v_exp_f32_e32 v61, v61
	v_mov_b32_e32 v58, v162
	v_mov_b32_e32 v59, v162
	v_pk_fma_f32 v[54:55], v[58:59], v[54:55], v[94:95]
	v_add_f32_e32 v60, 1.0, v60
	v_rcp_f32_e32 v60, v60
	v_mov_b32_dpp v116, v54 row_shr:2 row_mask:0xf bank_mask:0xf
	v_mov_b32_dpp v117, v55 row_shr:2 row_mask:0xf bank_mask:0xf
	v_add_f32_e32 v61, 1.0, v61
	v_mov_b32_dpp v62, v54 row_shr:1 row_mask:0xf bank_mask:0xf
	v_mov_b32_dpp v63, v55 row_shr:1 row_mask:0xf bank_mask:0xf
	v_pk_fma_f32 v[50:51], v[58:59], v[50:51], v[78:79]
	v_pk_mul_f32 v[58:59], v[86:87], v[116:117]
	v_rcp_f32_e32 v61, v61
	v_pk_fma_f32 v[58:59], v[82:83], v[62:63], v[58:59]
	v_pk_fma_f32 v[48:49], v[160:161], v[72:73], v[48:49] neg_lo:[1,0,0] neg_hi:[1,0,0]
	v_pk_fma_f32 v[58:59], v[54:55], v[70:71], v[58:59]
	v_pk_fma_f32 v[48:49], v[162:163], v[48:49], v[76:77]
	v_pk_add_f32 v[58:59], v[66:67], v[58:59]
	v_mul_f32_e32 v56, v56, v60
	v_mul_f32_e32 v48, v48, v56
	v_mul_f32_e32 v56, v57, v61
	v_mul_f32_e32 v57, 0xbfb8aa3b, v58
	v_exp_f32_e32 v57, v57
	v_mul_f32_e32 v60, 0xbfb8aa3b, v59
	v_exp_f32_e32 v60, v60
	v_mul_f32_e32 v49, v49, v56
	v_add_f32_e32 v56, 1.0, v57
	v_rcp_f32_e32 v56, v56
	v_add_f32_e32 v57, 1.0, v60
	v_rcp_f32_e32 v57, v57
	v_mov_b32_e32 v157, v156
	v_cvt_pk_bf16_f32 v48, v48, v49
	v_mul_f32_e32 v49, v58, v56
	v_mov_b32_e32 v159, v158
	v_mul_f32_e32 v49, v50, v49
	v_mul_f32_e32 v50, v59, v57
	v_pk_fma_f32 v[44:45], v[156:157], v[88:89], v[44:45] neg_lo:[1,0,0] neg_hi:[1,0,0]
	v_mul_f32_e32 v50, v51, v50
	v_cvt_pk_bf16_f32 v49, v49, v50
	flat_store_dwordx2 v[198:199], v[48:49] offset:8
	v_xor_b32_e32 v48, 0x80000000, v156
	v_pk_fma_f32 v[44:45], v[158:159], v[44:45], v[92:93]
	v_mov_b32_dpp v58, v52 row_ror:2 row_mask:0xf bank_mask:0xf
	v_mov_b32_dpp v59, v53 row_ror:2 row_mask:0xf bank_mask:0xf
	v_mov_b32_e32 v49, v48
	v_mov_b32_dpp v56, v52 row_ror:1 row_mask:0xf bank_mask:0xf
	v_mov_b32_dpp v58, v44 row_shr:2 row_mask:0xf bank_mask:0xf
	v_mov_b32_dpp v57, v53 row_ror:1 row_mask:0xf bank_mask:0xf
	v_mov_b32_dpp v59, v45 row_shr:2 row_mask:0xf bank_mask:0xf
	v_pk_fma_f32 v[46:47], v[48:49], v[90:91], v[46:47]
	v_mov_b32_e32 v50, v158
	v_mov_b32_e32 v51, v158
	v_mov_b32_dpp v56, v44 row_shr:1 row_mask:0xf bank_mask:0xf
	v_mov_b32_dpp v57, v45 row_shr:1 row_mask:0xf bank_mask:0xf
	v_pk_fma_f32 v[42:43], v[48:49], v[74:75], v[42:43]
	v_pk_mul_f32 v[48:49], v[84:85], v[58:59]
	v_pk_fma_f32 v[46:47], v[50:51], v[46:47], v[94:95]
	v_mov_b32_dpp v60, v54 row_ror:2 row_mask:0xf bank_mask:0xf
	v_mov_b32_dpp v61, v55 row_ror:2 row_mask:0xf bank_mask:0xf
	v_pk_fma_f32 v[48:49], v[80:81], v[56:57], v[48:49]
	v_mov_b32_dpp v52, v54 row_ror:1 row_mask:0xf bank_mask:0xf
	v_mov_b32_dpp v60, v46 row_shr:2 row_mask:0xf bank_mask:0xf
	v_mov_b32_dpp v53, v55 row_ror:1 row_mask:0xf bank_mask:0xf
	v_mov_b32_dpp v61, v47 row_shr:2 row_mask:0xf bank_mask:0xf
	v_pk_fma_f32 v[48:49], v[44:45], v[68:69], v[48:49]
	v_mov_b32_dpp v52, v46 row_shr:1 row_mask:0xf bank_mask:0xf
	v_mov_b32_dpp v53, v47 row_shr:1 row_mask:0xf bank_mask:0xf
	v_pk_fma_f32 v[42:43], v[50:51], v[42:43], v[78:79]
	v_pk_mul_f32 v[50:51], v[86:87], v[60:61]
	v_pk_add_f32 v[48:49], v[64:65], v[48:49]
	v_pk_fma_f32 v[50:51], v[82:83], v[52:53], v[50:51]
	v_mul_f32_e32 v52, 0xbfb8aa3b, v48
	v_exp_f32_e32 v52, v52
	v_mul_f32_e32 v53, 0xbfb8aa3b, v49
	v_exp_f32_e32 v53, v53
	v_pk_fma_f32 v[40:41], v[156:157], v[72:73], v[40:41] neg_lo:[1,0,0] neg_hi:[1,0,0]
	v_add_f32_e32 v52, 1.0, v52
	v_rcp_f32_e32 v52, v52
	v_add_f32_e32 v53, 1.0, v53
	v_rcp_f32_e32 v53, v53
	v_pk_fma_f32 v[50:51], v[46:47], v[70:71], v[50:51]
	v_pk_fma_f32 v[40:41], v[158:159], v[40:41], v[76:77]
	v_pk_add_f32 v[50:51], v[66:67], v[50:51]
	v_mul_f32_e32 v48, v48, v52
	v_mul_f32_e32 v40, v40, v48
	v_mul_f32_e32 v48, v49, v53
	v_mul_f32_e32 v49, 0xbfb8aa3b, v50
	v_exp_f32_e32 v49, v49
	v_mul_f32_e32 v52, 0xbfb8aa3b, v51
	v_exp_f32_e32 v52, v52
	v_mul_f32_e32 v41, v41, v48
	v_add_f32_e32 v48, 1.0, v49
	v_rcp_f32_e32 v48, v48
	v_add_f32_e32 v49, 1.0, v52
	v_rcp_f32_e32 v49, v49
	v_mov_b32_e32 v153, v152
	v_cvt_pk_bf16_f32 v40, v40, v41
	v_mul_f32_e32 v41, v50, v48
	v_mov_b32_e32 v155, v154
	v_mul_f32_e32 v41, v42, v41
	v_mul_f32_e32 v42, v51, v49
; DEVI unsigned pk2(float lo, float hi) { unsigned r; asm("v_cvt_pk_bf16_f32 %0, %1, %2" : "=v"(r) : "v"(lo), "v"(hi)); return r; }
; DEVI float siluf_(float x) { return x * sigmoidf_(x); }
; template <int CTRL> DEVI float dppf(float old, float src) { return __int_as_float(__builtin_amdgcn_update_dpp(__float_as_int(old), __float_as_int(src), CTRL, 0xf, 0xf, false)); }
;     DEVI void operator()(const f32x4 (&acc)[2][2][4][2], const pg8::Unit& u, int wr, int wc, int fr, int fq) const {
;     ...
; #pragma unroll
;             for (int ai = 0; ai < 2; ++ai) {
;                 f32x4 gprev = (f32x4){0.f, 0.f, 0.f, 0.f};
; #pragma unroll
;                 for (int m = 0; m < 4; ++m) {
;                     const int row = u.pm * 256 + ai * 128 + wr * 64 + m * 16 + fr;
;                     const f32x4 g = (acc[ai][0][m][n] - mu[ai][m] * sg) * rs[ai][m] + cg_;
;                     const f32x4 uu = (acc[ai][1][m][n] - mu[ai][m] * su) * rs[ai][m] + cu;
;                     f32x4 p1, p2;
; #pragma unroll
;                     for (int e = 0; e < 4; ++e) {
;                         p1[e] = dppf<0x111>(dppf<0x121>(0.f, gprev[e]), g[e]);
;                         p2[e] = dppf<0x112>(dppf<0x122>(0.f, gprev[e]), g[e]);
;                     }
;                     const int blk = row >> 6;
;                     if (m == 0 && fr < 2) {
;                         const f32x4 pg = (fr == 0) ? (w2 * g + cbv) : (w1 * p1 + w2 * g + cbv);
;                         *(f32x4*)(headpg + ((size_t)blk * 2 + fr) * DFF + j) = pg;
;                         *(f32x4*)(headup + ((size_t)blk * 2 + fr) * DFF + j) = uu;
;                     } else {
;                         const f32x4 cv = w0 * p2 + w1 * p1 + w2 * g + cbv;
;                         u32x2 o; o.x = pk2(siluf_(cv[0]) * uu[0], siluf_(cv[1]) * uu[1]); o.y = pk2(siluf_(cv[2]) * uu[2], siluf_(cv[3]) * uu[3]);
;                         *(u32x2*)(H + (size_t)row * DFF + j) = o;
;                     }
;                     if (m == 3 && fr >= 14) *(f32x4*)(tailg + ((size_t)blk * 2 + (fr - 14)) * DFF + j) = g;
;                     gprev = g;
	v_pk_fma_f32 v[36:37], v[152:153], v[88:89], v[36:37] neg_lo:[1,0,0] neg_hi:[1,0,0]
	v_mul_f32_e32 v42, v43, v42
	v_cvt_pk_bf16_f32 v41, v41, v42
	flat_store_dwordx2 v[196:197], v[40:41] offset:8
	v_xor_b32_e32 v40, 0x80000000, v152
	v_pk_fma_f32 v[36:37], v[154:155], v[36:37], v[92:93]
	v_mov_b32_dpp v50, v44 row_ror:2 row_mask:0xf bank_mask:0xf
	v_mov_b32_dpp v51, v45 row_ror:2 row_mask:0xf bank_mask:0xf
	v_mov_b32_e32 v41, v40
	v_mov_b32_dpp v48, v44 row_ror:1 row_mask:0xf bank_mask:0xf
	v_mov_b32_dpp v50, v36 row_shr:2 row_mask:0xf bank_mask:0xf
	v_mov_b32_dpp v49, v45 row_ror:1 row_mask:0xf bank_mask:0xf
	v_mov_b32_dpp v51, v37 row_shr:2 row_mask:0xf bank_mask:0xf
	v_pk_fma_f32 v[38:39], v[40:41], v[90:91], v[38:39]
	v_mov_b32_e32 v42, v154
	v_mov_b32_e32 v43, v154
	v_mov_b32_dpp v48, v36 row_shr:1 row_mask:0xf bank_mask:0xf
	v_mov_b32_dpp v49, v37 row_shr:1 row_mask:0xf bank_mask:0xf
	v_pk_fma_f32 v[34:35], v[40:41], v[74:75], v[34:35]
	v_pk_mul_f32 v[40:41], v[84:85], v[50:51]
	v_pk_fma_f32 v[38:39], v[42:43], v[38:39], v[94:95]
	v_mov_b32_dpp v52, v46 row_ror:2 row_mask:0xf bank_mask:0xf
	v_mov_b32_dpp v53, v47 row_ror:2 row_mask:0xf bank_mask:0xf
	v_pk_fma_f32 v[40:41], v[80:81], v[48:49], v[40:41]
	v_mov_b32_dpp v44, v46 row_ror:1 row_mask:0xf bank_mask:0xf
	v_mov_b32_dpp v52, v38 row_shr:2 row_mask:0xf bank_mask:0xf
	v_mov_b32_dpp v45, v47 row_ror:1 row_mask:0xf bank_mask:0xf
	v_mov_b32_dpp v53, v39 row_shr:2 row_mask:0xf bank_mask:0xf
	v_pk_fma_f32 v[40:41], v[36:37], v[68:69], v[40:41]
	v_mov_b32_dpp v44, v38 row_shr:1 row_mask:0xf bank_mask:0xf
	v_mov_b32_dpp v45, v39 row_shr:1 row_mask:0xf bank_mask:0xf
	v_pk_fma_f32 v[34:35], v[42:43], v[34:35], v[78:79]
	v_pk_mul_f32 v[42:43], v[86:87], v[52:53]
	v_pk_add_f32 v[40:41], v[64:65], v[40:41]
	v_pk_fma_f32 v[42:43], v[82:83], v[44:45], v[42:43]
	v_mul_f32_e32 v44, 0xbfb8aa3b, v40
	v_exp_f32_e32 v44, v44
	v_mul_f32_e32 v45, 0xbfb8aa3b, v41
	v_exp_f32_e32 v45, v45
	v_pk_fma_f32 v[32:33], v[152:153], v[72:73], v[32:33] neg_lo:[1,0,0] neg_hi:[1,0,0]
	v_add_f32_e32 v44, 1.0, v44
	v_rcp_f32_e32 v44, v44
	v_add_f32_e32 v45, 1.0, v45
	v_rcp_f32_e32 v45, v45
	v_pk_fma_f32 v[42:43], v[38:39], v[70:71], v[42:43]
	v_pk_fma_f32 v[32:33], v[154:155], v[32:33], v[76:77]
	v_pk_add_f32 v[42:43], v[66:67], v[42:43]
	v_mul_f32_e32 v40, v40, v44
	v_mul_f32_e32 v32, v32, v40
	v_mul_f32_e32 v40, v41, v45
	v_mul_f32_e32 v41, 0xbfb8aa3b, v42
	v_exp_f32_e32 v41, v41
	v_mul_f32_e32 v44, 0xbfb8aa3b, v43
	v_exp_f32_e32 v44, v44
	v_mul_f32_e32 v33, v33, v40
	v_add_f32_e32 v40, 1.0, v41
	v_rcp_f32_e32 v40, v40
	v_add_f32_e32 v41, 1.0, v44
	v_rcp_f32_e32 v41, v41
	v_cvt_pk_bf16_f32 v32, v32, v33
	v_mul_f32_e32 v33, v42, v40
	v_mul_f32_e32 v33, v34, v33
	v_mul_f32_e32 v34, v43, v41
	v_mul_f32_e32 v34, v35, v34
	v_cvt_pk_bf16_f32 v33, v33, v34
	flat_store_dwordx2 v[150:151], v[32:33] offset:8
	s_and_saveexec_b64 s[0:1], s[6:7]
	s_cbranch_execz .LBB0_2740
	flat_store_dwordx4 v[148:149], v[36:39] offset:16
.LBB0_2740:
	s_or_b64 exec, exec, s[0:1]
	s_nop 0
	v_xor_b32_e32 v36, 0x80000000, v132
	v_mov_b32_e32 v37, v36
	v_mov_b32_e32 v133, v132
	v_pk_fma_f32 v[30:31], v[36:37], v[90:91], v[30:31]
	v_pk_fma_f32 v[26:27], v[36:37], v[74:75], v[26:27]
	v_mov_b32_e32 v111, v110
	v_pk_fma_f32 v[28:29], v[132:133], v[88:89], v[28:29] neg_lo:[1,0,0] neg_hi:[1,0,0]
	v_mov_b32_e32 v40, v110
	v_mov_b32_e32 v41, v110
	v_mov_b32_dpp v37, v37 row_ror:1 row_mask:0xf bank_mask:0xf
	v_mov_b32_dpp v39, v39 row_ror:2 row_mask:0xf bank_mask:0xf
	v_pk_fma_f32 v[34:35], v[110:111], v[28:29], v[92:93]
	v_pk_fma_f32 v[32:33], v[40:41], v[30:31], v[94:95]
	v_pk_fma_f32 v[24:25], v[132:133], v[72:73], v[24:25] neg_lo:[1,0,0] neg_hi:[1,0,0]
	v_mov_b32_e32 v28, v37
	v_mov_b32_e32 v30, v39
	v_mov_b32_e32 v29, v37
	v_mov_b32_e32 v31, v39
	v_mov_b32_e32 v36, v37
	v_mov_b32_e32 v38, v39
	v_mov_b32_dpp v28, v34 row_shr:1 row_mask:0xf bank_mask:0xf
	v_mov_b32_dpp v30, v34 row_shr:2 row_mask:0xf bank_mask:0xf
	v_mov_b32_dpp v29, v35 row_shr:1 row_mask:0xf bank_mask:0xf
	v_mov_b32_dpp v31, v35 row_shr:2 row_mask:0xf bank_mask:0xf
	v_mov_b32_dpp v36, v32 row_shr:1 row_mask:0xf bank_mask:0xf
	v_mov_b32_dpp v38, v32 row_shr:2 row_mask:0xf bank_mask:0xf
	v_mov_b32_dpp v37, v33 row_shr:1 row_mask:0xf bank_mask:0xf
	v_mov_b32_dpp v39, v33 row_shr:2 row_mask:0xf bank_mask:0xf
	v_pk_fma_f32 v[24:25], v[110:111], v[24:25], v[76:77]
	v_pk_fma_f32 v[26:27], v[40:41], v[26:27], v[78:79]
	s_and_saveexec_b64 s[0:1], s[2:3]
	s_xor_b64 s[0:1], exec, s[0:1]
	s_cbranch_execz .LBB0_2742
	v_pk_mul_f32 v[30:31], v[84:85], v[30:31]
	v_pk_mul_f32 v[38:39], v[86:87], v[38:39]
	v_pk_fma_f32 v[28:29], v[80:81], v[28:29], v[30:31]
	v_pk_fma_f32 v[36:37], v[82:83], v[36:37], v[38:39]
	v_pk_fma_f32 v[28:29], v[34:35], v[68:69], v[28:29]
	s_nop 0
	v_pk_add_f32 v[28:29], v[64:65], v[28:29]
	s_nop 0
	v_mul_f32_e32 v30, 0xbfb8aa3b, v28
	v_exp_f32_e32 v38, v30
	v_mul_f32_e32 v30, 0xbfb8aa3b, v29
	v_exp_f32_e32 v39, v30
	v_pk_fma_f32 v[30:31], v[32:33], v[70:71], v[36:37]
	v_add_f32_e32 v36, 1.0, v38
	v_rcp_f32_e32 v36, v36
	v_add_f32_e32 v37, 1.0, v39
	v_rcp_f32_e32 v37, v37
	v_pk_add_f32 v[30:31], v[66:67], v[30:31]
	v_mul_f32_e32 v28, v28, v36
	v_mul_f32_e32 v24, v24, v28
	v_mul_f32_e32 v28, v29, v37
	v_mul_f32_e32 v29, 0xbfb8aa3b, v30
	v_exp_f32_e32 v29, v29
	v_mul_f32_e32 v36, 0xbfb8aa3b, v31
	v_exp_f32_e32 v36, v36
	v_mul_f32_e32 v25, v25, v28
	v_add_f32_e32 v28, 1.0, v29
	v_rcp_f32_e32 v28, v28
	v_add_f32_e32 v29, 1.0, v36
	v_rcp_f32_e32 v29, v29
	v_cvt_pk_bf16_f32 v24, v24, v25
	v_mul_f32_e32 v25, v30, v28
	v_mul_f32_e32 v25, v26, v25
	v_mul_f32_e32 v26, v31, v29
	v_mul_f32_e32 v26, v27, v26
	v_cvt_pk_bf16_f32 v25, v25, v26
	v_mov_b64_e32 v[26:27], s[18:19]
	v_mad_i64_i32 v[26:27], s[10:11], v107, s83, v[26:27]
	v_lshl_add_u64 v[26:27], v[184:185], 1, v[26:27]
	flat_store_dwordx2 v[26:27], v[24:25] offset:8

; DEVI unsigned pk2(float lo, float hi) { unsigned r; asm("v_cvt_pk_bf16_f32 %0, %1, %2" : "=v"(r) : "v"(lo), "v"(hi)); return r; }
; DEVI float siluf_(float x) { return x * sigmoidf_(x); }
; template <int CTRL> DEVI float dppf(float old, float src) { return __int_as_float(__builtin_amdgcn_update_dpp(__float_as_int(old), __float_as_int(src), CTRL, 0xf, 0xf, false)); }
;     DEVI void operator()(const f32x4 (&acc)[2][2][4][2], const pg8::Unit& u, int wr, int wc, int fr, int fq) const {
;     ...
; #pragma unroll
;             for (int ai = 0; ai < 2; ++ai) {
;                 f32x4 gprev = (f32x4){0.f, 0.f, 0.f, 0.f};
; #pragma unroll
;                 for (int m = 0; m < 4; ++m) {
;                     const int row = u.pm * 256 + ai * 128 + wr * 64 + m * 16 + fr;
;                     const f32x4 g = (acc[ai][0][m][n] - mu[ai][m] * sg) * rs[ai][m] + cg_;
;                     const f32x4 uu = (acc[ai][1][m][n] - mu[ai][m] * su) * rs[ai][m] + cu;
;                     f32x4 p1, p2;
; #pragma unroll
;                     for (int e = 0; e < 4; ++e) {
;                         p1[e] = dppf<0x111>(dppf<0x121>(0.f, gprev[e]), g[e]);
;                         p2[e] = dppf<0x112>(dppf<0x122>(0.f, gprev[e]), g[e]);
;                     }
;                     const int blk = row >> 6;
;                     if (m == 0 && fr < 2) {
;                         const f32x4 pg = (fr == 0) ? (w2 * g + cbv) : (w1 * p1 + w2 * g + cbv);
;                         *(f32x4*)(headpg + ((size_t)blk * 2 + fr) * DFF + j) = pg;
;                         *(f32x4*)(headup + ((size_t)blk * 2 + fr) * DFF + j) = uu;
;                     } else {
;                         const f32x4 cv = w0 * p2 + w1 * p1 + w2 * g + cbv;
;                         u32x2 o; o.x = pk2(siluf_(cv[0]) * uu[0], siluf_(cv[1]) * uu[1]); o.y = pk2(siluf_(cv[2]) * uu[2], siluf_(cv[3]) * uu[3]);
;                         *(u32x2*)(H + (size_t)row * DFF + j) = o;
;                     }
;                     if (m == 3 && fr >= 14) *(f32x4*)(tailg + ((size_t)blk * 2 + (fr - 14)) * DFF + j) = g;
;                     gprev = g;
.LBB0_2744:
	s_or_b64 exec, exec, s[0:1]
	v_mov_b32_e32 v109, v108
	v_mov_b32_e32 v135, v134
	v_pk_fma_f32 v[20:21], v[108:109], v[88:89], v[20:21] neg_lo:[1,0,0] neg_hi:[1,0,0]
	v_xor_b32_e32 v24, 0x80000000, v108
	v_pk_fma_f32 v[20:21], v[134:135], v[20:21], v[92:93]
	v_mov_b32_dpp v30, v34 row_ror:2 row_mask:0xf bank_mask:0xf
	v_mov_b32_dpp v31, v35 row_ror:2 row_mask:0xf bank_mask:0xf
	v_mov_b32_e32 v25, v24
	v_mov_b32_dpp v28, v34 row_ror:1 row_mask:0xf bank_mask:0xf
	v_mov_b32_dpp v30, v20 row_shr:2 row_mask:0xf bank_mask:0xf
	v_mov_b32_dpp v29, v35 row_ror:1 row_mask:0xf bank_mask:0xf
	v_mov_b32_dpp v31, v21 row_shr:2 row_mask:0xf bank_mask:0xf
	v_pk_fma_f32 v[22:23], v[24:25], v[90:91], v[22:23]
	v_mov_b32_dpp v28, v20 row_shr:1 row_mask:0xf bank_mask:0xf
	v_mov_b32_dpp v29, v21 row_shr:1 row_mask:0xf bank_mask:0xf
	v_pk_fma_f32 v[18:19], v[24:25], v[74:75], v[18:19]
	v_pk_mul_f32 v[24:25], v[84:85], v[30:31]
	v_mov_b32_e32 v26, v134
	v_pk_fma_f32 v[24:25], v[80:81], v[28:29], v[24:25]
	v_mov_b32_e32 v27, v134
	v_pk_fma_f32 v[24:25], v[20:21], v[68:69], v[24:25]
	v_pk_add_f32 v[24:25], v[64:65], v[24:25]
	v_mul_f32_e32 v28, 0xbfb8aa3b, v24
	v_exp_f32_e32 v28, v28
	v_mul_f32_e32 v29, 0xbfb8aa3b, v25
	v_exp_f32_e32 v29, v29
	v_pk_fma_f32 v[22:23], v[26:27], v[22:23], v[94:95]
	v_mov_b32_dpp v36, v32 row_ror:2 row_mask:0xf bank_mask:0xf
	v_mov_b32_dpp v37, v33 row_ror:2 row_mask:0xf bank_mask:0xf
	v_add_f32_e32 v28, 1.0, v28
	v_mov_b32_dpp v34, v32 row_ror:1 row_mask:0xf bank_mask:0xf
	v_mov_b32_dpp v36, v22 row_shr:2 row_mask:0xf bank_mask:0xf
	v_mov_b32_dpp v35, v33 row_ror:1 row_mask:0xf bank_mask:0xf
	v_mov_b32_dpp v37, v23 row_shr:2 row_mask:0xf bank_mask:0xf
	v_rcp_f32_e32 v28, v28
	v_add_f32_e32 v29, 1.0, v29
	v_mov_b32_dpp v34, v22 row_shr:1 row_mask:0xf bank_mask:0xf
	v_mov_b32_dpp v35, v23 row_shr:1 row_mask:0xf bank_mask:0xf
	v_pk_fma_f32 v[18:19], v[26:27], v[18:19], v[78:79]
	v_pk_mul_f32 v[26:27], v[86:87], v[36:37]
	v_rcp_f32_e32 v29, v29
	v_pk_fma_f32 v[26:27], v[82:83], v[34:35], v[26:27]
	v_pk_fma_f32 v[16:17], v[108:109], v[72:73], v[16:17] neg_lo:[1,0,0] neg_hi:[1,0,0]
	v_pk_fma_f32 v[26:27], v[22:23], v[70:71], v[26:27]
	v_pk_fma_f32 v[16:17], v[134:135], v[16:17], v[76:77]
	v_pk_add_f32 v[26:27], v[66:67], v[26:27]
	v_mul_f32_e32 v24, v24, v28
	v_mul_f32_e32 v16, v16, v24
	v_mul_f32_e32 v24, v25, v29
	v_mul_f32_e32 v25, 0xbfb8aa3b, v26
	v_exp_f32_e32 v25, v25
	v_mul_f32_e32 v28, 0xbfb8aa3b, v27
	v_exp_f32_e32 v28, v28
	v_mul_f32_e32 v17, v17, v24
	v_add_f32_e32 v24, 1.0, v25
	v_rcp_f32_e32 v24, v24
	v_add_f32_e32 v25, 1.0, v28
	v_rcp_f32_e32 v25, v25
	v_mov_b32_e32 v105, v104
	v_cvt_pk_bf16_f32 v16, v16, v17
	v_mul_f32_e32 v17, v26, v24
	v_mov_b32_e32 v107, v106
	v_mul_f32_e32 v17, v18, v17
	v_mul_f32_e32 v18, v27, v25
	v_pk_fma_f32 v[12:13], v[104:105], v[88:89], v[12:13] neg_lo:[1,0,0] neg_hi:[1,0,0]
	v_mul_f32_e32 v18, v19, v18
	v_cvt_pk_bf16_f32 v17, v17, v18
	flat_store_dwordx2 v[206:207], v[16:17] offset:8
	v_xor_b32_e32 v16, 0x80000000, v104
	v_pk_fma_f32 v[12:13], v[106:107], v[12:13], v[92:93]
	v_mov_b32_dpp v26, v20 row_ror:2 row_mask:0xf bank_mask:0xf
	v_mov_b32_dpp v27, v21 row_ror:2 row_mask:0xf bank_mask:0xf
	v_mov_b32_e32 v17, v16
	v_mov_b32_dpp v24, v20 row_ror:1 row_mask:0xf bank_mask:0xf
	v_mov_b32_dpp v26, v12 row_shr:2 row_mask:0xf bank_mask:0xf
	v_mov_b32_dpp v25, v21 row_ror:1 row_mask:0xf bank_mask:0xf
	v_mov_b32_dpp v27, v13 row_shr:2 row_mask:0xf bank_mask:0xf
	v_pk_fma_f32 v[14:15], v[16:17], v[90:91], v[14:15]
	v_mov_b32_e32 v18, v106
	v_mov_b32_e32 v19, v106
	v_mov_b32_dpp v24, v12 row_shr:1 row_mask:0xf bank_mask:0xf
	v_mov_b32_dpp v25, v13 row_shr:1 row_mask:0xf bank_mask:0xf
	v_pk_fma_f32 v[10:11], v[16:17], v[74:75], v[10:11]
	v_pk_mul_f32 v[16:17], v[84:85], v[26:27]
	v_pk_fma_f32 v[14:15], v[18:19], v[14:15], v[94:95]
	v_mov_b32_dpp v28, v22 row_ror:2 row_mask:0xf bank_mask:0xf
	v_mov_b32_dpp v29, v23 row_ror:2 row_mask:0xf bank_mask:0xf
	v_pk_fma_f32 v[16:17], v[80:81], v[24:25], v[16:17]
	v_mov_b32_dpp v20, v22 row_ror:1 row_mask:0xf bank_mask:0xf
	v_mov_b32_dpp v28, v14 row_shr:2 row_mask:0xf bank_mask:0xf
	v_mov_b32_dpp v21, v23 row_ror:1 row_mask:0xf bank_mask:0xf
; DEVI unsigned pk2(float lo, float hi) { unsigned r; asm("v_cvt_pk_bf16_f32 %0, %1, %2" : "=v"(r) : "v"(lo), "v"(hi)); return r; }
; DEVI float siluf_(float x) { return x * sigmoidf_(x); }
; template <int CTRL> DEVI float dppf(float old, float src) { return __int_as_float(__builtin_amdgcn_update_dpp(__float_as_int(old), __float_as_int(src), CTRL, 0xf, 0xf, false)); }
;     DEVI void operator()(const f32x4 (&acc)[2][2][4][2], const pg8::Unit& u, int wr, int wc, int fr, int fq) const {
;     ...
; #pragma unroll
;             for (int ai = 0; ai < 2; ++ai) {
;                 f32x4 gprev = (f32x4){0.f, 0.f, 0.f, 0.f};
; #pragma unroll
;                 for (int m = 0; m < 4; ++m) {
;                     const int row = u.pm * 256 + ai * 128 + wr * 64 + m * 16 + fr;
;                     const f32x4 g = (acc[ai][0][m][n] - mu[ai][m] * sg) * rs[ai][m] + cg_;
;                     const f32x4 uu = (acc[ai][1][m][n] - mu[ai][m] * su) * rs[ai][m] + cu;
;                     f32x4 p1, p2;
; #pragma unroll
;                     for (int e = 0; e < 4; ++e) {
;                         p1[e] = dppf<0x111>(dppf<0x121>(0.f, gprev[e]), g[e]);
;                         p2[e] = dppf<0x112>(dppf<0x122>(0.f, gprev[e]), g[e]);
;                     }
;                     const int blk = row >> 6;
;                     if (m == 0 && fr < 2) {
;                         const f32x4 pg = (fr == 0) ? (w2 * g + cbv) : (w1 * p1 + w2 * g + cbv);
;                         *(f32x4*)(headpg + ((size_t)blk * 2 + fr) * DFF + j) = pg;
;                         *(f32x4*)(headup + ((size_t)blk * 2 + fr) * DFF + j) = uu;
;                     } else {
;                         const f32x4 cv = w0 * p2 + w1 * p1 + w2 * g + cbv;
;                         u32x2 o; o.x = pk2(siluf_(cv[0]) * uu[0], siluf_(cv[1]) * uu[1]); o.y = pk2(siluf_(cv[2]) * uu[2], siluf_(cv[3]) * uu[3]);
;                         *(u32x2*)(H + (size_t)row * DFF + j) = o;
;                     }
;                     if (m == 3 && fr >= 14) *(f32x4*)(tailg + ((size_t)blk * 2 + (fr - 14)) * DFF + j) = g;
;                     gprev = g;
	v_mov_b32_dpp v29, v15 row_shr:2 row_mask:0xf bank_mask:0xf
	v_pk_fma_f32 v[16:17], v[12:13], v[68:69], v[16:17]
	v_mov_b32_dpp v20, v14 row_shr:1 row_mask:0xf bank_mask:0xf
	v_mov_b32_dpp v21, v15 row_shr:1 row_mask:0xf bank_mask:0xf
	v_pk_fma_f32 v[10:11], v[18:19], v[10:11], v[78:79]
	v_pk_mul_f32 v[18:19], v[86:87], v[28:29]
	v_pk_add_f32 v[16:17], v[64:65], v[16:17]
	v_pk_fma_f32 v[18:19], v[82:83], v[20:21], v[18:19]
	v_mul_f32_e32 v20, 0xbfb8aa3b, v16
	v_exp_f32_e32 v20, v20
	v_mul_f32_e32 v21, 0xbfb8aa3b, v17
	v_exp_f32_e32 v21, v21
	v_pk_fma_f32 v[8:9], v[104:105], v[72:73], v[8:9] neg_lo:[1,0,0] neg_hi:[1,0,0]
	v_add_f32_e32 v20, 1.0, v20
	v_rcp_f32_e32 v20, v20
	v_add_f32_e32 v21, 1.0, v21
	v_rcp_f32_e32 v21, v21
	v_pk_fma_f32 v[18:19], v[14:15], v[70:71], v[18:19]
	v_pk_fma_f32 v[8:9], v[106:107], v[8:9], v[76:77]
	v_pk_add_f32 v[18:19], v[66:67], v[18:19]
	v_mul_f32_e32 v16, v16, v20
	v_mul_f32_e32 v8, v8, v16
	v_mul_f32_e32 v16, v17, v21
	v_mul_f32_e32 v17, 0xbfb8aa3b, v18
	v_exp_f32_e32 v17, v17
	v_mul_f32_e32 v20, 0xbfb8aa3b, v19
	v_exp_f32_e32 v20, v20
	v_mul_f32_e32 v9, v9, v16
	v_add_f32_e32 v16, 1.0, v17
	v_rcp_f32_e32 v16, v16
	v_add_f32_e32 v17, 1.0, v20
	v_rcp_f32_e32 v17, v17
	v_mov_b32_e32 v101, v100
	v_cvt_pk_bf16_f32 v8, v8, v9
	v_mul_f32_e32 v9, v18, v16
	v_mov_b32_e32 v103, v102
	v_mul_f32_e32 v9, v10, v9
	v_mul_f32_e32 v10, v19, v17
	v_pk_fma_f32 v[4:5], v[100:101], v[88:89], v[4:5] neg_lo:[1,0,0] neg_hi:[1,0,0]
	v_mul_f32_e32 v10, v11, v10
	v_cvt_pk_bf16_f32 v9, v9, v10
	flat_store_dwordx2 v[204:205], v[8:9] offset:8
	v_xor_b32_e32 v8, 0x80000000, v100
	v_pk_fma_f32 v[4:5], v[102:103], v[4:5], v[92:93]
	v_mov_b32_dpp v18, v12 row_ror:2 row_mask:0xf bank_mask:0xf
	v_mov_b32_dpp v19, v13 row_ror:2 row_mask:0xf bank_mask:0xf
	v_mov_b32_e32 v9, v8
	v_mov_b32_dpp v16, v12 row_ror:1 row_mask:0xf bank_mask:0xf
	v_mov_b32_dpp v18, v4 row_shr:2 row_mask:0xf bank_mask:0xf
	v_mov_b32_dpp v17, v13 row_ror:1 row_mask:0xf bank_mask:0xf
	v_mov_b32_dpp v19, v5 row_shr:2 row_mask:0xf bank_mask:0xf
	v_pk_fma_f32 v[6:7], v[8:9], v[90:91], v[6:7]
	v_mov_b32_e32 v10, v102
	v_mov_b32_e32 v11, v102
	v_mov_b32_dpp v16, v4 row_shr:1 row_mask:0xf bank_mask:0xf
	v_mov_b32_dpp v17, v5 row_shr:1 row_mask:0xf bank_mask:0xf
	v_pk_fma_f32 v[2:3], v[8:9], v[74:75], v[2:3]
	v_pk_mul_f32 v[8:9], v[84:85], v[18:19]
	v_pk_fma_f32 v[6:7], v[10:11], v[6:7], v[94:95]
	v_mov_b32_dpp v20, v14 row_ror:2 row_mask:0xf bank_mask:0xf
	v_mov_b32_dpp v21, v15 row_ror:2 row_mask:0xf bank_mask:0xf
	v_pk_fma_f32 v[8:9], v[80:81], v[16:17], v[8:9]
	v_mov_b32_dpp v12, v14 row_ror:1 row_mask:0xf bank_mask:0xf
	v_mov_b32_dpp v20, v6 row_shr:2 row_mask:0xf bank_mask:0xf
	v_mov_b32_dpp v13, v15 row_ror:1 row_mask:0xf bank_mask:0xf
	v_mov_b32_dpp v21, v7 row_shr:2 row_mask:0xf bank_mask:0xf
	v_pk_fma_f32 v[8:9], v[4:5], v[68:69], v[8:9]
	v_mov_b32_dpp v12, v6 row_shr:1 row_mask:0xf bank_mask:0xf
	v_mov_b32_dpp v13, v7 row_shr:1 row_mask:0xf bank_mask:0xf
	v_pk_fma_f32 v[2:3], v[10:11], v[2:3], v[78:79]
	v_pk_mul_f32 v[10:11], v[86:87], v[20:21]
	v_pk_add_f32 v[8:9], v[64:65], v[8:9]
	v_pk_fma_f32 v[10:11], v[82:83], v[12:13], v[10:11]
	v_mul_f32_e32 v12, 0xbfb8aa3b, v8
	v_exp_f32_e32 v12, v12
	v_mul_f32_e32 v13, 0xbfb8aa3b, v9
	v_exp_f32_e32 v13, v13
	v_pk_fma_f32 v[0:1], v[100:101], v[72:73], v[0:1] neg_lo:[1,0,0] neg_hi:[1,0,0]
	v_add_f32_e32 v12, 1.0, v12
	v_rcp_f32_e32 v12, v12
	v_add_f32_e32 v13, 1.0, v13
	v_rcp_f32_e32 v13, v13
	v_pk_fma_f32 v[10:11], v[6:7], v[70:71], v[10:11]
	v_pk_fma_f32 v[0:1], v[102:103], v[0:1], v[76:77]
	v_pk_add_f32 v[10:11], v[66:67], v[10:11]
	v_mul_f32_e32 v8, v8, v12
	v_mul_f32_e32 v0, v0, v8
	v_mul_f32_e32 v8, v9, v13
	v_mul_f32_e32 v9, 0xbfb8aa3b, v10
	v_exp_f32_e32 v9, v9
	v_mul_f32_e32 v12, 0xbfb8aa3b, v11
	v_exp_f32_e32 v12, v12
	v_mul_f32_e32 v1, v1, v8
	v_add_f32_e32 v8, 1.0, v9
	v_rcp_f32_e32 v8, v8
	v_add_f32_e32 v9, 1.0, v12
	v_rcp_f32_e32 v9, v9
	v_cvt_pk_bf16_f32 v0, v0, v1
	v_mul_f32_e32 v1, v10, v8
	v_mul_f32_e32 v1, v2, v1
	v_mul_f32_e32 v2, v11, v9
	v_mul_f32_e32 v2, v3, v2
	v_cvt_pk_bf16_f32 v1, v1, v2
	flat_store_dwordx2 v[114:115], v[0:1] offset:8
	s_and_saveexec_b64 s[0:1], s[6:7]
	s_cbranch_execz .LBB0_2746
	flat_store_dwordx4 v[112:113], v[4:7] offset:16
